# move the redundant first accumulator-zeroing block (zero-trip K-loop path only) out of the per-unit hot path in all six GEMM phases
# speedup vs baseline: 1.0108x; 1.0108x over previous
; #define LAS __attribute__((address_space(3)))
; __global__ void __launch_bounds__(512, 2) mega(Args A) {
;     extern __shared__ __attribute__((aligned(16))) unsigned char lds_raw[];
;     LAS unsigned char* lds = (LAS unsigned char*)lds_raw;
;     cg::grid_group grid = cg::this_grid();
;     const int G = gridDim.x, bx = blockIdx.x;
;     const int vcu = (G % 8 == 0) ? (bx % 8) * (G / 8) + bx / 8 : bx;
;     unsigned char* ws = A.ws;
;     float* part[2] = {(float*)(ws + WS_PART0), (float*)(ws + WS_PART1)};
;     bf16_t* const HB0 = (bf16_t*)(ws + WS_HB); bf16_t* const HB1 = (bf16_t*)(ws + WS_HB1);
;     bf16_t* Z = (bf16_t*)(ws + WS_Z); bf16_t* ACT = Z; bf16_t* MIX = (bf16_t*)(ws + WS_MIX); bf16_t* PP = MIX;
;     if (bx == 0 && threadIdx.x < 8) __hip_atomic_store((unsigned*)(ws + WS_BAR) + 64 * threadIdx.x, 0u, __ATOMIC_RELAXED, __HIP_MEMORY_SCOPE_AGENT);
;     const unsigned my_xcc = (unsigned)__builtin_amdgcn_s_getreg((3 << 11) | 20) & 0xFu;
;     if (threadIdx.x == 0) __hip_atomic_store((unsigned*)(ws + WS_BAR + 4096) + bx, my_xcc, __ATOMIC_RELAXED, __HIP_MEMORY_SCOPE_AGENT);
_Z4mega4Args:
	s_add_u32 s84, s0, 0x98
	s_load_dwordx2 s[80:81], s[0:1], 0x90
	s_load_dword s88, s[0:1], 0x98
	s_addc_u32 s85, s1, 0
	s_cmp_eq_u32 s2, 0
	v_and_b32_e32 v232, 0x3ff, v0
	s_mov_b32 s82, s2
	s_cselect_b64 s[2:3], -1, 0
	v_cmp_gt_u32_e32 vcc, 8, v232
	s_and_b64 s[2:3], s[2:3], vcc
	s_and_saveexec_b64 s[4:5], s[2:3]
	s_cbranch_execz .LBB0_2
	v_lshlrev_b32_e32 v2, 8, v232
	v_mov_b32_e32 v3, 0
	s_waitcnt lgkmcnt(0)
	v_lshl_add_u64 v[4:5], s[80:81], 0, v[2:3]
	v_add_co_u32_e32 v4, vcc, 0x7800000, v4
	s_nop 1
	v_addc_co_u32_e32 v5, vcc, 0, v5, vcc
	global_store_dword v[4:5], v3, off sc1

; #define PG8_LAS __attribute__((address_space(3)))
; template <class Epi, class Sched, bool ALIGN_EPI = false, bool SP2 = false>
; __device__ __forceinline__ void gemm_phase(PG8_LAS unsigned char* lds, const Gemm g, const Sched& S, const Epi& E) {
;     ...
;     f32x4 acc[2][2][4][2];
; #pragma unroll
;     for (int a = 0; a < 2; ++a)
; #pragma unroll
;         for (int b = 0; b < 2; ++b)
; #pragma unroll
;             for (int m = 0; m < 4; ++m)
; #pragma unroll
;                 for (int n = 0; n < 2; ++n) acc[a][b][m][n] = (f32x4){0.f, 0.f, 0.f, 0.f};
;     ...
;     for (;;) {
;         const bool has_next = S.next(ui + 1, nxt);
;         const char* nA = has_next ? (const char*)g.A + (size_t)nxt.pm * tstepA : cA; const char* nB = has_next ? (const char*)g.Bt + (size_t)nxt.pn * tstep : cB;
;         for (int t = 0; t < nt; t += 2) {
;             const bool last = (t == nt - 2);
;             if constexpr (Epi::RVLDS) { if (last) {
;                 const char* pg = (const char*)E.part_in + (size_t)cur.pm * 16384 + (size_t)tid * 16;
;                 __builtin_amdgcn_global_load_lds((const unsigned*)pg, (PG8_LAS unsigned*)(lds + STAGE_BYTES + ldsw), 16, 0, 0);
;                 __builtin_amdgcn_global_load_lds((const unsigned*)(pg + 8192), (PG8_LAS unsigned*)(lds + STAGE_BYTES + 8192 + ldsw), 16, 0, 0); } }
;             const bool plast = Epi::RVLDS && last;
;             const bool defer = Epi::SPLIT && (t == 0) && (ui > 0);
;             const char* a1 = cA + (size_t)(t + 1) * kstep;
;             const char* a2 = last ? nA : cA + (size_t)(t + 2) * kstep; const char* b2 = last ? nB : cB + (size_t)(t + 2) * kstep;
.LBB0_250:
	s_andn2_b64 vcc, exec, s[16:17]
	s_cbranch_vccnz .Lzt_0
	s_ashr_i32 s23, s22, 31
	s_lshl_b64 s[28:29], s[22:23], 14
	s_add_u32 s24, s24, 0x80
	s_addc_u32 s25, s25, 0
	v_lshl_add_u64 v[216:217], v[210:211], 0, s[28:29]
	s_mov_b64 s[28:29], 0x2000
	s_add_u32 s23, s26, 0x100
	v_mov_b32_e32 v0, 0
	v_lshl_add_u64 v[218:219], v[216:217], 0, s[28:29]
	s_addc_u32 s33, s27, 0
	s_mov_b32 s51, 0
	v_mov_b32_e32 v1, v0
	v_mov_b32_e32 v2, v0
	v_mov_b32_e32 v3, v0
	v_mov_b32_e32 v4, v0
	v_mov_b32_e32 v5, v0
	v_mov_b32_e32 v6, v0
	v_mov_b32_e32 v7, v0
	v_mov_b32_e32 v16, v0
	v_mov_b32_e32 v17, v0
	v_mov_b32_e32 v18, v0
	v_mov_b32_e32 v19, v0
	v_mov_b32_e32 v20, v0
	v_mov_b32_e32 v21, v0
	v_mov_b32_e32 v22, v0
	v_mov_b32_e32 v23, v0
	v_mov_b32_e32 v32, v0
	v_mov_b32_e32 v33, v0
	v_mov_b32_e32 v34, v0
	v_mov_b32_e32 v35, v0
	v_mov_b32_e32 v36, v0
	v_mov_b32_e32 v37, v0
	v_mov_b32_e32 v38, v0
	v_mov_b32_e32 v39, v0
	v_mov_b32_e32 v48, v0
	v_mov_b32_e32 v49, v0
	v_mov_b32_e32 v50, v0
	v_mov_b32_e32 v51, v0
	v_mov_b32_e32 v52, v0
	v_mov_b32_e32 v53, v0
	v_mov_b32_e32 v54, v0
	v_mov_b32_e32 v55, v0
	v_mov_b32_e32 v8, v0
	v_mov_b32_e32 v9, v0
	v_mov_b32_e32 v10, v0
	v_mov_b32_e32 v11, v0
	v_mov_b32_e32 v12, v0
	v_mov_b32_e32 v13, v0
	v_mov_b32_e32 v14, v0
	v_mov_b32_e32 v15, v0
	v_mov_b32_e32 v24, v0
	v_mov_b32_e32 v25, v0
	v_mov_b32_e32 v26, v0
	v_mov_b32_e32 v27, v0
	v_mov_b32_e32 v28, v0
	v_mov_b32_e32 v29, v0
	v_mov_b32_e32 v30, v0
	v_mov_b32_e32 v31, v0
	v_mov_b32_e32 v40, v0
	v_mov_b32_e32 v41, v0
	v_mov_b32_e32 v42, v0
	v_mov_b32_e32 v43, v0
	v_mov_b32_e32 v44, v0
	v_mov_b32_e32 v45, v0
	v_mov_b32_e32 v46, v0
	v_mov_b32_e32 v47, v0
	v_mov_b32_e32 v56, v0
	v_mov_b32_e32 v57, v0
	v_mov_b32_e32 v58, v0
	v_mov_b32_e32 v59, v0
	v_mov_b32_e32 v60, v0
	v_mov_b32_e32 v61, v0
	v_mov_b32_e32 v62, v0
	v_mov_b32_e32 v63, v0
	v_mov_b32_e32 v64, v0
	v_mov_b32_e32 v65, v0
	v_mov_b32_e32 v66, v0
	v_mov_b32_e32 v67, v0
	v_mov_b32_e32 v68, v0
	v_mov_b32_e32 v69, v0
	v_mov_b32_e32 v70, v0
	v_mov_b32_e32 v71, v0
	v_mov_b32_e32 v80, v0
	v_mov_b32_e32 v81, v0
	v_mov_b32_e32 v82, v0
	v_mov_b32_e32 v83, v0
	v_mov_b32_e32 v84, v0
	v_mov_b32_e32 v85, v0
	v_mov_b32_e32 v86, v0
	v_mov_b32_e32 v87, v0
	v_mov_b32_e32 v96, v0
	v_mov_b32_e32 v97, v0
	v_mov_b32_e32 v98, v0
	v_mov_b32_e32 v99, v0
	v_mov_b32_e32 v100, v0
	v_mov_b32_e32 v101, v0
	v_mov_b32_e32 v102, v0
	v_mov_b32_e32 v103, v0
	v_mov_b32_e32 v112, v0
	v_mov_b32_e32 v113, v0
	v_mov_b32_e32 v114, v0
	v_mov_b32_e32 v115, v0
	v_mov_b32_e32 v116, v0
	v_mov_b32_e32 v117, v0
	v_mov_b32_e32 v118, v0
	v_mov_b32_e32 v119, v0
	v_mov_b32_e32 v72, v0
	v_mov_b32_e32 v73, v0
	v_mov_b32_e32 v74, v0
	v_mov_b32_e32 v75, v0
	v_mov_b32_e32 v76, v0
	v_mov_b32_e32 v77, v0
	v_mov_b32_e32 v78, v0
	v_mov_b32_e32 v79, v0
	v_mov_b32_e32 v88, v0
	v_mov_b32_e32 v89, v0
	v_mov_b32_e32 v90, v0
	v_mov_b32_e32 v91, v0
	v_mov_b32_e32 v92, v0
	v_mov_b32_e32 v93, v0
	v_mov_b32_e32 v94, v0
	v_mov_b32_e32 v95, v0
	v_mov_b32_e32 v104, v0
	v_mov_b32_e32 v105, v0
	v_mov_b32_e32 v106, v0
	v_mov_b32_e32 v107, v0
	v_mov_b32_e32 v108, v0
	v_mov_b32_e32 v109, v0
	v_mov_b32_e32 v110, v0
	v_mov_b32_e32 v111, v0
	v_mov_b32_e32 v120, v0
	v_mov_b32_e32 v121, v0
	v_mov_b32_e32 v122, v0
	v_mov_b32_e32 v123, v0
	v_mov_b32_e32 v124, v0
	v_mov_b32_e32 v125, v0
	v_mov_b32_e32 v126, v0
	v_mov_b32_e32 v127, v0
	s_branch .LBB0_253

; #define PG8_STAGE(bufoff, gbase, voff) do { _Pragma("unroll") for (int _i = 0; _i < 2; ++_i) \
;         __builtin_amdgcn_global_load_lds((const unsigned*)((const char*)(gbase) + (voff)[_i]), (PG8_LAS unsigned*)(lds + (bufoff) + ldsw + _i * 8192), 16, 0, 0); } while (0)
; #define PG8_LDA(dst, b, h) do { _Pragma("unroll") for (int m = 0; m < 4; ++m) _Pragma("unroll") for (int k = 0; k < 2; ++k) dst[m][k] = *(const PG8_LAS bf16x8*)(lds + PG8_SA(b, h) + aoff + m * 2048 + k * 1024); } while (0)
; #define PG8_LDB(dst, b, h) do { _Pragma("unroll") for (int n = 0; n < 2; ++n) _Pragma("unroll") for (int k = 0; k < 2; ++k) dst[n][k] = *(const PG8_LAS bf16x8*)(lds + PG8_SB(b, h) + boff + n * 2048 + k * 1024); } while (0)
; #define PG8_WAIT_V(n) asm volatile("s_waitcnt vmcnt(" #n ")" ::: "memory")
; #define PG8_WAIT_SEL(d, w4, w8) do { if constexpr (Epi::SPLIT) { if (d) { if constexpr (Epi::NSH == 4) PG8_WAIT_V(w4); else PG8_WAIT_V(w8); } else PG8_WAIT_V(8); } else PG8_WAIT_V(8); } while (0)
; #define PG8_SCHED __builtin_amdgcn_sched_barrier(0)
; template <class Epi, class Sched, bool ALIGN_EPI = false, bool SP2 = false>
; __device__ __forceinline__ void gemm_phase(PG8_LAS unsigned char* lds, const Gemm g, const Sched& S, const Epi& E) {
;     ...
;             const char* a1 = cA + (size_t)(t + 1) * kstep;
;             const char* a2 = last ? nA : cA + (size_t)(t + 2) * kstep; const char* b2 = last ? nB : cB + (size_t)(t + 2) * kstep;
;             const char* a3 = a2 + kstep; const char* b3 = b2 + kstep;
;             if (last && has_next) S.a_ready(nxt);
;             if constexpr (SP2) {
;             PG8_LDB(B0, 0, 0); PG8_LDB(B1, 0, 1); PG8_SCHED; PG8_LDA(At, 0, 0); PG8_STAGE(PG8_SA(1, 1), a1 + hstepA, voffA);
;             if (plast) PG8_WAIT_V(10); else PG8_WAIT_SEL(defer, 12, 16);
.LBB0_255:
	v_add_u32_e32 v128, 0, v239
	v_add_u32_e32 v129, 0x10000, v128
	v_add_u32_e32 v140, 0x14000, v128
	ds_read_b128 v[144:147], v129
	ds_read_b128 v[148:151], v129 offset:1024
	ds_read_b128 v[152:155], v129 offset:2048
	ds_read_b128 v[156:159], v129 offset:3072
	ds_read_b128 v[128:131], v140
	ds_read_b128 v[132:135], v140 offset:1024
	ds_read_b128 v[136:139], v140 offset:2048
	ds_read_b128 v[140:143], v140 offset:3072
	v_lshl_add_u64 v[220:221], s[24:25], 0, v[212:213]
	s_add_i32 m0, s35, 0xc000
	ds_read_b128 v[184:187], v240
	ds_read_b128 v[188:191], v240 offset:1024
	ds_read_b128 v[176:179], v240 offset:2048
	ds_read_b128 v[180:183], v240 offset:3072
	ds_read_b128 v[168:171], v240 offset:4096
	ds_read_b128 v[172:175], v240 offset:5120
	ds_read_b128 v[160:163], v240 offset:6144
	ds_read_b128 v[164:167], v240 offset:7168
	global_load_lds_dwordx4 v[220:221], off
	v_lshl_add_u64 v[220:221], s[24:25], 0, v[214:215]
	s_add_i32 m0, s35, 0xe000
	s_mov_b64 s[30:31], -1
	global_load_lds_dwordx4 v[220:221], off
	s_and_b64 vcc, exec, s[28:29]
	s_cbranch_vccz .LBB0_257
	s_waitcnt vmcnt(8)
	s_mov_b64 s[30:31], 0

; #define PG8_STAGE(bufoff, gbase, voff) do { _Pragma("unroll") for (int _i = 0; _i < 2; ++_i) \
;         __builtin_amdgcn_global_load_lds((const unsigned*)((const char*)(gbase) + (voff)[_i]), (PG8_LAS unsigned*)(lds + (bufoff) + ldsw + _i * 8192), 16, 0, 0); } while (0)
; #define PG8_LDA(dst, b, h) do { _Pragma("unroll") for (int m = 0; m < 4; ++m) _Pragma("unroll") for (int k = 0; k < 2; ++k) dst[m][k] = *(const PG8_LAS bf16x8*)(lds + PG8_SA(b, h) + aoff + m * 2048 + k * 1024); } while (0)
; #define PG8_LDB(dst, b, h) do { _Pragma("unroll") for (int n = 0; n < 2; ++n) _Pragma("unroll") for (int k = 0; k < 2; ++k) dst[n][k] = *(const PG8_LAS bf16x8*)(lds + PG8_SB(b, h) + boff + n * 2048 + k * 1024); } while (0)
; #define PG8_WAIT_V(n) asm volatile("s_waitcnt vmcnt(" #n ")" ::: "memory")
; #define PG8_WAIT_SEL(d, w4, w8) do { if constexpr (Epi::SPLIT) { if (d) { if constexpr (Epi::NSH == 4) PG8_WAIT_V(w4); else PG8_WAIT_V(w8); } else PG8_WAIT_V(8); } else PG8_WAIT_V(8); } while (0)
; #define PG8_BAR __builtin_amdgcn_s_barrier()
; template <class Epi, class Sched, bool ALIGN_EPI = false, bool SP2 = false>
; __device__ __forceinline__ void gemm_phase(PG8_LAS unsigned char* lds, const Gemm g, const Sched& S, const Epi& E) {
;     ...
;             const char* a2 = last ? nA : cA + (size_t)(t + 2) * kstep; const char* b2 = last ? nB : cB + (size_t)(t + 2) * kstep;
;             const char* a3 = a2 + kstep; const char* b3 = b2 + kstep;
;             if (last && has_next) S.a_ready(nxt);
;             if constexpr (SP2) {
;             PG8_LDB(B0, 0, 0); PG8_LDB(B1, 0, 1); PG8_SCHED; PG8_LDA(At, 0, 0); PG8_STAGE(PG8_SA(1, 1), a1 + hstepA, voffA);
;             if (plast) PG8_WAIT_V(10); else PG8_WAIT_SEL(defer, 12, 16);
;             PG8_WAIT_L(0); PG8_BAR; PG8_MMA(0, 0, At, B0); PG8_MMA(0, 1, At, B1);
;             if constexpr (Epi::SPLIT) { if (defer) {
;                 E.second(acc, prev, rv1, wr, wc, fr, fq);
;                 _Pragma("unroll") for (int b = 0; b < 2; ++b) _Pragma("unroll") for (int m = 0; m < 4; ++m) _Pragma("unroll") for (int n = 0; n < 2; ++n) acc[1][b][m][n] = (f32x4){0.f, 0.f, 0.f, 0.f}; } }
;             PG8_BAR; PG8_SCHED;
;             PG8_LDA(At, 0, 1); PG8_STAGE(PG8_SB(0, 0), b2, voffB); PG8_STAGE(PG8_SB(0, 1), b2 + hstep, voffB); PG8_STAGE(PG8_SA(0, 0), a2, voffA);
;             if (plast) PG8_WAIT_V(10); else PG8_WAIT_SEL(defer, 16, 24);
.LBB0_259:
	s_add_u32 s30, s24, 0x80
	s_addc_u32 s31, s25, 0
	s_waitcnt lgkmcnt(0)
	s_and_b64 s[26:27], s[26:27], exec
	s_cselect_b32 s27, s7, s31
	s_cselect_b32 s26, s6, s30
	s_cselect_b32 s31, s21, s33
	s_cselect_b32 s30, s20, s23
	s_barrier
	s_setprio 1
	s_waitcnt lgkmcnt(0)
	v_mfma_f32_16x16x32_bf16 v[124:127], v[144:147], v[184:187], v[124:127]
	v_mfma_f32_16x16x32_bf16 v[120:123], v[152:155], v[184:187], v[120:123]
	v_mfma_f32_16x16x32_bf16 v[108:111], v[144:147], v[176:179], v[108:111]
	v_mfma_f32_16x16x32_bf16 v[104:107], v[152:155], v[176:179], v[104:107]
	v_mfma_f32_16x16x32_bf16 v[92:95], v[144:147], v[168:171], v[92:95]
	v_mfma_f32_16x16x32_bf16 v[88:91], v[152:155], v[168:171], v[88:91]
	v_mfma_f32_16x16x32_bf16 v[76:79], v[144:147], v[160:163], v[76:79]
	v_mfma_f32_16x16x32_bf16 v[72:75], v[152:155], v[160:163], v[72:75]
	v_mfma_f32_16x16x32_bf16 v[124:127], v[148:151], v[188:191], v[124:127]
	v_mfma_f32_16x16x32_bf16 v[120:123], v[156:159], v[188:191], v[120:123]
	v_mfma_f32_16x16x32_bf16 v[108:111], v[148:151], v[180:183], v[108:111]
	v_mfma_f32_16x16x32_bf16 v[104:107], v[156:159], v[180:183], v[104:107]
	v_mfma_f32_16x16x32_bf16 v[92:95], v[148:151], v[172:175], v[92:95]
	v_mfma_f32_16x16x32_bf16 v[88:91], v[156:159], v[172:175], v[88:91]
	v_mfma_f32_16x16x32_bf16 v[76:79], v[148:151], v[164:167], v[76:79]
	v_mfma_f32_16x16x32_bf16 v[72:75], v[156:159], v[164:167], v[72:75]
	s_setprio 0
	s_setprio 1
	v_mfma_f32_16x16x32_bf16 v[116:119], v[128:131], v[184:187], v[116:119]
	v_mfma_f32_16x16x32_bf16 v[112:115], v[136:139], v[184:187], v[112:115]
	v_mfma_f32_16x16x32_bf16 v[100:103], v[128:131], v[176:179], v[100:103]
	v_mfma_f32_16x16x32_bf16 v[96:99], v[136:139], v[176:179], v[96:99]
	v_mfma_f32_16x16x32_bf16 v[84:87], v[128:131], v[168:171], v[84:87]
	v_mfma_f32_16x16x32_bf16 v[80:83], v[136:139], v[168:171], v[80:83]
	v_mfma_f32_16x16x32_bf16 v[68:71], v[128:131], v[160:163], v[68:71]
	v_mfma_f32_16x16x32_bf16 v[64:67], v[136:139], v[160:163], v[64:67]
	v_mfma_f32_16x16x32_bf16 v[116:119], v[132:135], v[188:191], v[116:119]
	v_mfma_f32_16x16x32_bf16 v[112:115], v[140:143], v[188:191], v[112:115]
	v_mfma_f32_16x16x32_bf16 v[100:103], v[132:135], v[180:183], v[100:103]
	v_mfma_f32_16x16x32_bf16 v[96:99], v[140:143], v[180:183], v[96:99]
	v_mfma_f32_16x16x32_bf16 v[84:87], v[132:135], v[172:175], v[84:87]
	v_mfma_f32_16x16x32_bf16 v[80:83], v[140:143], v[172:175], v[80:83]
	v_mfma_f32_16x16x32_bf16 v[68:71], v[132:135], v[164:167], v[68:71]
	v_mfma_f32_16x16x32_bf16 v[64:67], v[140:143], v[164:167], v[64:67]
	s_setprio 0
	s_barrier
	s_mov_b32 m0, s36
	v_lshl_add_u64 v[222:223], s[30:31], 0, v[192:193]
	v_lshl_add_u64 v[220:221], s[30:31], 0, v[204:205]
	s_add_u32 s30, s30, s12
	ds_read_b128 v[184:187], v240 offset:16384
	ds_read_b128 v[188:191], v240 offset:17408
	ds_read_b128 v[176:179], v240 offset:18432
	ds_read_b128 v[180:183], v240 offset:19456
	ds_read_b128 v[168:171], v240 offset:20480
	ds_read_b128 v[172:175], v240 offset:21504
	ds_read_b128 v[160:163], v240 offset:22528
	ds_read_b128 v[164:167], v240 offset:23552
	global_load_lds_dwordx4 v[222:223], off
	s_mov_b32 m0, s37
	s_addc_u32 s31, s31, s13
	global_load_lds_dwordx4 v[220:221], off
	v_lshl_add_u64 v[230:231], s[30:31], 0, v[192:193]
	s_mov_b32 m0, s38
	v_lshl_add_u64 v[228:229], s[30:31], 0, v[204:205]
	global_load_lds_dwordx4 v[230:231], off
	s_mov_b32 m0, s39
	v_lshl_add_u64 v[224:225], s[26:27], 0, v[208:209]
	global_load_lds_dwordx4 v[228:229], off
	s_mov_b32 m0, s35
	v_lshl_add_u64 v[226:227], s[26:27], 0, v[206:207]
	global_load_lds_dwordx4 v[224:225], off
	s_mov_b32 m0, s40
	s_mov_b64 s[30:31], -1
	global_load_lds_dwordx4 v[226:227], off
	s_and_b64 vcc, exec, s[28:29]
	s_cbranch_vccz .LBB0_261
	s_waitcnt vmcnt(8)
	s_mov_b64 s[30:31], 0

; __device__ __forceinline__ unsigned cvt_pk_bf16(float lo, float hi) { unsigned r; asm volatile("v_cvt_pk_bf16_f32 %0, %1, %2" : "=v"(r) : "v"(lo), "v"(hi)); return r; }
; #define LAS __attribute__((address_space(3)))
;     __device__ __forceinline__ void operator()(const f32x4 (&acc)[2][2][4][2], const pg8::Unit& u, int wr, int wc, int fr_, int fq_, LAS const unsigned char* xl) const {
;     ...
;         const int row0 = u.pm * 256 + wr * 64 + fr;
;         float rv[2][4];
;         if (MODE == 0 || MODE == 1 || MODE == 4) {
; #pragma unroll
;             for (int ai = 0; ai < 2; ++ai)
; #pragma unroll
;                 for (int m = 0; m < 4; ++m) { const f32x4 pv = *(LAS const f32x4*)(xl + (ai * 128 + wr * 64 + m * 16 + fr) * 64 + fq * 16); rv[ai][m] = (pv[0] + pv[1]) + (pv[2] + pv[3]); }
; #pragma unroll
;             for (int ai = 0; ai < 2; ++ai)
; #pragma unroll
;                 for (int m = 0; m < 4; ++m) rv[ai][m] = __builtin_amdgcn_rsqf(xrow16_sum(rv[ai][m]) * (1.0f / 1024.0f) + EPS);
;         }
;         if (MODE == 0 || MODE == 1 || MODE == 2) {
; #pragma unroll
;             for (int ai = 0; ai < 2; ++ai)
; #pragma unroll
;                 for (int m = 0; m < 4; ++m) {
;                     const int row = row0 + ai * 128 + m * 16;
;                     const float rinv = (MODE == 2) ? 1.f : rv[ai][m];
;                     if (MODE == 0 || MODE == 2) {
;                         bf16_t* rowp = O + (size_t)row * ldc + u.pn * 256 + wc * 32 + 8 * fq;
; #pragma unroll
;                         for (int bj = 0; bj < 2; ++bj) { const f32x4 v0 = acc[ai][bj][m][0] * rinv, v1 = acc[ai][bj][m][1] * rinv;
;                             u32x4 w; w.x = pg8::cvt_pk_bf16(v0[0], v0[1]); w.y = pg8::cvt_pk_bf16(v0[2], v0[3]); w.z = pg8::cvt_pk_bf16(v1[0], v1[1]); w.w = pg8::cvt_pk_bf16(v1[2], v1[3]);
;                             *(u32x4*)(rowp + bj * 128) = w; }
.LBB0_265:
	v_mov_b32_e32 v128, v237
	v_mov_b32_e32 v133, v238
	s_add_i32 s23, 0, 0x20000
	v_add_u32_e32 v134, s46, v128
	v_lshlrev_b32_e32 v128, 4, v133
	v_lshlrev_b32_e32 v129, 6, v134
	v_add3_u32 v132, s23, v128, v129
	ds_read_b128 v[128:131], v132
	s_and_b64 vcc, exec, s[4:5]
	s_waitcnt lgkmcnt(0)
	v_add_f32_e32 v128, v128, v129
	v_add_f32_e32 v129, v130, v131
	v_add_f32_e32 v135, v128, v129
	ds_read_b128 v[128:131], v132 offset:1024
	s_waitcnt lgkmcnt(0)
	v_add_f32_e32 v128, v128, v129
	v_add_f32_e32 v129, v130, v131
	v_add_f32_e32 v136, v128, v129
	ds_read_b128 v[128:131], v132 offset:2048
	s_waitcnt lgkmcnt(0)
	v_add_f32_e32 v128, v128, v129
	v_add_f32_e32 v129, v130, v131
	v_add_f32_e32 v137, v128, v129
	ds_read_b128 v[128:131], v132 offset:3072
	s_waitcnt lgkmcnt(0)
	v_add_f32_e32 v128, v128, v129
	v_add_f32_e32 v129, v130, v131
	v_add_f32_e32 v138, v128, v129
	ds_read_b128 v[128:131], v132 offset:8192
	s_waitcnt lgkmcnt(0)
	v_add_f32_e32 v128, v128, v129
	v_add_f32_e32 v129, v130, v131
	v_add_f32_e32 v139, v128, v129
	ds_read_b128 v[128:131], v132 offset:9216
	s_waitcnt lgkmcnt(0)
	v_add_f32_e32 v128, v128, v129
	v_add_f32_e32 v129, v130, v131
	v_add_f32_e32 v141, v128, v129
	ds_read_b128 v[128:131], v132 offset:10240
	s_waitcnt lgkmcnt(0)
	v_add_f32_e32 v128, v128, v129
	v_add_f32_e32 v129, v130, v131
	v_add_f32_e32 v143, v128, v129
	ds_read_b128 v[128:131], v132 offset:11264
	s_waitcnt lgkmcnt(0)
	v_add_f32_e32 v128, v128, v129
	v_add_f32_e32 v129, v130, v131
	v_add_f32_e32 v128, v128, v129
	v_mov_b32_e32 v129, v135
	s_nop 1
	v_permlane16_swap_b32_e32 v135, v129
	v_add_f32_e32 v129, v135, v129
	v_mov_b32_e32 v130, v129
	s_nop 1
	v_permlane32_swap_b32_e32 v129, v130
	v_add_f32_e32 v129, v129, v130
	v_fmamk_f32 v129, v129, 0x3a800000, v233
	v_rsq_f32_e32 v142, v129
	v_mov_b32_e32 v129, v136
	s_nop 1
	v_permlane16_swap_b32_e32 v136, v129
	v_add_f32_e32 v129, v136, v129
	v_mov_b32_e32 v130, v129
	s_nop 1
	v_permlane32_swap_b32_e32 v129, v130
	v_add_f32_e32 v129, v129, v130
	v_fmamk_f32 v129, v129, 0x3a800000, v233
	v_rsq_f32_e32 v144, v129
	v_mov_b32_e32 v129, v137
	s_nop 1
	v_permlane16_swap_b32_e32 v137, v129
	v_add_f32_e32 v129, v137, v129
	v_mov_b32_e32 v130, v129
	s_nop 1
	v_permlane32_swap_b32_e32 v129, v130
	v_add_f32_e32 v129, v129, v130
	v_fmamk_f32 v129, v129, 0x3a800000, v233
	v_rsq_f32_e32 v146, v129
	v_mov_b32_e32 v129, v138
	s_nop 1
	v_permlane16_swap_b32_e32 v138, v129
	v_add_f32_e32 v129, v138, v129
	v_mov_b32_e32 v130, v129
	s_nop 1
	v_permlane32_swap_b32_e32 v129, v130
	v_add_f32_e32 v129, v129, v130
	v_fmamk_f32 v129, v129, 0x3a800000, v233
	v_rsq_f32_e32 v140, v129
	v_mov_b32_e32 v129, v139
	s_nop 1
	v_permlane16_swap_b32_e32 v139, v129
	v_add_f32_e32 v129, v139, v129
	v_mov_b32_e32 v130, v129
	s_nop 1
	v_permlane32_swap_b32_e32 v129, v130
	v_add_f32_e32 v129, v129, v130
	v_fmamk_f32 v129, v129, 0x3a800000, v233
	v_rsq_f32_e32 v138, v129
	v_mov_b32_e32 v129, v141
	s_nop 1
	v_permlane16_swap_b32_e32 v141, v129
	v_add_f32_e32 v129, v141, v129
	v_mov_b32_e32 v130, v129
	s_nop 1
	v_permlane32_swap_b32_e32 v129, v130
	v_add_f32_e32 v129, v129, v130
	v_fmamk_f32 v129, v129, 0x3a800000, v233
	v_rsq_f32_e32 v136, v129
	v_mov_b32_e32 v129, v143
	s_nop 1
	v_permlane16_swap_b32_e32 v143, v129
	v_add_f32_e32 v129, v143, v129
	v_mov_b32_e32 v130, v129
	s_nop 1
	v_permlane32_swap_b32_e32 v129, v130
	v_add_f32_e32 v129, v129, v130
	v_fmamk_f32 v129, v129, 0x3a800000, v233
	v_rsq_f32_e32 v132, v129
	v_mov_b32_e32 v129, v128
	s_nop 1
	v_permlane16_swap_b32_e32 v128, v129
	v_add_f32_e32 v128, v128, v129
	v_mov_b32_e32 v129, v128
	s_nop 1
	v_permlane32_swap_b32_e32 v128, v129
	v_add_f32_e32 v128, v128, v129
	v_lshl_add_u32 v129, s22, 8, v134
	v_mov_b64_e32 v[130:131], s[72:73]
	v_mad_i64_i32 v[148:149], s[22:23], v129, s83, v[130:131]
	s_lshl_b32 s22, s50, 8
	s_ashr_i32 s23, s22, 31
	v_lshlrev_b32_e32 v134, 3, v133
	s_lshl_b64 s[22:23], s[22:23], 1
	v_ashrrev_i32_e32 v135, 31, v134
	v_lshl_add_u64 v[148:149], v[148:149], 0, s[22:23]
	v_lshl_add_u64 v[148:149], v[148:149], 0, s[86:87]
	v_lshlrev_b64 v[134:135], 1, v[134:135]
	v_lshl_add_u64 v[148:149], v[148:149], 0, v[134:135]
	v_pk_mul_f32 v[126:127], v[126:127], v[142:143] op_sel_hi:[1,0]
	v_pk_mul_f32 v[124:125], v[124:125], v[142:143] op_sel_hi:[1,0]
	v_pk_mul_f32 v[150:151], v[122:123], v[142:143] op_sel_hi:[1,0]
	v_pk_mul_f32 v[122:123], v[120:121], v[142:143] op_sel_hi:[1,0]
	v_cvt_pk_bf16_f32 v120, v124, v125
	v_cvt_pk_bf16_f32 v121, v126, v127
	v_pk_mul_f32 v[116:117], v[116:117], v[142:143] op_sel_hi:[1,0]
	v_cvt_pk_bf16_f32 v122, v122, v123
	v_cvt_pk_bf16_f32 v123, v150, v151
	global_store_dwordx4 v[148:149], v[120:123], off
	v_pk_mul_f32 v[118:119], v[118:119], v[142:143] op_sel_hi:[1,0]
	v_pk_mul_f32 v[110:111], v[110:111], v[144:145] op_sel_hi:[1,0]
	v_pk_mul_f32 v[120:121], v[114:115], v[142:143] op_sel_hi:[1,0]
	v_pk_mul_f32 v[114:115], v[112:113], v[142:143] op_sel_hi:[1,0]
	v_cvt_pk_bf16_f32 v112, v116, v117
	v_cvt_pk_bf16_f32 v113, v118, v119
	v_pk_mul_f32 v[108:109], v[108:109], v[144:145] op_sel_hi:[1,0]
	v_cvt_pk_bf16_f32 v114, v114, v115
	v_cvt_pk_bf16_f32 v115, v120, v121
	global_store_dwordx4 v[148:149], v[112:115], off offset:256
	v_pk_mul_f32 v[100:101], v[100:101], v[144:145] op_sel_hi:[1,0]
	v_pk_mul_f32 v[102:103], v[102:103], v[144:145] op_sel_hi:[1,0]
	v_add_u32_e32 v112, 16, v129
	v_mad_i64_i32 v[112:113], s[24:25], v112, s83, v[130:131]
	v_lshl_add_u64 v[112:113], v[112:113], 0, s[22:23]
	v_lshl_add_u64 v[112:113], v[112:113], 0, s[86:87]
	v_lshl_add_u64 v[112:113], v[112:113], 0, v[134:135]
	v_pk_mul_f32 v[114:115], v[106:107], v[144:145] op_sel_hi:[1,0]
; __device__ __forceinline__ unsigned cvt_pk_bf16(float lo, float hi) { unsigned r; asm volatile("v_cvt_pk_bf16_f32 %0, %1, %2" : "=v"(r) : "v"(lo), "v"(hi)); return r; }
;     __device__ __forceinline__ void operator()(const f32x4 (&acc)[2][2][4][2], const pg8::Unit& u, int wr, int wc, int fr_, int fq_, LAS const unsigned char* xl) const {
;     ...
; #pragma unroll
;             for (int ai = 0; ai < 2; ++ai)
; #pragma unroll
;                 for (int m = 0; m < 4; ++m) {
;                     const int row = row0 + ai * 128 + m * 16;
;                     const float rinv = (MODE == 2) ? 1.f : rv[ai][m];
;                     if (MODE == 0 || MODE == 2) {
;                         bf16_t* rowp = O + (size_t)row * ldc + u.pn * 256 + wc * 32 + 8 * fq;
; #pragma unroll
;                         for (int bj = 0; bj < 2; ++bj) { const f32x4 v0 = acc[ai][bj][m][0] * rinv, v1 = acc[ai][bj][m][1] * rinv;
;                             u32x4 w; w.x = pg8::cvt_pk_bf16(v0[0], v0[1]); w.y = pg8::cvt_pk_bf16(v0[2], v0[3]); w.z = pg8::cvt_pk_bf16(v1[0], v1[1]); w.w = pg8::cvt_pk_bf16(v1[2], v1[3]);
;                             *(u32x4*)(rowp + bj * 128) = w; }
	v_pk_mul_f32 v[106:107], v[104:105], v[144:145] op_sel_hi:[1,0]
	v_cvt_pk_bf16_f32 v104, v108, v109
	v_cvt_pk_bf16_f32 v105, v110, v111
	v_pk_mul_f32 v[94:95], v[94:95], v[146:147] op_sel_hi:[1,0]
	v_cvt_pk_bf16_f32 v106, v106, v107
	v_cvt_pk_bf16_f32 v107, v114, v115
	global_store_dwordx4 v[112:113], v[104:107], off
	v_pk_mul_f32 v[92:93], v[92:93], v[146:147] op_sel_hi:[1,0]
	v_pk_mul_f32 v[84:85], v[84:85], v[146:147] op_sel_hi:[1,0]
	v_pk_mul_f32 v[104:105], v[98:99], v[144:145] op_sel_hi:[1,0]
	v_pk_mul_f32 v[98:99], v[96:97], v[144:145] op_sel_hi:[1,0]
	v_cvt_pk_bf16_f32 v96, v100, v101
	v_cvt_pk_bf16_f32 v97, v102, v103
	v_pk_mul_f32 v[86:87], v[86:87], v[146:147] op_sel_hi:[1,0]
	v_cvt_pk_bf16_f32 v98, v98, v99
	v_cvt_pk_bf16_f32 v99, v104, v105
	global_store_dwordx4 v[112:113], v[96:99], off offset:256
	v_pk_mul_f32 v[78:79], v[78:79], v[140:141] op_sel_hi:[1,0]
	v_pk_mul_f32 v[76:77], v[76:77], v[140:141] op_sel_hi:[1,0]
	v_add_u32_e32 v96, 32, v129
	v_mad_i64_i32 v[96:97], s[24:25], v96, s83, v[130:131]
	v_lshl_add_u64 v[96:97], v[96:97], 0, s[22:23]
	v_lshl_add_u64 v[96:97], v[96:97], 0, s[86:87]
	v_lshl_add_u64 v[96:97], v[96:97], 0, v[134:135]
	v_pk_mul_f32 v[98:99], v[90:91], v[146:147] op_sel_hi:[1,0]
	v_pk_mul_f32 v[90:91], v[88:89], v[146:147] op_sel_hi:[1,0]
	v_cvt_pk_bf16_f32 v88, v92, v93
	v_cvt_pk_bf16_f32 v89, v94, v95
	v_pk_mul_f32 v[68:69], v[68:69], v[140:141] op_sel_hi:[1,0]
	v_cvt_pk_bf16_f32 v90, v90, v91
	v_cvt_pk_bf16_f32 v91, v98, v99
	global_store_dwordx4 v[96:97], v[88:91], off
	v_pk_mul_f32 v[70:71], v[70:71], v[140:141] op_sel_hi:[1,0]
	v_pk_mul_f32 v[62:63], v[62:63], v[138:139] op_sel_hi:[1,0]
	v_pk_mul_f32 v[88:89], v[82:83], v[146:147] op_sel_hi:[1,0]
	v_pk_mul_f32 v[82:83], v[80:81], v[146:147] op_sel_hi:[1,0]
	v_cvt_pk_bf16_f32 v80, v84, v85
	v_cvt_pk_bf16_f32 v81, v86, v87
	v_pk_mul_f32 v[60:61], v[60:61], v[138:139] op_sel_hi:[1,0]
	v_cvt_pk_bf16_f32 v82, v82, v83
	v_cvt_pk_bf16_f32 v83, v88, v89
	global_store_dwordx4 v[96:97], v[80:83], off offset:256
	v_pk_mul_f32 v[52:53], v[52:53], v[138:139] op_sel_hi:[1,0]
	v_pk_mul_f32 v[54:55], v[54:55], v[138:139] op_sel_hi:[1,0]
	v_add_u32_e32 v80, 48, v129
	v_mad_i64_i32 v[80:81], s[24:25], v80, s83, v[130:131]
	v_lshl_add_u64 v[80:81], v[80:81], 0, s[22:23]
	v_lshl_add_u64 v[80:81], v[80:81], 0, s[86:87]
	v_lshl_add_u64 v[80:81], v[80:81], 0, v[134:135]
	v_pk_mul_f32 v[82:83], v[74:75], v[140:141] op_sel_hi:[1,0]
	v_pk_mul_f32 v[74:75], v[72:73], v[140:141] op_sel_hi:[1,0]
	v_cvt_pk_bf16_f32 v72, v76, v77
	v_cvt_pk_bf16_f32 v73, v78, v79
	v_pk_mul_f32 v[46:47], v[46:47], v[136:137] op_sel_hi:[1,0]
	v_cvt_pk_bf16_f32 v74, v74, v75
	v_cvt_pk_bf16_f32 v75, v82, v83
	global_store_dwordx4 v[80:81], v[72:75], off
	v_pk_mul_f32 v[44:45], v[44:45], v[136:137] op_sel_hi:[1,0]
	v_pk_mul_f32 v[36:37], v[36:37], v[136:137] op_sel_hi:[1,0]
	v_pk_mul_f32 v[72:73], v[66:67], v[140:141] op_sel_hi:[1,0]
	v_pk_mul_f32 v[66:67], v[64:65], v[140:141] op_sel_hi:[1,0]
	v_cvt_pk_bf16_f32 v64, v68, v69
	v_cvt_pk_bf16_f32 v65, v70, v71
	v_pk_mul_f32 v[38:39], v[38:39], v[136:137] op_sel_hi:[1,0]
	v_cvt_pk_bf16_f32 v66, v66, v67
	v_cvt_pk_bf16_f32 v67, v72, v73
	global_store_dwordx4 v[80:81], v[64:67], off offset:256
	v_pk_mul_f32 v[30:31], v[30:31], v[132:133] op_sel_hi:[1,0]
	v_pk_mul_f32 v[28:29], v[28:29], v[132:133] op_sel_hi:[1,0]
	v_add_u32_e32 v64, 0x80, v129
	v_mad_i64_i32 v[64:65], s[24:25], v64, s83, v[130:131]
	v_lshl_add_u64 v[64:65], v[64:65], 0, s[22:23]
	v_lshl_add_u64 v[64:65], v[64:65], 0, s[86:87]
	v_lshl_add_u64 v[64:65], v[64:65], 0, v[134:135]
	v_pk_mul_f32 v[66:67], v[58:59], v[138:139] op_sel_hi:[1,0]
	v_pk_mul_f32 v[58:59], v[56:57], v[138:139] op_sel_hi:[1,0]
	v_cvt_pk_bf16_f32 v56, v60, v61
; __device__ __forceinline__ unsigned cvt_pk_bf16(float lo, float hi) { unsigned r; asm volatile("v_cvt_pk_bf16_f32 %0, %1, %2" : "=v"(r) : "v"(lo), "v"(hi)); return r; }
; #define PG8_WAIT_V(n) asm volatile("s_waitcnt vmcnt(" #n ")" ::: "memory")
; #define PG8_BAR __builtin_amdgcn_s_barrier()
; template <class Epi, class Sched, bool ALIGN_EPI = false, bool SP2 = false>
; __device__ __forceinline__ void gemm_phase(PG8_LAS unsigned char* lds, const Gemm g, const Sched& S, const Epi& E) {
;     ...
;         if constexpr (ALIGN_EPI) { if (wr == 0) PG8_BAR; }
;         if constexpr (Epi::SPLIT) {
;             if (has_next) { E.first(acc, cur, rv1, wr, wc, fr, fq); prev = cur; }
;             else E(acc, cur, wr, wc, fr, fq, lds + STAGE_BYTES);
;         } else if constexpr (!Epi::AFTER_DRAIN) { E(acc, cur, wr, wc, fr, fq, lds + STAGE_BYTES); S.done(cur); }
;         if (!has_next) break;
; #pragma unroll
;         for (int a = 0; a < (Epi::SPLIT ? 1 : 2); ++a)
; #pragma unroll
;             for (int b = 0; b < 2; ++b)
; #pragma unroll
;                 for (int m = 0; m < 4; ++m)
; #pragma unroll
;                     for (int n = 0; n < 2; ++n) acc[a][b][m][n] = (f32x4){0.f, 0.f, 0.f, 0.f};
;         cur = nxt; cA = nA; cB = nB; ++ui;
;         if constexpr (ALIGN_EPI) { if (wr == 1) PG8_BAR; }
;     }
;     PG8_WAIT_V(0);
;     if constexpr (!ALIGN_EPI) { if (wr == 0) PG8_BAR; }
;     __device__ __forceinline__ void operator()(const f32x4 (&acc)[2][2][4][2], const pg8::Unit& u, int wr, int wc, int fr_, int fq_, LAS const unsigned char* xl) const {
;     ...
;                 for (int m = 0; m < 4; ++m) {
;                     const int row = row0 + ai * 128 + m * 16;
;                     const float rinv = (MODE == 2) ? 1.f : rv[ai][m];
;                     if (MODE == 0 || MODE == 2) {
;                         bf16_t* rowp = O + (size_t)row * ldc + u.pn * 256 + wc * 32 + 8 * fq;
; #pragma unroll
;                         for (int bj = 0; bj < 2; ++bj) { const f32x4 v0 = acc[ai][bj][m][0] * rinv, v1 = acc[ai][bj][m][1] * rinv;
;                             u32x4 w; w.x = pg8::cvt_pk_bf16(v0[0], v0[1]); w.y = pg8::cvt_pk_bf16(v0[2], v0[3]); w.z = pg8::cvt_pk_bf16(v1[0], v1[1]); w.w = pg8::cvt_pk_bf16(v1[2], v1[3]);
;                             *(u32x4*)(rowp + bj * 128) = w; }
	v_cvt_pk_bf16_f32 v57, v62, v63
	v_fmamk_f32 v128, v128, 0x3a800000, v233
	v_cvt_pk_bf16_f32 v58, v58, v59
	v_cvt_pk_bf16_f32 v59, v66, v67
	global_store_dwordx4 v[64:65], v[56:59], off
	v_pk_mul_f32 v[20:21], v[20:21], v[132:133] op_sel_hi:[1,0]
	v_rsq_f32_e32 v128, v128
	v_pk_mul_f32 v[56:57], v[50:51], v[138:139] op_sel_hi:[1,0]
	v_pk_mul_f32 v[50:51], v[48:49], v[138:139] op_sel_hi:[1,0]
	v_cvt_pk_bf16_f32 v48, v52, v53
	v_cvt_pk_bf16_f32 v49, v54, v55
	v_pk_mul_f32 v[22:23], v[22:23], v[132:133] op_sel_hi:[1,0]
	v_cvt_pk_bf16_f32 v50, v50, v51
	v_cvt_pk_bf16_f32 v51, v56, v57
	global_store_dwordx4 v[64:65], v[48:51], off offset:256
	v_pk_mul_f32 v[14:15], v[14:15], v[128:129] op_sel_hi:[1,0]
	v_pk_mul_f32 v[12:13], v[12:13], v[128:129] op_sel_hi:[1,0]
	v_add_u32_e32 v48, 0x90, v129
	v_mad_i64_i32 v[48:49], s[24:25], v48, s83, v[130:131]
	v_lshl_add_u64 v[48:49], v[48:49], 0, s[22:23]
	v_lshl_add_u64 v[48:49], v[48:49], 0, s[86:87]
	v_lshl_add_u64 v[48:49], v[48:49], 0, v[134:135]
	v_pk_mul_f32 v[50:51], v[42:43], v[136:137] op_sel_hi:[1,0]
	v_pk_mul_f32 v[42:43], v[40:41], v[136:137] op_sel_hi:[1,0]
	v_cvt_pk_bf16_f32 v40, v44, v45
	v_cvt_pk_bf16_f32 v41, v46, v47
	v_pk_mul_f32 v[6:7], v[6:7], v[128:129] op_sel_hi:[1,0]
	v_cvt_pk_bf16_f32 v42, v42, v43
	v_cvt_pk_bf16_f32 v43, v50, v51
	global_store_dwordx4 v[48:49], v[40:43], off
	v_pk_mul_f32 v[4:5], v[4:5], v[128:129] op_sel_hi:[1,0]
	s_nop 0
	v_pk_mul_f32 v[40:41], v[34:35], v[136:137] op_sel_hi:[1,0]
	v_pk_mul_f32 v[34:35], v[32:33], v[136:137] op_sel_hi:[1,0]
	v_cvt_pk_bf16_f32 v32, v36, v37
	v_cvt_pk_bf16_f32 v33, v38, v39
	s_nop 0
	v_cvt_pk_bf16_f32 v34, v34, v35
	v_cvt_pk_bf16_f32 v35, v40, v41
	global_store_dwordx4 v[48:49], v[32:35], off offset:256
	s_nop 1
	v_add_u32_e32 v32, 0xa0, v129
	v_mad_i64_i32 v[32:33], s[24:25], v32, s83, v[130:131]
	v_lshl_add_u64 v[32:33], v[32:33], 0, s[22:23]
	v_lshl_add_u64 v[32:33], v[32:33], 0, s[86:87]
	v_lshl_add_u64 v[32:33], v[32:33], 0, v[134:135]
	v_pk_mul_f32 v[34:35], v[26:27], v[132:133] op_sel_hi:[1,0]
	v_pk_mul_f32 v[26:27], v[24:25], v[132:133] op_sel_hi:[1,0]
	v_cvt_pk_bf16_f32 v24, v28, v29
	v_cvt_pk_bf16_f32 v25, v30, v31
	s_nop 0
	v_cvt_pk_bf16_f32 v26, v26, v27
	v_cvt_pk_bf16_f32 v27, v34, v35
	global_store_dwordx4 v[32:33], v[24:27], off
	s_nop 1
	v_pk_mul_f32 v[24:25], v[18:19], v[132:133] op_sel_hi:[1,0]
	v_pk_mul_f32 v[18:19], v[16:17], v[132:133] op_sel_hi:[1,0]
	v_cvt_pk_bf16_f32 v16, v20, v21
	v_cvt_pk_bf16_f32 v17, v22, v23
	s_nop 0
	v_cvt_pk_bf16_f32 v18, v18, v19
	v_cvt_pk_bf16_f32 v19, v24, v25
	global_store_dwordx4 v[32:33], v[16:19], off offset:256
	s_nop 1
	v_add_u32_e32 v16, 0xb0, v129
	v_mad_i64_i32 v[16:17], s[24:25], v16, s83, v[130:131]
	v_lshl_add_u64 v[16:17], v[16:17], 0, s[22:23]
	v_lshl_add_u64 v[16:17], v[16:17], 0, s[86:87]
	v_lshl_add_u64 v[16:17], v[16:17], 0, v[134:135]
	v_pk_mul_f32 v[18:19], v[10:11], v[128:129] op_sel_hi:[1,0]
	v_pk_mul_f32 v[10:11], v[8:9], v[128:129] op_sel_hi:[1,0]
	v_cvt_pk_bf16_f32 v8, v12, v13
	v_cvt_pk_bf16_f32 v9, v14, v15
	s_mov_b64 s[22:23], -1
	v_cvt_pk_bf16_f32 v10, v10, v11
	v_cvt_pk_bf16_f32 v11, v18, v19
	global_store_dwordx4 v[16:17], v[8:11], off
	s_nop 1
	v_pk_mul_f32 v[8:9], v[2:3], v[128:129] op_sel_hi:[1,0]
	v_pk_mul_f32 v[2:3], v[0:1], v[128:129] op_sel_hi:[1,0]
	v_cvt_pk_bf16_f32 v0, v4, v5
	v_cvt_pk_bf16_f32 v1, v6, v7
	s_nop 0
	v_cvt_pk_bf16_f32 v2, v2, v3
	v_cvt_pk_bf16_f32 v3, v8, v9
	global_store_dwordx4 v[16:17], v[0:3], off offset:256
	s_cbranch_vccnz .LBB0_243
	s_andn2_b64 vcc, exec, s[0:1]
	s_cbranch_vccnz .LBB0_242
	s_barrier
	s_branch .LBB0_242
.LBB0_268:
	s_waitcnt vmcnt(0)
	s_barrier
	s_mov_b64 s[0:1], -1
	s_and_b64 vcc, exec, s[66:67]
	s_cbranch_vccz .LBB0_229

; #define PG8_LAS __attribute__((address_space(3)))
; #define PG8_STAGE(bufoff, gbase, voff) do { _Pragma("unroll") for (int _i = 0; _i < 2; ++_i) \
;         __builtin_amdgcn_global_load_lds((const unsigned*)((const char*)(gbase) + (voff)[_i]), (PG8_LAS unsigned*)(lds + (bufoff) + ldsw + _i * 8192), 16, 0, 0); } while (0)
; #define PG8_LDA(dst, b, h) do { _Pragma("unroll") for (int m = 0; m < 4; ++m) _Pragma("unroll") for (int k = 0; k < 2; ++k) dst[m][k] = *(const PG8_LAS bf16x8*)(lds + PG8_SA(b, h) + aoff + m * 2048 + k * 1024); } while (0)
; #define PG8_WAIT_V(n) asm volatile("s_waitcnt vmcnt(" #n ")" ::: "memory")
; #define PG8_BAR __builtin_amdgcn_s_barrier()
; template <class Epi, class Sched, bool ALIGN_EPI = false, bool SP2 = false>
; __device__ __forceinline__ void gemm_phase(PG8_LAS unsigned char* lds, const Gemm g, const Sched& S, const Epi& E) {
;     ...
;     for (;;) {
;         const bool has_next = S.next(ui + 1, nxt);
;         const char* nA = has_next ? (const char*)g.A + (size_t)nxt.pm * tstepA : cA; const char* nB = has_next ? (const char*)g.Bt + (size_t)nxt.pn * tstep : cB;
;         for (int t = 0; t < nt; t += 2) {
;             const bool last = (t == nt - 2);
;             if constexpr (Epi::RVLDS) { if (last) {
;                 const char* pg = (const char*)E.part_in + (size_t)cur.pm * 16384 + (size_t)tid * 16;
;                 __builtin_amdgcn_global_load_lds((const unsigned*)pg, (PG8_LAS unsigned*)(lds + STAGE_BYTES + ldsw), 16, 0, 0);
;                 __builtin_amdgcn_global_load_lds((const unsigned*)(pg + 8192), (PG8_LAS unsigned*)(lds + STAGE_BYTES + 8192 + ldsw), 16, 0, 0); } }
;             const bool plast = Epi::RVLDS && last;
;             const bool defer = Epi::SPLIT && (t == 0) && (ui > 0);
;             const char* a1 = cA + (size_t)(t + 1) * kstep;
;             const char* a2 = last ? nA : cA + (size_t)(t + 2) * kstep; const char* b2 = last ? nB : cB + (size_t)(t + 2) * kstep;
;             const char* a3 = a2 + kstep; const char* b3 = b2 + kstep;
;             if (last && has_next) S.a_ready(nxt);
;             if constexpr (SP2) {
;             PG8_LDB(B0, 0, 0); PG8_LDB(B1, 0, 1); PG8_SCHED; PG8_LDA(At, 0, 0); PG8_STAGE(PG8_SA(1, 1), a1 + hstepA, voffA);
;             if (plast) PG8_WAIT_V(10); else PG8_WAIT_SEL(defer, 12, 16);
;             PG8_WAIT_L(0); PG8_BAR; PG8_MMA(0, 0, At, B0); PG8_MMA(0, 1, At, B1);
.LBB0_351:
	s_andn2_b64 vcc, exec, s[22:23]
	s_cbranch_vccnz .Lzt_1
	s_add_u32 s0, s0, 0x80
	s_addc_u32 s1, s1, 0
	s_add_u32 s33, s28, 0x100
	v_mov_b32_e32 v0, 0
	s_addc_u32 s50, s29, 0
	s_mov_b32 s28, 0
	v_mov_b32_e32 v1, v0
	v_mov_b32_e32 v2, v0
	v_mov_b32_e32 v3, v0
	v_mov_b32_e32 v4, v0
	v_mov_b32_e32 v5, v0
	v_mov_b32_e32 v6, v0
	v_mov_b32_e32 v7, v0
	v_mov_b32_e32 v16, v0
	v_mov_b32_e32 v17, v0
	v_mov_b32_e32 v18, v0
	v_mov_b32_e32 v19, v0
	v_mov_b32_e32 v20, v0
	v_mov_b32_e32 v21, v0
	v_mov_b32_e32 v22, v0
	v_mov_b32_e32 v23, v0
	v_mov_b32_e32 v32, v0
	v_mov_b32_e32 v33, v0
	v_mov_b32_e32 v34, v0
	v_mov_b32_e32 v35, v0
	v_mov_b32_e32 v36, v0
	v_mov_b32_e32 v37, v0
	v_mov_b32_e32 v38, v0
	v_mov_b32_e32 v39, v0
	v_mov_b32_e32 v48, v0
	v_mov_b32_e32 v49, v0
	v_mov_b32_e32 v50, v0
	v_mov_b32_e32 v51, v0
	v_mov_b32_e32 v52, v0
	v_mov_b32_e32 v53, v0
	v_mov_b32_e32 v54, v0
	v_mov_b32_e32 v55, v0
	v_mov_b32_e32 v8, v0
	v_mov_b32_e32 v9, v0
	v_mov_b32_e32 v10, v0
	v_mov_b32_e32 v11, v0
	v_mov_b32_e32 v12, v0
	v_mov_b32_e32 v13, v0
	v_mov_b32_e32 v14, v0
	v_mov_b32_e32 v15, v0
	v_mov_b32_e32 v24, v0
	v_mov_b32_e32 v25, v0
	v_mov_b32_e32 v26, v0
	v_mov_b32_e32 v27, v0
	v_mov_b32_e32 v28, v0
	v_mov_b32_e32 v29, v0
	v_mov_b32_e32 v30, v0
	v_mov_b32_e32 v31, v0
	v_mov_b32_e32 v40, v0
	v_mov_b32_e32 v41, v0
	v_mov_b32_e32 v42, v0
	v_mov_b32_e32 v43, v0
	v_mov_b32_e32 v44, v0
	v_mov_b32_e32 v45, v0
	v_mov_b32_e32 v46, v0
	v_mov_b32_e32 v47, v0
	v_mov_b32_e32 v56, v0
	v_mov_b32_e32 v57, v0
	v_mov_b32_e32 v58, v0
	v_mov_b32_e32 v59, v0
	v_mov_b32_e32 v60, v0
	v_mov_b32_e32 v61, v0
	v_mov_b32_e32 v62, v0
	v_mov_b32_e32 v63, v0
	v_mov_b32_e32 v64, v0
	v_mov_b32_e32 v65, v0
	v_mov_b32_e32 v66, v0
	v_mov_b32_e32 v67, v0
	v_mov_b32_e32 v68, v0
	v_mov_b32_e32 v69, v0
	v_mov_b32_e32 v70, v0
	v_mov_b32_e32 v71, v0
	v_mov_b32_e32 v80, v0
	v_mov_b32_e32 v81, v0
	v_mov_b32_e32 v82, v0
	v_mov_b32_e32 v83, v0
	v_mov_b32_e32 v84, v0
	v_mov_b32_e32 v85, v0
	v_mov_b32_e32 v86, v0
	v_mov_b32_e32 v87, v0
	v_mov_b32_e32 v96, v0
	v_mov_b32_e32 v97, v0
	v_mov_b32_e32 v98, v0
	v_mov_b32_e32 v99, v0
	v_mov_b32_e32 v100, v0
	v_mov_b32_e32 v101, v0
	v_mov_b32_e32 v102, v0
	v_mov_b32_e32 v103, v0
	v_mov_b32_e32 v112, v0
	v_mov_b32_e32 v113, v0
	v_mov_b32_e32 v114, v0
	v_mov_b32_e32 v115, v0
	v_mov_b32_e32 v116, v0
	v_mov_b32_e32 v117, v0
	v_mov_b32_e32 v118, v0
	v_mov_b32_e32 v119, v0
	v_mov_b32_e32 v72, v0
	v_mov_b32_e32 v73, v0
	v_mov_b32_e32 v74, v0
	v_mov_b32_e32 v75, v0
	v_mov_b32_e32 v76, v0
	v_mov_b32_e32 v77, v0
	v_mov_b32_e32 v78, v0
	v_mov_b32_e32 v79, v0
	v_mov_b32_e32 v88, v0
	v_mov_b32_e32 v89, v0
	v_mov_b32_e32 v90, v0
	v_mov_b32_e32 v91, v0
	v_mov_b32_e32 v92, v0
	v_mov_b32_e32 v93, v0
	v_mov_b32_e32 v94, v0
	v_mov_b32_e32 v95, v0
	v_mov_b32_e32 v104, v0
	v_mov_b32_e32 v105, v0
	v_mov_b32_e32 v106, v0
	v_mov_b32_e32 v107, v0
	v_mov_b32_e32 v108, v0
	v_mov_b32_e32 v109, v0
	v_mov_b32_e32 v110, v0
	v_mov_b32_e32 v111, v0
	v_mov_b32_e32 v124, v0
	v_mov_b32_e32 v125, v0
	v_mov_b32_e32 v126, v0
	v_mov_b32_e32 v127, v0
	v_mov_b32_e32 v120, v0
	v_mov_b32_e32 v121, v0
	v_mov_b32_e32 v122, v0
	v_mov_b32_e32 v123, v0
.LBB0_353:
	s_add_i32 s51, s28, 2
	s_add_u32 s52, s0, 0x80
	s_addc_u32 s29, s1, 0
	s_add_i32 s54, 0, 0x10000
	s_cmp_eq_u32 s45, s28
	s_cselect_b32 s29, s9, s29
	s_cselect_b32 s28, s8, s52
	s_cselect_b32 s53, s27, s50
	s_cselect_b32 s52, s26, s33
	s_add_i32 s55, 0, 0x14000
	v_add_u32_e32 v140, s54, v186
	v_add_u32_e32 v166, s55, v186
	ds_read_b128 v[128:131], v140
	ds_read_b128 v[132:135], v140 offset:1024
	ds_read_b128 v[136:139], v140 offset:2048
	ds_read_b128 v[140:143], v140 offset:3072
	ds_read_b128 v[144:147], v166
	ds_read_b128 v[148:151], v166 offset:1024
	ds_read_b128 v[152:155], v166 offset:2048
	ds_read_b128 v[166:169], v166 offset:3072
	v_lshl_add_u64 v[182:183], s[0:1], 0, v[162:163]
	s_add_i32 m0, s35, 0xc000
	ds_read_b128 v[170:173], v187
	ds_read_b128 v[174:177], v187 offset:1024
	ds_read_b128 v[178:181], v187 offset:2048
	ds_read_b128 v[188:191], v187 offset:3072
	ds_read_b128 v[204:207], v187 offset:4096
	ds_read_b128 v[208:211], v187 offset:5120
	ds_read_b128 v[212:215], v187 offset:6144
	ds_read_b128 v[216:219], v187 offset:7168
	global_load_lds_dwordx4 v[182:183], off
	v_lshl_add_u64 v[182:183], s[0:1], 0, v[164:165]
	s_add_i32 m0, s35, 0xe000
	s_nop 0
	global_load_lds_dwordx4 v[182:183], off
	s_waitcnt vmcnt(8)
	s_waitcnt lgkmcnt(0)
	s_barrier
	s_setprio 1
	s_waitcnt lgkmcnt(0)
	v_mfma_f32_16x16x32_bf16 v[120:123], v[128:131], v[170:173], v[120:123]
	v_mfma_f32_16x16x32_bf16 v[124:127], v[136:139], v[170:173], v[124:127]
	v_mfma_f32_16x16x32_bf16 v[108:111], v[128:131], v[178:181], v[108:111]
	v_mfma_f32_16x16x32_bf16 v[104:107], v[136:139], v[178:181], v[104:107]
	v_mfma_f32_16x16x32_bf16 v[92:95], v[128:131], v[204:207], v[92:95]
	v_mfma_f32_16x16x32_bf16 v[88:91], v[136:139], v[204:207], v[88:91]
	v_mfma_f32_16x16x32_bf16 v[76:79], v[128:131], v[212:215], v[76:79]
	v_mfma_f32_16x16x32_bf16 v[72:75], v[136:139], v[212:215], v[72:75]
	v_mfma_f32_16x16x32_bf16 v[120:123], v[132:135], v[174:177], v[120:123]
	v_mfma_f32_16x16x32_bf16 v[124:127], v[140:143], v[174:177], v[124:127]
	v_mfma_f32_16x16x32_bf16 v[108:111], v[132:135], v[188:191], v[108:111]
	v_mfma_f32_16x16x32_bf16 v[104:107], v[140:143], v[188:191], v[104:107]
	v_mfma_f32_16x16x32_bf16 v[92:95], v[132:135], v[208:211], v[92:95]
	v_mfma_f32_16x16x32_bf16 v[88:91], v[140:143], v[208:211], v[88:91]
	v_mfma_f32_16x16x32_bf16 v[76:79], v[132:135], v[216:219], v[76:79]
	v_mfma_f32_16x16x32_bf16 v[72:75], v[140:143], v[216:219], v[72:75]
	s_setprio 0
	s_setprio 1
	v_mfma_f32_16x16x32_bf16 v[116:119], v[144:147], v[170:173], v[116:119]
	v_mfma_f32_16x16x32_bf16 v[112:115], v[152:155], v[170:173], v[112:115]
	v_mfma_f32_16x16x32_bf16 v[100:103], v[144:147], v[178:181], v[100:103]
	v_mfma_f32_16x16x32_bf16 v[96:99], v[152:155], v[178:181], v[96:99]
	v_mfma_f32_16x16x32_bf16 v[84:87], v[144:147], v[204:207], v[84:87]
	v_mfma_f32_16x16x32_bf16 v[80:83], v[152:155], v[204:207], v[80:83]
	v_mfma_f32_16x16x32_bf16 v[68:71], v[144:147], v[212:215], v[68:71]
	v_mfma_f32_16x16x32_bf16 v[64:67], v[152:155], v[212:215], v[64:67]
	v_mfma_f32_16x16x32_bf16 v[116:119], v[148:151], v[174:177], v[116:119]
	v_mfma_f32_16x16x32_bf16 v[112:115], v[166:169], v[174:177], v[112:115]
	v_mfma_f32_16x16x32_bf16 v[100:103], v[148:151], v[188:191], v[100:103]
	v_mfma_f32_16x16x32_bf16 v[96:99], v[166:169], v[188:191], v[96:99]
	v_mfma_f32_16x16x32_bf16 v[84:87], v[148:151], v[208:211], v[84:87]
	v_mfma_f32_16x16x32_bf16 v[80:83], v[166:169], v[208:211], v[80:83]
	v_mfma_f32_16x16x32_bf16 v[68:71], v[148:151], v[216:219], v[68:71]
	v_mfma_f32_16x16x32_bf16 v[64:67], v[166:169], v[216:219], v[64:67]
	s_setprio 0
	s_barrier
; #define PG8_STAGE(bufoff, gbase, voff) do { _Pragma("unroll") for (int _i = 0; _i < 2; ++_i) \
;         __builtin_amdgcn_global_load_lds((const unsigned*)((const char*)(gbase) + (voff)[_i]), (PG8_LAS unsigned*)(lds + (bufoff) + ldsw + _i * 8192), 16, 0, 0); } while (0)
; #define PG8_LDA(dst, b, h) do { _Pragma("unroll") for (int m = 0; m < 4; ++m) _Pragma("unroll") for (int k = 0; k < 2; ++k) dst[m][k] = *(const PG8_LAS bf16x8*)(lds + PG8_SA(b, h) + aoff + m * 2048 + k * 1024); } while (0)
; #define PG8_LDB(dst, b, h) do { _Pragma("unroll") for (int n = 0; n < 2; ++n) _Pragma("unroll") for (int k = 0; k < 2; ++k) dst[n][k] = *(const PG8_LAS bf16x8*)(lds + PG8_SB(b, h) + boff + n * 2048 + k * 1024); } while (0)
; #define PG8_MMA(ai, bj, At, Bt) do { __builtin_amdgcn_s_setprio(1); _Pragma("unroll") for (int m = 0; m < 4; ++m) _Pragma("unroll") for (int n = 0; n < 2; ++n) _Pragma("unroll") for (int k = 0; k < 2; ++k) \
;         acc[ai][bj][m][n] = __builtin_amdgcn_mfma_f32_16x16x32_bf16(Bt[n][k], At[m][k], acc[ai][bj][m][n], 0, 0, 0); __builtin_amdgcn_s_setprio(0); } while (0)
; #define PG8_WAIT_V(n) asm volatile("s_waitcnt vmcnt(" #n ")" ::: "memory")
; #define PG8_WAIT_L(n) asm volatile("s_waitcnt lgkmcnt(" #n ")" ::: "memory")
; #define PG8_BAR __builtin_amdgcn_s_barrier()
; template <class Epi, class Sched, bool ALIGN_EPI = false, bool SP2 = false>
; __device__ __forceinline__ void gemm_phase(PG8_LAS unsigned char* lds, const Gemm g, const Sched& S, const Epi& E) {
;     ...
;             PG8_WAIT_L(0); PG8_BAR; PG8_MMA(0, 0, At, B0); PG8_MMA(0, 1, At, B1);
;             if constexpr (Epi::SPLIT) { if (defer) {
;                 E.second(acc, prev, rv1, wr, wc, fr, fq);
;                 _Pragma("unroll") for (int b = 0; b < 2; ++b) _Pragma("unroll") for (int m = 0; m < 4; ++m) _Pragma("unroll") for (int n = 0; n < 2; ++n) acc[1][b][m][n] = (f32x4){0.f, 0.f, 0.f, 0.f}; } }
;             PG8_BAR; PG8_SCHED;
;             PG8_LDA(At, 0, 1); PG8_STAGE(PG8_SB(0, 0), b2, voffB); PG8_STAGE(PG8_SB(0, 1), b2 + hstep, voffB); PG8_STAGE(PG8_SA(0, 0), a2, voffA);
;             if (plast) PG8_WAIT_V(10); else PG8_WAIT_SEL(defer, 16, 24);
;             PG8_WAIT_L(0); PG8_BAR; PG8_MMA(1, 0, At, B0); PG8_MMA(1, 1, At, B1); PG8_BAR; PG8_SCHED;
;             PG8_LDB(B0, 1, 0); PG8_LDB(B1, 1, 1); PG8_SCHED; PG8_LDA(At, 1, 0); PG8_STAGE(PG8_SA(0, 1), a2 + hstepA, voffA);
	s_add_i32 s54, s54, s34
	v_lshl_add_u64 v[182:183], s[52:53], 0, v[192:193]
	s_mov_b32 m0, s54
	ds_read_b128 v[170:173], v187 offset:16384
	ds_read_b128 v[174:177], v187 offset:17408
	ds_read_b128 v[178:181], v187 offset:18432
	ds_read_b128 v[188:191], v187 offset:19456
	ds_read_b128 v[204:207], v187 offset:20480
	ds_read_b128 v[208:211], v187 offset:21504
	ds_read_b128 v[212:215], v187 offset:22528
	ds_read_b128 v[216:219], v187 offset:23552
	global_load_lds_dwordx4 v[182:183], off
	s_add_i32 m0, s54, 0x2000
	v_lshl_add_u64 v[194:195], s[52:53], 0, v[156:157]
	s_add_u32 s52, s52, s16
	s_addc_u32 s53, s53, s17
	s_add_i32 s54, s55, s34
	global_load_lds_dwordx4 v[194:195], off
	v_lshl_add_u64 v[200:201], s[52:53], 0, v[192:193]
	s_mov_b32 m0, s54
	v_lshl_add_u64 v[202:203], s[52:53], 0, v[156:157]
	global_load_lds_dwordx4 v[200:201], off
	s_add_i32 m0, s54, 0x2000
	v_lshl_add_u64 v[220:221], s[28:29], 0, v[160:161]
	global_load_lds_dwordx4 v[202:203], off
	s_mov_b32 m0, s35
	v_lshl_add_u64 v[222:223], s[28:29], 0, v[158:159]
	global_load_lds_dwordx4 v[220:221], off
	s_mov_b32 m0, s36
	s_nop 0
	global_load_lds_dwordx4 v[222:223], off
	s_waitcnt vmcnt(8)
	s_waitcnt lgkmcnt(0)
	s_barrier
	s_setprio 1
	s_waitcnt lgkmcnt(0)
	v_mfma_f32_16x16x32_bf16 v[60:63], v[128:131], v[170:173], v[60:63]
	v_mfma_f32_16x16x32_bf16 v[56:59], v[136:139], v[170:173], v[56:59]
	v_mfma_f32_16x16x32_bf16 v[44:47], v[128:131], v[178:181], v[44:47]
	v_mfma_f32_16x16x32_bf16 v[40:43], v[136:139], v[178:181], v[40:43]
	v_mfma_f32_16x16x32_bf16 v[28:31], v[128:131], v[204:207], v[28:31]
	v_mfma_f32_16x16x32_bf16 v[24:27], v[136:139], v[204:207], v[24:27]
	v_mfma_f32_16x16x32_bf16 v[12:15], v[128:131], v[212:215], v[12:15]
	v_mfma_f32_16x16x32_bf16 v[8:11], v[136:139], v[212:215], v[8:11]
	v_mfma_f32_16x16x32_bf16 v[60:63], v[132:135], v[174:177], v[60:63]
	v_mfma_f32_16x16x32_bf16 v[56:59], v[140:143], v[174:177], v[56:59]
	v_mfma_f32_16x16x32_bf16 v[44:47], v[132:135], v[188:191], v[44:47]
	v_mfma_f32_16x16x32_bf16 v[40:43], v[140:143], v[188:191], v[40:43]
	v_mfma_f32_16x16x32_bf16 v[28:31], v[132:135], v[208:211], v[28:31]
	v_mfma_f32_16x16x32_bf16 v[24:27], v[140:143], v[208:211], v[24:27]
	v_mfma_f32_16x16x32_bf16 v[12:15], v[132:135], v[216:219], v[12:15]
	v_mfma_f32_16x16x32_bf16 v[8:11], v[140:143], v[216:219], v[8:11]
	s_setprio 0
	s_setprio 1
	v_mfma_f32_16x16x32_bf16 v[52:55], v[144:147], v[170:173], v[52:55]
	v_mfma_f32_16x16x32_bf16 v[48:51], v[152:155], v[170:173], v[48:51]
	v_mfma_f32_16x16x32_bf16 v[36:39], v[144:147], v[178:181], v[36:39]
	v_mfma_f32_16x16x32_bf16 v[32:35], v[152:155], v[178:181], v[32:35]
	v_mfma_f32_16x16x32_bf16 v[20:23], v[144:147], v[204:207], v[20:23]
	v_mfma_f32_16x16x32_bf16 v[16:19], v[152:155], v[204:207], v[16:19]
	v_mfma_f32_16x16x32_bf16 v[4:7], v[144:147], v[212:215], v[4:7]
	v_mfma_f32_16x16x32_bf16 v[0:3], v[152:155], v[212:215], v[0:3]
	v_mfma_f32_16x16x32_bf16 v[52:55], v[148:151], v[174:177], v[52:55]
	v_mfma_f32_16x16x32_bf16 v[48:51], v[166:169], v[174:177], v[48:51]
	v_mfma_f32_16x16x32_bf16 v[36:39], v[148:151], v[188:191], v[36:39]
	v_mfma_f32_16x16x32_bf16 v[32:35], v[166:169], v[188:191], v[32:35]
	v_mfma_f32_16x16x32_bf16 v[20:23], v[148:151], v[208:211], v[20:23]
	v_mfma_f32_16x16x32_bf16 v[16:19], v[166:169], v[208:211], v[16:19]
	v_mfma_f32_16x16x32_bf16 v[4:7], v[148:151], v[216:219], v[4:7]
	v_mfma_f32_16x16x32_bf16 v[0:3], v[166:169], v[216:219], v[0:3]
	s_setprio 0
	s_barrier
	s_add_i32 s52, 0, 0x18000
	s_add_i32 s53, 0, 0x1c000
	v_add_u32_e32 v140, s52, v186
	v_add_u32_e32 v166, s53, v186
	ds_read_b128 v[128:131], v140
	ds_read_b128 v[132:135], v140 offset:1024
	ds_read_b128 v[136:139], v140 offset:2048
	ds_read_b128 v[140:143], v140 offset:3072
	ds_read_b128 v[144:147], v166
	ds_read_b128 v[148:151], v166 offset:1024
	ds_read_b128 v[152:155], v166 offset:2048
	ds_read_b128 v[166:169], v166 offset:3072
	s_add_u32 s28, s28, s12
	s_addc_u32 s29, s29, s13
	s_mov_b32 m0, s37
	v_lshl_add_u64 v[224:225], s[28:29], 0, v[160:161]
	ds_read_b128 v[170:173], v187 offset:32768
	ds_read_b128 v[174:177], v187 offset:33792
	ds_read_b128 v[178:181], v187 offset:34816
	ds_read_b128 v[188:191], v187 offset:35840
	ds_read_b128 v[204:207], v187 offset:36864
	ds_read_b128 v[208:211], v187 offset:37888
	ds_read_b128 v[212:215], v187 offset:38912
	ds_read_b128 v[216:219], v187 offset:39936
	global_load_lds_dwordx4 v[224:225], off
	v_lshl_add_u64 v[224:225], s[28:29], 0, v[158:159]
	s_mov_b32 m0, s38
	s_nop 0
	global_load_lds_dwordx4 v[224:225], off
	s_waitcnt vmcnt(8)
	s_waitcnt lgkmcnt(0)
	s_barrier
; #define PG8_STAGE(bufoff, gbase, voff) do { _Pragma("unroll") for (int _i = 0; _i < 2; ++_i) \
;         __builtin_amdgcn_global_load_lds((const unsigned*)((const char*)(gbase) + (voff)[_i]), (PG8_LAS unsigned*)(lds + (bufoff) + ldsw + _i * 8192), 16, 0, 0); } while (0)
; #define PG8_LDA(dst, b, h) do { _Pragma("unroll") for (int m = 0; m < 4; ++m) _Pragma("unroll") for (int k = 0; k < 2; ++k) dst[m][k] = *(const PG8_LAS bf16x8*)(lds + PG8_SA(b, h) + aoff + m * 2048 + k * 1024); } while (0)
; #define PG8_LDB(dst, b, h) do { _Pragma("unroll") for (int n = 0; n < 2; ++n) _Pragma("unroll") for (int k = 0; k < 2; ++k) dst[n][k] = *(const PG8_LAS bf16x8*)(lds + PG8_SB(b, h) + boff + n * 2048 + k * 1024); } while (0)
; #define PG8_MMA(ai, bj, At, Bt) do { __builtin_amdgcn_s_setprio(1); _Pragma("unroll") for (int m = 0; m < 4; ++m) _Pragma("unroll") for (int n = 0; n < 2; ++n) _Pragma("unroll") for (int k = 0; k < 2; ++k) \
;         acc[ai][bj][m][n] = __builtin_amdgcn_mfma_f32_16x16x32_bf16(Bt[n][k], At[m][k], acc[ai][bj][m][n], 0, 0, 0); __builtin_amdgcn_s_setprio(0); } while (0)
; #define PG8_WAIT_V(n) asm volatile("s_waitcnt vmcnt(" #n ")" ::: "memory")
; #define PG8_WAIT_SEL(d, w4, w8) do { if constexpr (Epi::SPLIT) { if (d) { if constexpr (Epi::NSH == 4) PG8_WAIT_V(w4); else PG8_WAIT_V(w8); } else PG8_WAIT_V(8); } else PG8_WAIT_V(8); } while (0)
; #define PG8_WAIT_L(n) asm volatile("s_waitcnt lgkmcnt(" #n ")" ::: "memory")
; #define PG8_BAR __builtin_amdgcn_s_barrier()
; #define PG8_SCHED __builtin_amdgcn_sched_barrier(0)
; template <class Epi, class Sched, bool ALIGN_EPI = false, bool SP2 = false>
; __device__ __forceinline__ void gemm_phase(PG8_LAS unsigned char* lds, const Gemm g, const Sched& S, const Epi& E) {
;     ...
;             PG8_LDB(B0, 1, 0); PG8_LDB(B1, 1, 1); PG8_SCHED; PG8_LDA(At, 1, 0); PG8_STAGE(PG8_SA(0, 1), a2 + hstepA, voffA);
;             PG8_WAIT_SEL(defer, 12, 16); PG8_WAIT_L(0); PG8_BAR; PG8_MMA(0, 0, At, B0); PG8_MMA(0, 1, At, B1); PG8_BAR; PG8_SCHED;
;             PG8_LDA(At, 1, 1); PG8_STAGE(PG8_SB(1, 0), b3, voffB); PG8_STAGE(PG8_SB(1, 1), b3 + hstep, voffB); PG8_STAGE(PG8_SA(1, 0), a3, voffA);
;             PG8_WAIT_V(8); PG8_WAIT_L(0); PG8_BAR; PG8_MMA(1, 0, At, B0); PG8_MMA(1, 1, At, B1); PG8_BAR; PG8_SCHED;
	s_setprio 1
	s_waitcnt lgkmcnt(0)
	v_mfma_f32_16x16x32_bf16 v[120:123], v[128:131], v[170:173], v[120:123]
	v_mfma_f32_16x16x32_bf16 v[124:127], v[136:139], v[170:173], v[124:127]
	v_mfma_f32_16x16x32_bf16 v[108:111], v[128:131], v[178:181], v[108:111]
	v_mfma_f32_16x16x32_bf16 v[104:107], v[136:139], v[178:181], v[104:107]
	v_mfma_f32_16x16x32_bf16 v[92:95], v[128:131], v[204:207], v[92:95]
	v_mfma_f32_16x16x32_bf16 v[88:91], v[136:139], v[204:207], v[88:91]
	v_mfma_f32_16x16x32_bf16 v[76:79], v[128:131], v[212:215], v[76:79]
	v_mfma_f32_16x16x32_bf16 v[72:75], v[136:139], v[212:215], v[72:75]
	v_mfma_f32_16x16x32_bf16 v[120:123], v[132:135], v[174:177], v[120:123]
	v_mfma_f32_16x16x32_bf16 v[124:127], v[140:143], v[174:177], v[124:127]
	v_mfma_f32_16x16x32_bf16 v[108:111], v[132:135], v[188:191], v[108:111]
	v_mfma_f32_16x16x32_bf16 v[104:107], v[140:143], v[188:191], v[104:107]
	v_mfma_f32_16x16x32_bf16 v[92:95], v[132:135], v[208:211], v[92:95]
	v_mfma_f32_16x16x32_bf16 v[88:91], v[140:143], v[208:211], v[88:91]
	v_mfma_f32_16x16x32_bf16 v[76:79], v[132:135], v[216:219], v[76:79]
	v_mfma_f32_16x16x32_bf16 v[72:75], v[140:143], v[216:219], v[72:75]
	s_setprio 0
	s_setprio 1
	v_mfma_f32_16x16x32_bf16 v[116:119], v[144:147], v[170:173], v[116:119]
	v_mfma_f32_16x16x32_bf16 v[112:115], v[152:155], v[170:173], v[112:115]
	v_mfma_f32_16x16x32_bf16 v[100:103], v[144:147], v[178:181], v[100:103]
	v_mfma_f32_16x16x32_bf16 v[96:99], v[152:155], v[178:181], v[96:99]
	v_mfma_f32_16x16x32_bf16 v[84:87], v[144:147], v[204:207], v[84:87]
	v_mfma_f32_16x16x32_bf16 v[80:83], v[152:155], v[204:207], v[80:83]
	v_mfma_f32_16x16x32_bf16 v[68:71], v[144:147], v[212:215], v[68:71]
	v_mfma_f32_16x16x32_bf16 v[64:67], v[152:155], v[212:215], v[64:67]
	v_mfma_f32_16x16x32_bf16 v[116:119], v[148:151], v[174:177], v[116:119]
	v_mfma_f32_16x16x32_bf16 v[112:115], v[166:169], v[174:177], v[112:115]
	v_mfma_f32_16x16x32_bf16 v[100:103], v[148:151], v[188:191], v[100:103]
	v_mfma_f32_16x16x32_bf16 v[96:99], v[166:169], v[188:191], v[96:99]
	v_mfma_f32_16x16x32_bf16 v[84:87], v[148:151], v[208:211], v[84:87]
	v_mfma_f32_16x16x32_bf16 v[80:83], v[166:169], v[208:211], v[80:83]
	v_mfma_f32_16x16x32_bf16 v[68:71], v[148:151], v[216:219], v[68:71]
	v_mfma_f32_16x16x32_bf16 v[64:67], v[166:169], v[216:219], v[64:67]
	s_setprio 0
	s_barrier
	s_add_i32 s28, s52, s34
	v_lshl_add_u64 v[182:183], v[182:183], 0, s[90:91]
	s_mov_b32 m0, s28
	ds_read_b128 v[170:173], v187 offset:49152
	ds_read_b128 v[174:177], v187 offset:50176
	ds_read_b128 v[178:181], v187 offset:51200
	ds_read_b128 v[188:191], v187 offset:52224
	ds_read_b128 v[204:207], v187 offset:53248
	ds_read_b128 v[208:211], v187 offset:54272
	ds_read_b128 v[212:215], v187 offset:55296
	ds_read_b128 v[216:219], v187 offset:56320
	global_load_lds_dwordx4 v[182:183], off
	v_lshl_add_u64 v[182:183], v[194:195], 0, s[90:91]
	s_add_i32 m0, s28, 0x2000
	s_add_i32 s28, s53, s34
	global_load_lds_dwordx4 v[182:183], off
	v_lshl_add_u64 v[182:183], v[200:201], 0, s[90:91]
	s_mov_b32 m0, s28
	s_nop 0
	global_load_lds_dwordx4 v[182:183], off
	v_lshl_add_u64 v[182:183], v[202:203], 0, s[90:91]
	s_add_i32 m0, s28, 0x2000
	s_nop 0
	global_load_lds_dwordx4 v[182:183], off
	v_lshl_add_u64 v[182:183], v[220:221], 0, s[90:91]
	s_mov_b32 m0, s43
	s_nop 0
	global_load_lds_dwordx4 v[182:183], off
	v_lshl_add_u64 v[182:183], v[222:223], 0, s[90:91]
	s_mov_b32 m0, s44
	s_nop 0
	global_load_lds_dwordx4 v[182:183], off
	s_waitcnt vmcnt(8)
	s_waitcnt lgkmcnt(0)
	s_barrier
	s_setprio 1
	s_waitcnt lgkmcnt(0)
	v_mfma_f32_16x16x32_bf16 v[60:63], v[128:131], v[170:173], v[60:63]
	v_mfma_f32_16x16x32_bf16 v[56:59], v[136:139], v[170:173], v[56:59]
	v_mfma_f32_16x16x32_bf16 v[44:47], v[128:131], v[178:181], v[44:47]
	v_mfma_f32_16x16x32_bf16 v[40:43], v[136:139], v[178:181], v[40:43]
	v_mfma_f32_16x16x32_bf16 v[28:31], v[128:131], v[204:207], v[28:31]
	v_mfma_f32_16x16x32_bf16 v[24:27], v[136:139], v[204:207], v[24:27]
	v_mfma_f32_16x16x32_bf16 v[12:15], v[128:131], v[212:215], v[12:15]
	v_mfma_f32_16x16x32_bf16 v[8:11], v[136:139], v[212:215], v[8:11]
	v_mfma_f32_16x16x32_bf16 v[60:63], v[132:135], v[174:177], v[60:63]
	v_mfma_f32_16x16x32_bf16 v[56:59], v[140:143], v[174:177], v[56:59]
	v_mfma_f32_16x16x32_bf16 v[44:47], v[132:135], v[188:191], v[44:47]
	v_mfma_f32_16x16x32_bf16 v[40:43], v[140:143], v[188:191], v[40:43]
	v_mfma_f32_16x16x32_bf16 v[28:31], v[132:135], v[208:211], v[28:31]
	v_mfma_f32_16x16x32_bf16 v[24:27], v[140:143], v[208:211], v[24:27]
	v_mfma_f32_16x16x32_bf16 v[12:15], v[132:135], v[216:219], v[12:15]
	v_mfma_f32_16x16x32_bf16 v[8:11], v[140:143], v[216:219], v[8:11]
	s_setprio 0
	s_setprio 1
	v_mfma_f32_16x16x32_bf16 v[52:55], v[144:147], v[170:173], v[52:55]
	v_mfma_f32_16x16x32_bf16 v[48:51], v[152:155], v[170:173], v[48:51]
	v_mfma_f32_16x16x32_bf16 v[36:39], v[144:147], v[178:181], v[36:39]
	v_mfma_f32_16x16x32_bf16 v[32:35], v[152:155], v[178:181], v[32:35]
	v_mfma_f32_16x16x32_bf16 v[20:23], v[144:147], v[204:207], v[20:23]
	v_mfma_f32_16x16x32_bf16 v[16:19], v[152:155], v[204:207], v[16:19]
	v_mfma_f32_16x16x32_bf16 v[4:7], v[144:147], v[212:215], v[4:7]
	v_mfma_f32_16x16x32_bf16 v[0:3], v[152:155], v[212:215], v[0:3]
	v_mfma_f32_16x16x32_bf16 v[52:55], v[148:151], v[174:177], v[52:55]
	v_mfma_f32_16x16x32_bf16 v[48:51], v[166:169], v[174:177], v[48:51]
	v_mfma_f32_16x16x32_bf16 v[36:39], v[148:151], v[188:191], v[36:39]
	v_mfma_f32_16x16x32_bf16 v[32:35], v[166:169], v[188:191], v[32:35]
	v_mfma_f32_16x16x32_bf16 v[20:23], v[148:151], v[208:211], v[20:23]
	v_mfma_f32_16x16x32_bf16 v[16:19], v[166:169], v[208:211], v[16:19]
	v_mfma_f32_16x16x32_bf16 v[4:7], v[148:151], v[216:219], v[4:7]
	v_mfma_f32_16x16x32_bf16 v[0:3], v[166:169], v[216:219], v[0:3]
	s_setprio 0
	s_barrier
	s_add_u32 s0, s0, 0x100
	s_addc_u32 s1, s1, 0
	s_add_u32 s33, s33, 0x100
	s_addc_u32 s50, s50, 0
	s_cmp_ge_i32 s51, s40
	s_mov_b32 s28, s51
	s_cbranch_scc0 .LBB0_353

; #define PG8_BAR __builtin_amdgcn_s_barrier()
; template <class Epi, class Sched, bool ALIGN_EPI = false, bool SP2 = false>
; __device__ __forceinline__ void gemm_phase(PG8_LAS unsigned char* lds, const Gemm g, const Sched& S, const Epi& E) {
;     ...
;         if constexpr (ALIGN_EPI) { if (wr == 0) PG8_BAR; }
;         if constexpr (Epi::SPLIT) {
;             if (has_next) { E.first(acc, cur, rv1, wr, wc, fr, fq); prev = cur; }
;             else E(acc, cur, wr, wc, fr, fq, lds + STAGE_BYTES);
;         } else if constexpr (!Epi::AFTER_DRAIN) { E(acc, cur, wr, wc, fr, fq, lds + STAGE_BYTES); S.done(cur); }
;         if (!has_next) break;
; #pragma unroll
;         for (int a = 0; a < (Epi::SPLIT ? 1 : 2); ++a)
; #pragma unroll
;             for (int b = 0; b < 2; ++b)
; #pragma unroll
;                 for (int m = 0; m < 4; ++m)
; #pragma unroll
;                     for (int n = 0; n < 2; ++n) acc[a][b][m][n] = (f32x4){0.f, 0.f, 0.f, 0.f};
;         cur = nxt; cA = nA; cB = nB; ++ui;
;         if constexpr (ALIGN_EPI) { if (wr == 1) PG8_BAR; }
;     __device__ __forceinline__ void operator()(const f32x4 (&acc)[2][2][4][2], const pg8::Unit& u, int wr, int wc, int fr_, int fq_, LAS const unsigned char* xl) const {
;     ...
;                     ss = xrow16_sum(ss);
;                     if (fq == 0) part_out[(size_t)row * 16 + u.pn * 4 + wc] = ss;
.LBB0_372:
	s_or_b64 exec, exec, s[28:29]
	s_and_b64 vcc, exec, s[6:7]
	s_mov_b64 s[0:1], -1
	s_cbranch_vccnz .LBB0_340
	s_andn2_b64 vcc, exec, s[20:21]
	s_cbranch_vccnz .LBB0_339
	s_barrier
	s_branch .LBB0_339

; #define PG8_LAS __attribute__((address_space(3)))
; template <class Epi, class Sched, bool ALIGN_EPI = false, bool SP2 = false>
; __device__ __forceinline__ void gemm_phase(PG8_LAS unsigned char* lds, const Gemm g, const Sched& S, const Epi& E) {
;     ...
;     for (;;) {
;         const bool has_next = S.next(ui + 1, nxt);
;         const char* nA = has_next ? (const char*)g.A + (size_t)nxt.pm * tstepA : cA; const char* nB = has_next ? (const char*)g.Bt + (size_t)nxt.pn * tstep : cB;
;         for (int t = 0; t < nt; t += 2) {
;             const bool last = (t == nt - 2);
;             if constexpr (Epi::RVLDS) { if (last) {
;                 const char* pg = (const char*)E.part_in + (size_t)cur.pm * 16384 + (size_t)tid * 16;
;                 __builtin_amdgcn_global_load_lds((const unsigned*)pg, (PG8_LAS unsigned*)(lds + STAGE_BYTES + ldsw), 16, 0, 0);
;                 __builtin_amdgcn_global_load_lds((const unsigned*)(pg + 8192), (PG8_LAS unsigned*)(lds + STAGE_BYTES + 8192 + ldsw), 16, 0, 0); } }
;             const bool plast = Epi::RVLDS && last;
;             const bool defer = Epi::SPLIT && (t == 0) && (ui > 0);
;             const char* a1 = cA + (size_t)(t + 1) * kstep;
;             const char* a2 = last ? nA : cA + (size_t)(t + 2) * kstep; const char* b2 = last ? nB : cB + (size_t)(t + 2) * kstep;
.LBB0_410:
	s_andn2_b64 vcc, exec, s[22:23]
	s_cbranch_vccnz .Lzt_2
	s_ashr_i32 s1, s0, 31
	s_lshl_b64 s[30:31], s[0:1], 14
	s_add_u32 s26, s26, 0x80
	s_addc_u32 s27, s27, 0
	v_lshl_add_u64 v[216:217], v[210:211], 0, s[30:31]
	s_mov_b64 s[30:31], 0x2000
	s_add_u32 s1, s28, 0x100
	v_mov_b32_e32 v0, 0
	v_lshl_add_u64 v[218:219], v[216:217], 0, s[30:31]
	s_addc_u32 s33, s29, 0
	s_mov_b32 s55, 0
	v_mov_b32_e32 v1, v0
	v_mov_b32_e32 v2, v0
	v_mov_b32_e32 v3, v0
	v_mov_b32_e32 v12, v0
	v_mov_b32_e32 v13, v0
	v_mov_b32_e32 v14, v0
	v_mov_b32_e32 v15, v0
	v_mov_b32_e32 v20, v0
	v_mov_b32_e32 v21, v0
	v_mov_b32_e32 v22, v0
	v_mov_b32_e32 v23, v0
	v_mov_b32_e32 v28, v0
	v_mov_b32_e32 v29, v0
	v_mov_b32_e32 v30, v0
	v_mov_b32_e32 v31, v0
	v_mov_b32_e32 v36, v0
	v_mov_b32_e32 v37, v0
	v_mov_b32_e32 v38, v0
	v_mov_b32_e32 v39, v0
	v_mov_b32_e32 v44, v0
	v_mov_b32_e32 v45, v0
	v_mov_b32_e32 v46, v0
	v_mov_b32_e32 v47, v0
	v_mov_b32_e32 v52, v0
	v_mov_b32_e32 v53, v0
	v_mov_b32_e32 v54, v0
	v_mov_b32_e32 v55, v0
	v_mov_b32_e32 v60, v0
	v_mov_b32_e32 v61, v0
	v_mov_b32_e32 v62, v0
	v_mov_b32_e32 v63, v0
	v_mov_b32_e32 v4, v0
	v_mov_b32_e32 v5, v0
	v_mov_b32_e32 v6, v0
	v_mov_b32_e32 v7, v0
	v_mov_b32_e32 v8, v0
	v_mov_b32_e32 v9, v0
	v_mov_b32_e32 v10, v0
	v_mov_b32_e32 v11, v0
	v_mov_b32_e32 v16, v0
	v_mov_b32_e32 v17, v0
	v_mov_b32_e32 v18, v0
	v_mov_b32_e32 v19, v0
	v_mov_b32_e32 v24, v0
	v_mov_b32_e32 v25, v0
	v_mov_b32_e32 v26, v0
	v_mov_b32_e32 v27, v0
	v_mov_b32_e32 v32, v0
	v_mov_b32_e32 v33, v0
	v_mov_b32_e32 v34, v0
	v_mov_b32_e32 v35, v0
	v_mov_b32_e32 v40, v0
	v_mov_b32_e32 v41, v0
	v_mov_b32_e32 v42, v0
	v_mov_b32_e32 v43, v0
	v_mov_b32_e32 v48, v0
	v_mov_b32_e32 v49, v0
	v_mov_b32_e32 v50, v0
	v_mov_b32_e32 v51, v0
	v_mov_b32_e32 v56, v0
	v_mov_b32_e32 v57, v0
	v_mov_b32_e32 v58, v0
	v_mov_b32_e32 v59, v0
	v_mov_b32_e32 v68, v0
	v_mov_b32_e32 v69, v0
	v_mov_b32_e32 v70, v0
	v_mov_b32_e32 v71, v0
	v_mov_b32_e32 v76, v0
	v_mov_b32_e32 v77, v0
	v_mov_b32_e32 v78, v0
	v_mov_b32_e32 v79, v0
	v_mov_b32_e32 v84, v0
	v_mov_b32_e32 v85, v0
	v_mov_b32_e32 v86, v0
	v_mov_b32_e32 v87, v0
	v_mov_b32_e32 v92, v0
	v_mov_b32_e32 v93, v0
	v_mov_b32_e32 v94, v0
	v_mov_b32_e32 v95, v0
	v_mov_b32_e32 v100, v0
	v_mov_b32_e32 v101, v0
	v_mov_b32_e32 v102, v0
	v_mov_b32_e32 v103, v0
	v_mov_b32_e32 v108, v0
	v_mov_b32_e32 v109, v0
	v_mov_b32_e32 v110, v0
	v_mov_b32_e32 v111, v0
	v_mov_b32_e32 v116, v0
	v_mov_b32_e32 v117, v0
	v_mov_b32_e32 v118, v0
	v_mov_b32_e32 v119, v0
	v_mov_b32_e32 v124, v0
	v_mov_b32_e32 v125, v0
	v_mov_b32_e32 v126, v0
	v_mov_b32_e32 v127, v0
	v_mov_b32_e32 v64, v0
	v_mov_b32_e32 v65, v0
	v_mov_b32_e32 v66, v0
	v_mov_b32_e32 v67, v0
	v_mov_b32_e32 v72, v0
	v_mov_b32_e32 v73, v0
	v_mov_b32_e32 v74, v0
	v_mov_b32_e32 v75, v0
	v_mov_b32_e32 v80, v0
	v_mov_b32_e32 v81, v0
	v_mov_b32_e32 v82, v0
	v_mov_b32_e32 v83, v0
	v_mov_b32_e32 v88, v0
	v_mov_b32_e32 v89, v0
	v_mov_b32_e32 v90, v0
	v_mov_b32_e32 v91, v0
	v_mov_b32_e32 v96, v0
	v_mov_b32_e32 v97, v0
	v_mov_b32_e32 v98, v0
	v_mov_b32_e32 v99, v0
	v_mov_b32_e32 v104, v0
	v_mov_b32_e32 v105, v0
	v_mov_b32_e32 v106, v0
	v_mov_b32_e32 v107, v0
	v_mov_b32_e32 v112, v0
	v_mov_b32_e32 v113, v0
	v_mov_b32_e32 v114, v0
	v_mov_b32_e32 v115, v0
	v_mov_b32_e32 v120, v0
	v_mov_b32_e32 v121, v0
	v_mov_b32_e32 v122, v0
	v_mov_b32_e32 v123, v0
	s_branch .LBB0_413

; #define PG8_STAGE(bufoff, gbase, voff) do { _Pragma("unroll") for (int _i = 0; _i < 2; ++_i) \
;         __builtin_amdgcn_global_load_lds((const unsigned*)((const char*)(gbase) + (voff)[_i]), (PG8_LAS unsigned*)(lds + (bufoff) + ldsw + _i * 8192), 16, 0, 0); } while (0)
; #define PG8_LDA(dst, b, h) do { _Pragma("unroll") for (int m = 0; m < 4; ++m) _Pragma("unroll") for (int k = 0; k < 2; ++k) dst[m][k] = *(const PG8_LAS bf16x8*)(lds + PG8_SA(b, h) + aoff + m * 2048 + k * 1024); } while (0)
; #define PG8_LDB(dst, b, h) do { _Pragma("unroll") for (int n = 0; n < 2; ++n) _Pragma("unroll") for (int k = 0; k < 2; ++k) dst[n][k] = *(const PG8_LAS bf16x8*)(lds + PG8_SB(b, h) + boff + n * 2048 + k * 1024); } while (0)
; #define PG8_WAIT_V(n) asm volatile("s_waitcnt vmcnt(" #n ")" ::: "memory")
; #define PG8_WAIT_SEL(d, w4, w8) do { if constexpr (Epi::SPLIT) { if (d) { if constexpr (Epi::NSH == 4) PG8_WAIT_V(w4); else PG8_WAIT_V(w8); } else PG8_WAIT_V(8); } else PG8_WAIT_V(8); } while (0)
; #define PG8_SCHED __builtin_amdgcn_sched_barrier(0)
; template <class Epi, class Sched, bool ALIGN_EPI = false, bool SP2 = false>
; __device__ __forceinline__ void gemm_phase(PG8_LAS unsigned char* lds, const Gemm g, const Sched& S, const Epi& E) {
;     ...
;             const char* a1 = cA + (size_t)(t + 1) * kstep;
;             const char* a2 = last ? nA : cA + (size_t)(t + 2) * kstep; const char* b2 = last ? nB : cB + (size_t)(t + 2) * kstep;
;             const char* a3 = a2 + kstep; const char* b3 = b2 + kstep;
;             if (last && has_next) S.a_ready(nxt);
;             if constexpr (SP2) {
;             PG8_LDB(B0, 0, 0); PG8_LDB(B1, 0, 1); PG8_SCHED; PG8_LDA(At, 0, 0); PG8_STAGE(PG8_SA(1, 1), a1 + hstepA, voffA);
;             if (plast) PG8_WAIT_V(10); else PG8_WAIT_SEL(defer, 12, 16);
.LBB0_415:
	v_add_u32_e32 v128, 0, v239
	v_add_u32_e32 v129, 0x10000, v128
	v_add_u32_e32 v140, 0x14000, v128
	ds_read_b128 v[144:147], v129
	ds_read_b128 v[148:151], v129 offset:1024
	ds_read_b128 v[152:155], v129 offset:2048
	ds_read_b128 v[156:159], v129 offset:3072
	ds_read_b128 v[128:131], v140
	ds_read_b128 v[132:135], v140 offset:1024
	ds_read_b128 v[136:139], v140 offset:2048
	ds_read_b128 v[140:143], v140 offset:3072
	v_lshl_add_u64 v[194:195], s[26:27], 0, v[212:213]
	s_add_i32 m0, s39, 0xc000
	ds_read_b128 v[184:187], v240
	ds_read_b128 v[188:191], v240 offset:1024
	ds_read_b128 v[176:179], v240 offset:2048
	ds_read_b128 v[180:183], v240 offset:3072
	ds_read_b128 v[168:171], v240 offset:4096
	ds_read_b128 v[172:175], v240 offset:5120
	ds_read_b128 v[160:163], v240 offset:6144
	ds_read_b128 v[164:167], v240 offset:7168
	global_load_lds_dwordx4 v[194:195], off
	v_lshl_add_u64 v[194:195], s[26:27], 0, v[214:215]
	s_add_i32 m0, s39, 0xe000
	s_mov_b64 s[34:35], -1
	global_load_lds_dwordx4 v[194:195], off
	s_and_b64 vcc, exec, s[30:31]
	s_cbranch_vccz .LBB0_417
	s_waitcnt vmcnt(8)
	s_mov_b64 s[34:35], 0

; #define PG8_STAGE(bufoff, gbase, voff) do { _Pragma("unroll") for (int _i = 0; _i < 2; ++_i) \
;         __builtin_amdgcn_global_load_lds((const unsigned*)((const char*)(gbase) + (voff)[_i]), (PG8_LAS unsigned*)(lds + (bufoff) + ldsw + _i * 8192), 16, 0, 0); } while (0)
; #define PG8_LDA(dst, b, h) do { _Pragma("unroll") for (int m = 0; m < 4; ++m) _Pragma("unroll") for (int k = 0; k < 2; ++k) dst[m][k] = *(const PG8_LAS bf16x8*)(lds + PG8_SA(b, h) + aoff + m * 2048 + k * 1024); } while (0)
; #define PG8_LDB(dst, b, h) do { _Pragma("unroll") for (int n = 0; n < 2; ++n) _Pragma("unroll") for (int k = 0; k < 2; ++k) dst[n][k] = *(const PG8_LAS bf16x8*)(lds + PG8_SB(b, h) + boff + n * 2048 + k * 1024); } while (0)
; #define PG8_WAIT_V(n) asm volatile("s_waitcnt vmcnt(" #n ")" ::: "memory")
; #define PG8_WAIT_SEL(d, w4, w8) do { if constexpr (Epi::SPLIT) { if (d) { if constexpr (Epi::NSH == 4) PG8_WAIT_V(w4); else PG8_WAIT_V(w8); } else PG8_WAIT_V(8); } else PG8_WAIT_V(8); } while (0)
; #define PG8_BAR __builtin_amdgcn_s_barrier()
; template <class Epi, class Sched, bool ALIGN_EPI = false, bool SP2 = false>
; __device__ __forceinline__ void gemm_phase(PG8_LAS unsigned char* lds, const Gemm g, const Sched& S, const Epi& E) {
;     ...
;             const char* a2 = last ? nA : cA + (size_t)(t + 2) * kstep; const char* b2 = last ? nB : cB + (size_t)(t + 2) * kstep;
;             const char* a3 = a2 + kstep; const char* b3 = b2 + kstep;
;             if (last && has_next) S.a_ready(nxt);
;             if constexpr (SP2) {
;             PG8_LDB(B0, 0, 0); PG8_LDB(B1, 0, 1); PG8_SCHED; PG8_LDA(At, 0, 0); PG8_STAGE(PG8_SA(1, 1), a1 + hstepA, voffA);
;             if (plast) PG8_WAIT_V(10); else PG8_WAIT_SEL(defer, 12, 16);
;             PG8_WAIT_L(0); PG8_BAR; PG8_MMA(0, 0, At, B0); PG8_MMA(0, 1, At, B1);
;             if constexpr (Epi::SPLIT) { if (defer) {
;                 E.second(acc, prev, rv1, wr, wc, fr, fq);
;                 _Pragma("unroll") for (int b = 0; b < 2; ++b) _Pragma("unroll") for (int m = 0; m < 4; ++m) _Pragma("unroll") for (int n = 0; n < 2; ++n) acc[1][b][m][n] = (f32x4){0.f, 0.f, 0.f, 0.f}; } }
;             PG8_BAR; PG8_SCHED;
;             PG8_LDA(At, 0, 1); PG8_STAGE(PG8_SB(0, 0), b2, voffB); PG8_STAGE(PG8_SB(0, 1), b2 + hstep, voffB); PG8_STAGE(PG8_SA(0, 0), a2, voffA);
;             if (plast) PG8_WAIT_V(10); else PG8_WAIT_SEL(defer, 16, 24);
.LBB0_419:
	s_add_u32 s34, s26, 0x80
	s_addc_u32 s35, s27, 0
	s_waitcnt lgkmcnt(0)
	s_and_b64 s[28:29], s[28:29], exec
	s_cselect_b32 s29, s9, s35
	s_cselect_b32 s28, s8, s34
	s_cselect_b32 s35, s11, s33
	s_cselect_b32 s34, s10, s1
	s_barrier
	s_setprio 1
	s_waitcnt lgkmcnt(0)
	v_mfma_f32_16x16x32_bf16 v[120:123], v[144:147], v[184:187], v[120:123]
	v_mfma_f32_16x16x32_bf16 v[112:115], v[152:155], v[184:187], v[112:115]
	v_mfma_f32_16x16x32_bf16 v[104:107], v[144:147], v[176:179], v[104:107]
	v_mfma_f32_16x16x32_bf16 v[96:99], v[152:155], v[176:179], v[96:99]
	v_mfma_f32_16x16x32_bf16 v[88:91], v[144:147], v[168:171], v[88:91]
	v_mfma_f32_16x16x32_bf16 v[80:83], v[152:155], v[168:171], v[80:83]
	v_mfma_f32_16x16x32_bf16 v[72:75], v[144:147], v[160:163], v[72:75]
	v_mfma_f32_16x16x32_bf16 v[64:67], v[152:155], v[160:163], v[64:67]
	v_mfma_f32_16x16x32_bf16 v[120:123], v[148:151], v[188:191], v[120:123]
	v_mfma_f32_16x16x32_bf16 v[112:115], v[156:159], v[188:191], v[112:115]
	v_mfma_f32_16x16x32_bf16 v[104:107], v[148:151], v[180:183], v[104:107]
	v_mfma_f32_16x16x32_bf16 v[96:99], v[156:159], v[180:183], v[96:99]
	v_mfma_f32_16x16x32_bf16 v[88:91], v[148:151], v[172:175], v[88:91]
	v_mfma_f32_16x16x32_bf16 v[80:83], v[156:159], v[172:175], v[80:83]
	v_mfma_f32_16x16x32_bf16 v[72:75], v[148:151], v[164:167], v[72:75]
	v_mfma_f32_16x16x32_bf16 v[64:67], v[156:159], v[164:167], v[64:67]
	s_setprio 0
	s_setprio 1
	v_mfma_f32_16x16x32_bf16 v[124:127], v[128:131], v[184:187], v[124:127]
	v_mfma_f32_16x16x32_bf16 v[116:119], v[136:139], v[184:187], v[116:119]
	v_mfma_f32_16x16x32_bf16 v[108:111], v[128:131], v[176:179], v[108:111]
	v_mfma_f32_16x16x32_bf16 v[100:103], v[136:139], v[176:179], v[100:103]
	v_mfma_f32_16x16x32_bf16 v[92:95], v[128:131], v[168:171], v[92:95]
	v_mfma_f32_16x16x32_bf16 v[84:87], v[136:139], v[168:171], v[84:87]
	v_mfma_f32_16x16x32_bf16 v[76:79], v[128:131], v[160:163], v[76:79]
	v_mfma_f32_16x16x32_bf16 v[68:71], v[136:139], v[160:163], v[68:71]
	v_mfma_f32_16x16x32_bf16 v[124:127], v[132:135], v[188:191], v[124:127]
	v_mfma_f32_16x16x32_bf16 v[116:119], v[140:143], v[188:191], v[116:119]
	v_mfma_f32_16x16x32_bf16 v[108:111], v[132:135], v[180:183], v[108:111]
	v_mfma_f32_16x16x32_bf16 v[100:103], v[140:143], v[180:183], v[100:103]
	v_mfma_f32_16x16x32_bf16 v[92:95], v[132:135], v[172:175], v[92:95]
	v_mfma_f32_16x16x32_bf16 v[84:87], v[140:143], v[172:175], v[84:87]
	v_mfma_f32_16x16x32_bf16 v[76:79], v[132:135], v[164:167], v[76:79]
	v_mfma_f32_16x16x32_bf16 v[68:71], v[140:143], v[164:167], v[68:71]
	s_setprio 0
	s_barrier
	s_mov_b32 m0, s40
	v_lshl_add_u64 v[222:223], s[34:35], 0, v[192:193]
	v_lshl_add_u64 v[220:221], s[34:35], 0, v[204:205]
	s_add_u32 s34, s34, s16
	ds_read_b128 v[184:187], v240 offset:16384
	ds_read_b128 v[188:191], v240 offset:17408
	ds_read_b128 v[176:179], v240 offset:18432
	ds_read_b128 v[180:183], v240 offset:19456
	ds_read_b128 v[168:171], v240 offset:20480
	ds_read_b128 v[172:175], v240 offset:21504
	ds_read_b128 v[160:163], v240 offset:22528
	ds_read_b128 v[164:167], v240 offset:23552
	global_load_lds_dwordx4 v[222:223], off
	s_mov_b32 m0, s41
	s_addc_u32 s35, s35, s17
	global_load_lds_dwordx4 v[220:221], off
	v_lshl_add_u64 v[230:231], s[34:35], 0, v[192:193]
	s_mov_b32 m0, s42
	v_lshl_add_u64 v[228:229], s[34:35], 0, v[204:205]
	global_load_lds_dwordx4 v[230:231], off
	s_mov_b32 m0, s43
	v_lshl_add_u64 v[224:225], s[28:29], 0, v[208:209]
	global_load_lds_dwordx4 v[228:229], off
	s_mov_b32 m0, s39
	v_lshl_add_u64 v[226:227], s[28:29], 0, v[206:207]
	global_load_lds_dwordx4 v[224:225], off
	s_mov_b32 m0, s44
	s_mov_b64 s[34:35], -1
	global_load_lds_dwordx4 v[226:227], off
	s_and_b64 vcc, exec, s[30:31]
	s_cbranch_vccz .LBB0_421
	s_waitcnt vmcnt(8)
	s_mov_b64 s[34:35], 0

; #define LAS __attribute__((address_space(3)))
; __device__ __forceinline__ float fast_sigmoid(float x) { return __builtin_amdgcn_rcpf(1.0f + __expf(-x)); }
;     __device__ __forceinline__ void operator()(const f32x4 (&acc)[2][2][4][2], const pg8::Unit& u, int wr, int wc, int fr_, int fq_, LAS const unsigned char* xl) const {
;     ...
;         if (MODE == 0 || MODE == 1 || MODE == 4) {
; #pragma unroll
;             for (int ai = 0; ai < 2; ++ai)
; #pragma unroll
;                 for (int m = 0; m < 4; ++m) { const f32x4 pv = *(LAS const f32x4*)(xl + (ai * 128 + wr * 64 + m * 16 + fr) * 64 + fq * 16); rv[ai][m] = (pv[0] + pv[1]) + (pv[2] + pv[3]); }
; #pragma unroll
;             for (int ai = 0; ai < 2; ++ai)
; #pragma unroll
;                 for (int m = 0; m < 4; ++m) rv[ai][m] = __builtin_amdgcn_rsqf(xrow16_sum(rv[ai][m]) * (1.0f / 1024.0f) + EPS);
;         }
;         if (MODE == 0 || MODE == 1 || MODE == 2) {
; #pragma unroll
;             for (int ai = 0; ai < 2; ++ai)
; #pragma unroll
;                 for (int m = 0; m < 4; ++m) {
;                     const int row = row0 + ai * 128 + m * 16;
;                     const float rinv = (MODE == 2) ? 1.f : rv[ai][m];
;                     if (MODE == 0 || MODE == 2) {
;                         bf16_t* rowp = O + (size_t)row * ldc + u.pn * 256 + wc * 32 + 8 * fq;
; #pragma unroll
;                         for (int bj = 0; bj < 2; ++bj) { const f32x4 v0 = acc[ai][bj][m][0] * rinv, v1 = acc[ai][bj][m][1] * rinv;
;                             u32x4 w; w.x = pg8::cvt_pk_bf16(v0[0], v0[1]); w.y = pg8::cvt_pk_bf16(v0[2], v0[3]); w.z = pg8::cvt_pk_bf16(v1[0], v1[1]); w.w = pg8::cvt_pk_bf16(v1[2], v1[3]);
;                             *(u32x4*)(rowp + bj * 128) = w; }
;                     } else {
;                         bf16_t* rowp = O + (size_t)row * ldc + u.pn * 128 + wc * 32 + 8 * fq;
;                         float a[8];
; #pragma unroll
;                         for (int n = 0; n < 2; ++n)
; #pragma unroll
;                             for (int j = 0; j < 4; ++j) { const float g = acc[ai][0][m][n][j] * rinv, up = acc[ai][1][m][n][j] * rinv; a[4 * n + j] = g * fast_sigmoid(g) * up; }
;                         u32x4 w; w.x = pg8::cvt_pk_bf16(a[0], a[1]); w.y = pg8::cvt_pk_bf16(a[2], a[3]); w.z = pg8::cvt_pk_bf16(a[4], a[5]); w.w = pg8::cvt_pk_bf16(a[6], a[7]);
;                         *(u32x4*)rowp = w;
.LBB0_425:
	v_mov_b32_e32 v128, v237
	v_mov_b32_e32 v133, v238
	s_add_i32 s1, 0, 0x20000
	v_add_u32_e32 v135, s48, v128
	v_lshlrev_b32_e32 v128, 4, v133
	v_lshlrev_b32_e32 v129, 6, v135
	v_add3_u32 v132, s1, v128, v129
	ds_read_b128 v[128:131], v132
	v_mov_b32_e32 v150, v124
	v_mov_b32_e32 v151, v120
	v_lshlrev_b32_e32 v146, 3, v133
	v_ashrrev_i32_e32 v147, 31, v146
	s_waitcnt lgkmcnt(0)
	v_add_f32_e32 v128, v128, v129
	v_add_f32_e32 v129, v130, v131
	v_add_f32_e32 v134, v128, v129
	ds_read_b128 v[128:131], v132 offset:1024
	s_and_b64 vcc, exec, s[6:7]
	s_waitcnt lgkmcnt(0)
	v_add_f32_e32 v128, v128, v129
	v_add_f32_e32 v129, v130, v131
	v_add_f32_e32 v136, v128, v129
	ds_read_b128 v[128:131], v132 offset:2048
	s_waitcnt lgkmcnt(0)
	v_add_f32_e32 v128, v128, v129
	v_add_f32_e32 v129, v130, v131
	v_add_f32_e32 v137, v128, v129
	ds_read_b128 v[128:131], v132 offset:3072
	s_waitcnt lgkmcnt(0)
	v_add_f32_e32 v128, v128, v129
	v_add_f32_e32 v129, v130, v131
	v_add_f32_e32 v138, v128, v129
	ds_read_b128 v[128:131], v132 offset:8192
	s_waitcnt lgkmcnt(0)
	v_add_f32_e32 v128, v128, v129
	v_add_f32_e32 v129, v130, v131
	v_add_f32_e32 v139, v128, v129
	ds_read_b128 v[128:131], v132 offset:9216
	s_waitcnt lgkmcnt(0)
	v_add_f32_e32 v128, v128, v129
	v_add_f32_e32 v129, v130, v131
	v_add_f32_e32 v141, v128, v129
	ds_read_b128 v[128:131], v132 offset:10240
	s_waitcnt lgkmcnt(0)
	v_add_f32_e32 v128, v128, v129
	v_add_f32_e32 v129, v130, v131
	v_add_f32_e32 v143, v128, v129
	ds_read_b128 v[128:131], v132 offset:11264
	s_waitcnt lgkmcnt(0)
	v_add_f32_e32 v128, v128, v129
	v_add_f32_e32 v129, v130, v131
	v_add_f32_e32 v128, v128, v129
	v_mov_b32_e32 v129, v134
	s_nop 1
	v_permlane16_swap_b32_e32 v134, v129
	v_add_f32_e32 v129, v134, v129
	v_mov_b32_e32 v130, v129
	s_nop 1
	v_permlane32_swap_b32_e32 v129, v130
	v_add_f32_e32 v129, v129, v130
	v_fmamk_f32 v129, v129, 0x3a800000, v233
	v_rsq_f32_e32 v144, v129
	v_mov_b32_e32 v129, v136
	s_nop 1
	v_permlane16_swap_b32_e32 v136, v129
	v_pk_mul_f32 v[150:151], v[150:151], v[144:145] op_sel_hi:[1,0]
	v_add_f32_e32 v129, v136, v129
	v_mul_f32_e32 v120, 0xbfb8aa3b, v151
	v_exp_f32_e32 v120, v120
	v_mov_b32_e32 v130, v129
	s_nop 1
	v_permlane32_swap_b32_e32 v129, v130
	v_add_f32_e32 v120, 1.0, v120
	v_rcp_f32_e32 v120, v120
	v_add_f32_e32 v129, v129, v130
	v_fmamk_f32 v129, v129, 0x3a800000, v233
	v_rsq_f32_e32 v142, v129
	v_mul_f32_e32 v120, v151, v120
	v_mul_f32_e32 v124, v150, v120
	v_mov_b32_e32 v120, v125
	v_pk_mul_f32 v[120:121], v[120:121], v[144:145] op_sel_hi:[1,0]
	v_mov_b32_e32 v129, v137
	v_mul_f32_e32 v125, 0xbfb8aa3b, v121
	v_exp_f32_e32 v125, v125
	v_permlane16_swap_b32_e32 v137, v129
	v_add_f32_e32 v129, v137, v129
	v_add_f32_e32 v125, 1.0, v125
	v_rcp_f32_e32 v125, v125
	v_mov_b32_e32 v130, v129
	s_nop 1
	v_permlane32_swap_b32_e32 v129, v130
	v_mul_f32_e32 v121, v121, v125
	v_mul_f32_e32 v125, v120, v121
	v_mov_b32_e32 v120, v126
	v_mov_b32_e32 v121, v122
	v_pk_mul_f32 v[120:121], v[120:121], v[144:145] op_sel_hi:[1,0]
	v_add_f32_e32 v129, v129, v130
	v_mul_f32_e32 v122, 0xbfb8aa3b, v121
	v_exp_f32_e32 v122, v122
	v_fmamk_f32 v129, v129, 0x3a800000, v233
	v_rsq_f32_e32 v140, v129
	v_mov_b32_e32 v129, v138
	v_add_f32_e32 v122, 1.0, v122
	v_rcp_f32_e32 v122, v122
	v_permlane16_swap_b32_e32 v138, v129
	v_add_f32_e32 v129, v138, v129
	v_mul_f32_e32 v121, v121, v122
	v_mov_b32_e32 v122, v127
	v_mul_f32_e32 v126, v120, v121
	v_pk_mul_f32 v[120:121], v[122:123], v[144:145] op_sel_hi:[1,0]
	v_mov_b32_e32 v130, v129
	v_mul_f32_e32 v122, 0xbfb8aa3b, v121
	v_exp_f32_e32 v122, v122
	v_permlane32_swap_b32_e32 v129, v130
	v_add_f32_e32 v129, v129, v130
	v_add_f32_e32 v122, 1.0, v122
	v_rcp_f32_e32 v122, v122
	v_fmamk_f32 v129, v129, 0x3a800000, v233
	v_rsq_f32_e32 v138, v129
	v_mov_b32_e32 v129, v139
	v_mul_f32_e32 v121, v121, v122
	v_mul_f32_e32 v122, v120, v121
	v_mov_b32_e32 v120, v116
	v_mov_b32_e32 v121, v112
	v_pk_mul_f32 v[120:121], v[120:121], v[144:145] op_sel_hi:[1,0]
	v_permlane16_swap_b32_e32 v139, v129
	v_mul_f32_e32 v112, 0xbfb8aa3b, v121
	v_exp_f32_e32 v112, v112
	v_add_f32_e32 v129, v139, v129
	v_mov_b32_e32 v130, v129
	s_nop 1
	v_permlane32_swap_b32_e32 v129, v130
	v_add_f32_e32 v112, 1.0, v112
	v_rcp_f32_e32 v112, v112
	v_add_f32_e32 v129, v129, v130
	v_fmamk_f32 v129, v129, 0x3a800000, v233
	v_rsq_f32_e32 v136, v129
	v_mul_f32_e32 v112, v121, v112
	v_mul_f32_e32 v116, v120, v112
	v_mov_b32_e32 v112, v117
	v_pk_mul_f32 v[112:113], v[112:113], v[144:145] op_sel_hi:[1,0]
	v_mov_b32_e32 v129, v141
	v_mul_f32_e32 v117, 0xbfb8aa3b, v113
	v_exp_f32_e32 v117, v117
	v_permlane16_swap_b32_e32 v141, v129
	v_add_f32_e32 v129, v141, v129
	v_add_f32_e32 v117, 1.0, v117
	v_rcp_f32_e32 v117, v117
	v_mov_b32_e32 v130, v129
	s_nop 1
	v_permlane32_swap_b32_e32 v129, v130
	v_mul_f32_e32 v113, v113, v117
	v_mul_f32_e32 v117, v112, v113
	v_mov_b32_e32 v112, v118
	v_mov_b32_e32 v113, v114
	v_pk_mul_f32 v[112:113], v[112:113], v[144:145] op_sel_hi:[1,0]
	v_add_f32_e32 v129, v129, v130
	v_mul_f32_e32 v114, 0xbfb8aa3b, v113
	v_exp_f32_e32 v114, v114
	v_fmamk_f32 v129, v129, 0x3a800000, v233
	v_rsq_f32_e32 v134, v129
	v_mov_b32_e32 v129, v143
	v_add_f32_e32 v114, 1.0, v114
	v_rcp_f32_e32 v114, v114
	v_permlane16_swap_b32_e32 v143, v129
	v_add_f32_e32 v129, v143, v129
	v_mov_b32_e32 v130, v129
	v_mul_f32_e32 v113, v113, v114
	v_mov_b32_e32 v114, v119
	v_permlane32_swap_b32_e32 v129, v130
	v_mul_f32_e32 v120, v112, v113
	v_pk_mul_f32 v[112:113], v[114:115], v[144:145] op_sel_hi:[1,0]
	v_add_f32_e32 v129, v129, v130
	v_mul_f32_e32 v114, 0xbfb8aa3b, v113
	v_fmamk_f32 v129, v129, 0x3a800000, v233
	v_exp_f32_e32 v114, v114
; __device__ __forceinline__ unsigned cvt_pk_bf16(float lo, float hi) { unsigned r; asm volatile("v_cvt_pk_bf16_f32 %0, %1, %2" : "=v"(r) : "v"(lo), "v"(hi)); return r; }
; __device__ __forceinline__ float fast_sigmoid(float x) { return __builtin_amdgcn_rcpf(1.0f + __expf(-x)); }
;     __device__ __forceinline__ void operator()(const f32x4 (&acc)[2][2][4][2], const pg8::Unit& u, int wr, int wc, int fr_, int fq_, LAS const unsigned char* xl) const {
;     ...
;                     } else {
;                         bf16_t* rowp = O + (size_t)row * ldc + u.pn * 128 + wc * 32 + 8 * fq;
;                         float a[8];
; #pragma unroll
;                         for (int n = 0; n < 2; ++n)
; #pragma unroll
;                             for (int j = 0; j < 4; ++j) { const float g = acc[ai][0][m][n][j] * rinv, up = acc[ai][1][m][n][j] * rinv; a[4 * n + j] = g * fast_sigmoid(g) * up; }
;                         u32x4 w; w.x = pg8::cvt_pk_bf16(a[0], a[1]); w.y = pg8::cvt_pk_bf16(a[2], a[3]); w.z = pg8::cvt_pk_bf16(a[4], a[5]); w.w = pg8::cvt_pk_bf16(a[6], a[7]);
;                         *(u32x4*)rowp = w;
	v_rsq_f32_e32 v132, v129
	v_mov_b32_e32 v129, v128
	s_nop 1
	v_permlane16_swap_b32_e32 v128, v129
	v_add_f32_e32 v128, v128, v129
	v_mov_b32_e32 v129, v128
	v_add_f32_e32 v114, 1.0, v114
	s_nop 0
	v_permlane32_swap_b32_e32 v128, v129
	v_rcp_f32_e32 v114, v114
	v_add_f32_e32 v128, v128, v129
	v_lshl_add_u32 v129, s0, 8, v135
	s_lshl_b32 s0, s2, 7
	s_ashr_i32 s1, s0, 31
	v_mov_b64_e32 v[130:131], s[72:73]
	v_mad_i64_i32 v[148:149], s[26:27], v129, s83, v[130:131]
	s_lshl_b64 s[0:1], s[0:1], 1
	v_lshl_add_u64 v[148:149], v[148:149], 0, s[0:1]
	v_mul_f32_e32 v113, v113, v114
	v_lshl_add_u64 v[148:149], v[148:149], 0, s[86:87]
	v_mul_f32_e32 v121, v112, v113
	v_lshlrev_b64 v[112:113], 1, v[146:147]
	v_lshl_add_u64 v[118:119], v[148:149], 0, v[112:113]
	v_cvt_pk_bf16_f32 v114, v124, v125
	v_cvt_pk_bf16_f32 v115, v126, v122
	v_cvt_pk_bf16_f32 v116, v116, v117
	v_cvt_pk_bf16_f32 v117, v120, v121
	global_store_dwordx4 v[118:119], v[114:117], off
	v_fmamk_f32 v128, v128, 0x3a800000, v233
	v_rsq_f32_e32 v128, v128
	v_mov_b32_e32 v116, v108
	v_mov_b32_e32 v117, v104
	v_pk_mul_f32 v[116:117], v[116:117], v[142:143] op_sel_hi:[1,0]
	v_add_u32_e32 v114, 16, v129
	v_mul_f32_e32 v104, 0xbfb8aa3b, v117
	v_exp_f32_e32 v104, v104
	v_mad_i64_i32 v[114:115], s[26:27], v114, s83, v[130:131]
	v_lshl_add_u64 v[114:115], v[114:115], 0, s[0:1]
	v_add_f32_e32 v104, 1.0, v104
	v_rcp_f32_e32 v104, v104
	v_lshl_add_u64 v[114:115], v[114:115], 0, s[86:87]
	v_mul_f32_e32 v104, v117, v104
	v_mul_f32_e32 v108, v116, v104
	v_mov_b32_e32 v104, v109
	v_pk_mul_f32 v[104:105], v[104:105], v[142:143] op_sel_hi:[1,0]
	s_nop 0
	v_mul_f32_e32 v109, 0xbfb8aa3b, v105
	v_exp_f32_e32 v109, v109
	s_nop 0
	v_add_f32_e32 v109, 1.0, v109
	v_rcp_f32_e32 v109, v109
	s_nop 0
	v_mul_f32_e32 v105, v105, v109
	v_mul_f32_e32 v109, v104, v105
	v_mov_b32_e32 v104, v110
	v_mov_b32_e32 v105, v106
	v_pk_mul_f32 v[104:105], v[104:105], v[142:143] op_sel_hi:[1,0]
	s_nop 0
	v_mul_f32_e32 v106, 0xbfb8aa3b, v105
	v_exp_f32_e32 v106, v106
	s_nop 0
	v_add_f32_e32 v106, 1.0, v106
	v_rcp_f32_e32 v106, v106
	s_nop 0
	v_mul_f32_e32 v105, v105, v106
	v_mov_b32_e32 v106, v111
	v_mul_f32_e32 v110, v104, v105
	v_pk_mul_f32 v[104:105], v[106:107], v[142:143] op_sel_hi:[1,0]
	s_nop 0
	v_mul_f32_e32 v106, 0xbfb8aa3b, v105
	v_exp_f32_e32 v106, v106
	s_nop 0
	v_add_f32_e32 v106, 1.0, v106
	v_rcp_f32_e32 v106, v106
	s_nop 0
	v_mul_f32_e32 v105, v105, v106
	v_mul_f32_e32 v106, v104, v105
	v_mov_b32_e32 v104, v100
	v_mov_b32_e32 v105, v96
	v_pk_mul_f32 v[104:105], v[104:105], v[142:143] op_sel_hi:[1,0]
	s_nop 0
	v_mul_f32_e32 v96, 0xbfb8aa3b, v105
	v_exp_f32_e32 v96, v96
	s_nop 0
	v_add_f32_e32 v96, 1.0, v96
	v_rcp_f32_e32 v96, v96
	s_nop 0
	v_mul_f32_e32 v96, v105, v96
	v_mul_f32_e32 v104, v104, v96
	v_mov_b32_e32 v96, v101
	v_pk_mul_f32 v[96:97], v[96:97], v[142:143] op_sel_hi:[1,0]
	s_nop 0
	v_mul_f32_e32 v100, 0xbfb8aa3b, v97
	v_exp_f32_e32 v100, v100
	s_nop 0
	v_add_f32_e32 v100, 1.0, v100
	v_rcp_f32_e32 v100, v100
	s_nop 0
	v_mul_f32_e32 v97, v97, v100
	v_mul_f32_e32 v105, v96, v97
	v_mov_b32_e32 v96, v102
	v_mov_b32_e32 v97, v98
	v_pk_mul_f32 v[96:97], v[96:97], v[142:143] op_sel_hi:[1,0]
	v_lshl_add_u64 v[100:101], v[114:115], 0, v[112:113]
	v_mul_f32_e32 v98, 0xbfb8aa3b, v97
	v_exp_f32_e32 v98, v98
	s_nop 0
	v_add_f32_e32 v98, 1.0, v98
	v_rcp_f32_e32 v98, v98
	s_nop 0
	v_mul_f32_e32 v97, v97, v98
	v_mov_b32_e32 v98, v103
	v_mul_f32_e32 v102, v96, v97
	v_pk_mul_f32 v[96:97], v[98:99], v[142:143] op_sel_hi:[1,0]
	s_nop 0
	v_mul_f32_e32 v98, 0xbfb8aa3b, v97
	v_exp_f32_e32 v98, v98
	s_nop 0
	v_add_f32_e32 v98, 1.0, v98
	v_rcp_f32_e32 v98, v98
	s_nop 0
	v_mul_f32_e32 v97, v97, v98
	v_mul_f32_e32 v99, v96, v97
	v_cvt_pk_bf16_f32 v96, v108, v109
	v_cvt_pk_bf16_f32 v97, v110, v106
	v_cvt_pk_bf16_f32 v98, v104, v105
	v_cvt_pk_bf16_f32 v99, v102, v99
	global_store_dwordx4 v[100:101], v[96:99], off
	s_nop 1
	v_mov_b32_e32 v98, v92
	v_mov_b32_e32 v99, v88
	v_pk_mul_f32 v[98:99], v[98:99], v[140:141] op_sel_hi:[1,0]
	v_add_u32_e32 v96, 32, v129
	v_mul_f32_e32 v88, 0xbfb8aa3b, v99
	v_exp_f32_e32 v88, v88
	v_mad_i64_i32 v[96:97], s[26:27], v96, s83, v[130:131]
	v_lshl_add_u64 v[96:97], v[96:97], 0, s[0:1]
	v_add_f32_e32 v88, 1.0, v88
	v_rcp_f32_e32 v88, v88
	v_lshl_add_u64 v[96:97], v[96:97], 0, s[86:87]
	v_mul_f32_e32 v88, v99, v88
	v_mul_f32_e32 v92, v98, v88
	v_mov_b32_e32 v88, v93
	v_pk_mul_f32 v[88:89], v[88:89], v[140:141] op_sel_hi:[1,0]
	s_nop 0
	v_mul_f32_e32 v93, 0xbfb8aa3b, v89
	v_exp_f32_e32 v93, v93
	s_nop 0
	v_add_f32_e32 v93, 1.0, v93
	v_rcp_f32_e32 v93, v93
	s_nop 0
	v_mul_f32_e32 v89, v89, v93
	v_mul_f32_e32 v93, v88, v89
	v_mov_b32_e32 v88, v94
	v_mov_b32_e32 v89, v90
	v_pk_mul_f32 v[88:89], v[88:89], v[140:141] op_sel_hi:[1,0]
	s_nop 0
	v_mul_f32_e32 v90, 0xbfb8aa3b, v89
	v_exp_f32_e32 v90, v90
	s_nop 0
	v_add_f32_e32 v90, 1.0, v90
	v_rcp_f32_e32 v90, v90
	s_nop 0
	v_mul_f32_e32 v89, v89, v90
	v_mov_b32_e32 v90, v95
	v_mul_f32_e32 v94, v88, v89
	v_pk_mul_f32 v[88:89], v[90:91], v[140:141] op_sel_hi:[1,0]
	s_nop 0
	v_mul_f32_e32 v90, 0xbfb8aa3b, v89
	v_exp_f32_e32 v90, v90
	s_nop 0
	v_add_f32_e32 v90, 1.0, v90
	v_rcp_f32_e32 v90, v90
	s_nop 0
	v_mul_f32_e32 v89, v89, v90
	v_mul_f32_e32 v90, v88, v89
	v_mov_b32_e32 v88, v84
	v_mov_b32_e32 v89, v80
	v_pk_mul_f32 v[88:89], v[88:89], v[140:141] op_sel_hi:[1,0]
	s_nop 0
	v_mul_f32_e32 v80, 0xbfb8aa3b, v89
	v_exp_f32_e32 v80, v80
	s_nop 0
	v_add_f32_e32 v80, 1.0, v80
	v_rcp_f32_e32 v80, v80
	s_nop 0
	v_mul_f32_e32 v80, v89, v80
	v_mul_f32_e32 v88, v88, v80
	v_mov_b32_e32 v80, v85
	v_pk_mul_f32 v[80:81], v[80:81], v[140:141] op_sel_hi:[1,0]
	s_nop 0
; __device__ __forceinline__ unsigned cvt_pk_bf16(float lo, float hi) { unsigned r; asm volatile("v_cvt_pk_bf16_f32 %0, %1, %2" : "=v"(r) : "v"(lo), "v"(hi)); return r; }
; __device__ __forceinline__ float fast_sigmoid(float x) { return __builtin_amdgcn_rcpf(1.0f + __expf(-x)); }
;     __device__ __forceinline__ void operator()(const f32x4 (&acc)[2][2][4][2], const pg8::Unit& u, int wr, int wc, int fr_, int fq_, LAS const unsigned char* xl) const {
;     ...
;                     } else {
;                         bf16_t* rowp = O + (size_t)row * ldc + u.pn * 128 + wc * 32 + 8 * fq;
;                         float a[8];
; #pragma unroll
;                         for (int n = 0; n < 2; ++n)
; #pragma unroll
;                             for (int j = 0; j < 4; ++j) { const float g = acc[ai][0][m][n][j] * rinv, up = acc[ai][1][m][n][j] * rinv; a[4 * n + j] = g * fast_sigmoid(g) * up; }
;                         u32x4 w; w.x = pg8::cvt_pk_bf16(a[0], a[1]); w.y = pg8::cvt_pk_bf16(a[2], a[3]); w.z = pg8::cvt_pk_bf16(a[4], a[5]); w.w = pg8::cvt_pk_bf16(a[6], a[7]);
;                         *(u32x4*)rowp = w;
	v_mul_f32_e32 v84, 0xbfb8aa3b, v81
	v_exp_f32_e32 v84, v84
	s_nop 0
	v_add_f32_e32 v84, 1.0, v84
	v_rcp_f32_e32 v84, v84
	s_nop 0
	v_mul_f32_e32 v81, v81, v84
	v_mul_f32_e32 v89, v80, v81
	v_mov_b32_e32 v80, v86
	v_mov_b32_e32 v81, v82
	v_pk_mul_f32 v[80:81], v[80:81], v[140:141] op_sel_hi:[1,0]
	v_lshl_add_u64 v[84:85], v[96:97], 0, v[112:113]
	v_mul_f32_e32 v82, 0xbfb8aa3b, v81
	v_exp_f32_e32 v82, v82
	s_nop 0
	v_add_f32_e32 v82, 1.0, v82
	v_rcp_f32_e32 v82, v82
	s_nop 0
	v_mul_f32_e32 v81, v81, v82
	v_mov_b32_e32 v82, v87
	v_mul_f32_e32 v86, v80, v81
	v_pk_mul_f32 v[80:81], v[82:83], v[140:141] op_sel_hi:[1,0]
	s_nop 0
	v_mul_f32_e32 v82, 0xbfb8aa3b, v81
	v_exp_f32_e32 v82, v82
	s_nop 0
	v_add_f32_e32 v82, 1.0, v82
	v_rcp_f32_e32 v82, v82
	s_nop 0
	v_mul_f32_e32 v81, v81, v82
	v_mul_f32_e32 v83, v80, v81
	v_cvt_pk_bf16_f32 v80, v92, v93
	v_cvt_pk_bf16_f32 v81, v94, v90
	v_cvt_pk_bf16_f32 v82, v88, v89
	v_cvt_pk_bf16_f32 v83, v86, v83
	global_store_dwordx4 v[84:85], v[80:83], off
	s_nop 1
	v_mov_b32_e32 v82, v76
	v_mov_b32_e32 v83, v72
	v_pk_mul_f32 v[82:83], v[82:83], v[138:139] op_sel_hi:[1,0]
	v_add_u32_e32 v80, 48, v129
	v_mul_f32_e32 v72, 0xbfb8aa3b, v83
	v_exp_f32_e32 v72, v72
	v_mad_i64_i32 v[80:81], s[26:27], v80, s83, v[130:131]
	v_lshl_add_u64 v[80:81], v[80:81], 0, s[0:1]
	v_add_f32_e32 v72, 1.0, v72
	v_rcp_f32_e32 v72, v72
	v_lshl_add_u64 v[80:81], v[80:81], 0, s[86:87]
	v_mul_f32_e32 v72, v83, v72
	v_mul_f32_e32 v76, v82, v72
	v_mov_b32_e32 v72, v77
	v_pk_mul_f32 v[72:73], v[72:73], v[138:139] op_sel_hi:[1,0]
	s_nop 0
	v_mul_f32_e32 v77, 0xbfb8aa3b, v73
	v_exp_f32_e32 v77, v77
	s_nop 0
	v_add_f32_e32 v77, 1.0, v77
	v_rcp_f32_e32 v77, v77
	s_nop 0
	v_mul_f32_e32 v73, v73, v77
	v_mul_f32_e32 v77, v72, v73
	v_mov_b32_e32 v72, v78
	v_mov_b32_e32 v73, v74
	v_pk_mul_f32 v[72:73], v[72:73], v[138:139] op_sel_hi:[1,0]
	s_nop 0
	v_mul_f32_e32 v74, 0xbfb8aa3b, v73
	v_exp_f32_e32 v74, v74
	s_nop 0
	v_add_f32_e32 v74, 1.0, v74
	v_rcp_f32_e32 v74, v74
	s_nop 0
	v_mul_f32_e32 v73, v73, v74
	v_mov_b32_e32 v74, v79
	v_mul_f32_e32 v78, v72, v73
	v_pk_mul_f32 v[72:73], v[74:75], v[138:139] op_sel_hi:[1,0]
	s_nop 0
	v_mul_f32_e32 v74, 0xbfb8aa3b, v73
	v_exp_f32_e32 v74, v74
	s_nop 0
	v_add_f32_e32 v74, 1.0, v74
	v_rcp_f32_e32 v74, v74
	s_nop 0
	v_mul_f32_e32 v73, v73, v74
	v_mul_f32_e32 v74, v72, v73
	v_mov_b32_e32 v72, v68
	v_mov_b32_e32 v73, v64
	v_pk_mul_f32 v[72:73], v[72:73], v[138:139] op_sel_hi:[1,0]
	s_nop 0
	v_mul_f32_e32 v64, 0xbfb8aa3b, v73
	v_exp_f32_e32 v64, v64
	s_nop 0
	v_add_f32_e32 v64, 1.0, v64
	v_rcp_f32_e32 v64, v64
	s_nop 0
	v_mul_f32_e32 v64, v73, v64
	v_mul_f32_e32 v72, v72, v64
	v_mov_b32_e32 v64, v69
	v_pk_mul_f32 v[64:65], v[64:65], v[138:139] op_sel_hi:[1,0]
	s_nop 0
	v_mul_f32_e32 v68, 0xbfb8aa3b, v65
	v_exp_f32_e32 v68, v68
	s_nop 0
	v_add_f32_e32 v68, 1.0, v68
	v_rcp_f32_e32 v68, v68
	s_nop 0
	v_mul_f32_e32 v65, v65, v68
	v_mul_f32_e32 v73, v64, v65
	v_mov_b32_e32 v64, v70
	v_mov_b32_e32 v65, v66
	v_pk_mul_f32 v[64:65], v[64:65], v[138:139] op_sel_hi:[1,0]
	v_lshl_add_u64 v[68:69], v[80:81], 0, v[112:113]
	v_mul_f32_e32 v66, 0xbfb8aa3b, v65
	v_exp_f32_e32 v66, v66
	s_nop 0
	v_add_f32_e32 v66, 1.0, v66
	v_rcp_f32_e32 v66, v66
	s_nop 0
	v_mul_f32_e32 v65, v65, v66
	v_mov_b32_e32 v66, v71
	v_mul_f32_e32 v70, v64, v65
	v_pk_mul_f32 v[64:65], v[66:67], v[138:139] op_sel_hi:[1,0]
	s_nop 0
	v_mul_f32_e32 v66, 0xbfb8aa3b, v65
	v_exp_f32_e32 v66, v66
	s_nop 0
	v_add_f32_e32 v66, 1.0, v66
	v_rcp_f32_e32 v66, v66
	s_nop 0
	v_mul_f32_e32 v65, v65, v66
	v_mul_f32_e32 v67, v64, v65
	v_cvt_pk_bf16_f32 v64, v76, v77
	v_cvt_pk_bf16_f32 v65, v78, v74
	v_cvt_pk_bf16_f32 v66, v72, v73
	v_cvt_pk_bf16_f32 v67, v70, v67
	global_store_dwordx4 v[68:69], v[64:67], off
	s_nop 1
	v_mov_b32_e32 v66, v60
	v_mov_b32_e32 v67, v56
	v_pk_mul_f32 v[66:67], v[66:67], v[136:137] op_sel_hi:[1,0]
	v_add_u32_e32 v64, 0x80, v129
	v_mul_f32_e32 v56, 0xbfb8aa3b, v67
	v_exp_f32_e32 v56, v56
	v_mad_i64_i32 v[64:65], s[26:27], v64, s83, v[130:131]
	v_lshl_add_u64 v[64:65], v[64:65], 0, s[0:1]
	v_add_f32_e32 v56, 1.0, v56
	v_rcp_f32_e32 v56, v56
	v_lshl_add_u64 v[64:65], v[64:65], 0, s[86:87]
	v_mul_f32_e32 v56, v67, v56
	v_mul_f32_e32 v60, v66, v56
	v_mov_b32_e32 v56, v61
	v_pk_mul_f32 v[56:57], v[56:57], v[136:137] op_sel_hi:[1,0]
	s_nop 0
	v_mul_f32_e32 v61, 0xbfb8aa3b, v57
	v_exp_f32_e32 v61, v61
	s_nop 0
	v_add_f32_e32 v61, 1.0, v61
	v_rcp_f32_e32 v61, v61
	s_nop 0
	v_mul_f32_e32 v57, v57, v61
	v_mul_f32_e32 v61, v56, v57
	v_mov_b32_e32 v56, v62
	v_mov_b32_e32 v57, v58
	v_pk_mul_f32 v[56:57], v[56:57], v[136:137] op_sel_hi:[1,0]
	s_nop 0
	v_mul_f32_e32 v58, 0xbfb8aa3b, v57
	v_exp_f32_e32 v58, v58
	s_nop 0
	v_add_f32_e32 v58, 1.0, v58
	v_rcp_f32_e32 v58, v58
	s_nop 0
	v_mul_f32_e32 v57, v57, v58
	v_mov_b32_e32 v58, v63
	v_mul_f32_e32 v62, v56, v57
	v_pk_mul_f32 v[56:57], v[58:59], v[136:137] op_sel_hi:[1,0]
	s_nop 0
	v_mul_f32_e32 v58, 0xbfb8aa3b, v57
	v_exp_f32_e32 v58, v58
	s_nop 0
	v_add_f32_e32 v58, 1.0, v58
	v_rcp_f32_e32 v58, v58
	s_nop 0
	v_mul_f32_e32 v57, v57, v58
	v_mul_f32_e32 v58, v56, v57
	v_mov_b32_e32 v56, v52
	v_mov_b32_e32 v57, v48
	v_pk_mul_f32 v[56:57], v[56:57], v[136:137] op_sel_hi:[1,0]
	s_nop 0
	v_mul_f32_e32 v48, 0xbfb8aa3b, v57
	v_exp_f32_e32 v48, v48
	s_nop 0
	v_add_f32_e32 v48, 1.0, v48
	v_rcp_f32_e32 v48, v48
	s_nop 0
	v_mul_f32_e32 v48, v57, v48
	v_mul_f32_e32 v56, v56, v48
	v_mov_b32_e32 v48, v53
	v_pk_mul_f32 v[48:49], v[48:49], v[136:137] op_sel_hi:[1,0]
	s_nop 0
	v_mul_f32_e32 v52, 0xbfb8aa3b, v49
	v_exp_f32_e32 v52, v52
	s_nop 0
	v_add_f32_e32 v52, 1.0, v52
	v_rcp_f32_e32 v52, v52
	s_nop 0
	v_mul_f32_e32 v49, v49, v52
; __device__ __forceinline__ unsigned cvt_pk_bf16(float lo, float hi) { unsigned r; asm volatile("v_cvt_pk_bf16_f32 %0, %1, %2" : "=v"(r) : "v"(lo), "v"(hi)); return r; }
; __device__ __forceinline__ float fast_sigmoid(float x) { return __builtin_amdgcn_rcpf(1.0f + __expf(-x)); }
;     __device__ __forceinline__ void operator()(const f32x4 (&acc)[2][2][4][2], const pg8::Unit& u, int wr, int wc, int fr_, int fq_, LAS const unsigned char* xl) const {
;     ...
;                     } else {
;                         bf16_t* rowp = O + (size_t)row * ldc + u.pn * 128 + wc * 32 + 8 * fq;
;                         float a[8];
; #pragma unroll
;                         for (int n = 0; n < 2; ++n)
; #pragma unroll
;                             for (int j = 0; j < 4; ++j) { const float g = acc[ai][0][m][n][j] * rinv, up = acc[ai][1][m][n][j] * rinv; a[4 * n + j] = g * fast_sigmoid(g) * up; }
;                         u32x4 w; w.x = pg8::cvt_pk_bf16(a[0], a[1]); w.y = pg8::cvt_pk_bf16(a[2], a[3]); w.z = pg8::cvt_pk_bf16(a[4], a[5]); w.w = pg8::cvt_pk_bf16(a[6], a[7]);
;                         *(u32x4*)rowp = w;
	v_mul_f32_e32 v57, v48, v49
	v_mov_b32_e32 v48, v54
	v_mov_b32_e32 v49, v50
	v_pk_mul_f32 v[48:49], v[48:49], v[136:137] op_sel_hi:[1,0]
	v_lshl_add_u64 v[52:53], v[64:65], 0, v[112:113]
	v_mul_f32_e32 v50, 0xbfb8aa3b, v49
	v_exp_f32_e32 v50, v50
	s_nop 0
	v_add_f32_e32 v50, 1.0, v50
	v_rcp_f32_e32 v50, v50
	s_nop 0
	v_mul_f32_e32 v49, v49, v50
	v_mov_b32_e32 v50, v55
	v_mul_f32_e32 v54, v48, v49
	v_pk_mul_f32 v[48:49], v[50:51], v[136:137] op_sel_hi:[1,0]
	s_nop 0
	v_mul_f32_e32 v50, 0xbfb8aa3b, v49
	v_exp_f32_e32 v50, v50
	s_nop 0
	v_add_f32_e32 v50, 1.0, v50
	v_rcp_f32_e32 v50, v50
	s_nop 0
	v_mul_f32_e32 v49, v49, v50
	v_mul_f32_e32 v51, v48, v49
	v_cvt_pk_bf16_f32 v48, v60, v61
	v_cvt_pk_bf16_f32 v49, v62, v58
	v_cvt_pk_bf16_f32 v50, v56, v57
	v_cvt_pk_bf16_f32 v51, v54, v51
	global_store_dwordx4 v[52:53], v[48:51], off
	s_nop 1
	v_mov_b32_e32 v50, v44
	v_mov_b32_e32 v51, v40
	v_pk_mul_f32 v[50:51], v[50:51], v[134:135] op_sel_hi:[1,0]
	v_add_u32_e32 v48, 0x90, v129
	v_mul_f32_e32 v40, 0xbfb8aa3b, v51
	v_exp_f32_e32 v40, v40
	v_mad_i64_i32 v[48:49], s[26:27], v48, s83, v[130:131]
	v_lshl_add_u64 v[48:49], v[48:49], 0, s[0:1]
	v_add_f32_e32 v40, 1.0, v40
	v_rcp_f32_e32 v40, v40
	v_lshl_add_u64 v[48:49], v[48:49], 0, s[86:87]
	v_mul_f32_e32 v40, v51, v40
	v_mul_f32_e32 v44, v50, v40
	v_mov_b32_e32 v40, v45
	v_pk_mul_f32 v[40:41], v[40:41], v[134:135] op_sel_hi:[1,0]
	s_nop 0
	v_mul_f32_e32 v45, 0xbfb8aa3b, v41
	v_exp_f32_e32 v45, v45
	s_nop 0
	v_add_f32_e32 v45, 1.0, v45
	v_rcp_f32_e32 v45, v45
	s_nop 0
	v_mul_f32_e32 v41, v41, v45
	v_mul_f32_e32 v45, v40, v41
	v_mov_b32_e32 v40, v46
	v_mov_b32_e32 v41, v42
	v_pk_mul_f32 v[40:41], v[40:41], v[134:135] op_sel_hi:[1,0]
	s_nop 0
	v_mul_f32_e32 v42, 0xbfb8aa3b, v41
	v_exp_f32_e32 v42, v42
	s_nop 0
	v_add_f32_e32 v42, 1.0, v42
	v_rcp_f32_e32 v42, v42
	s_nop 0
	v_mul_f32_e32 v41, v41, v42
	v_mov_b32_e32 v42, v47
	v_mul_f32_e32 v46, v40, v41
	v_pk_mul_f32 v[40:41], v[42:43], v[134:135] op_sel_hi:[1,0]
	s_nop 0
	v_mul_f32_e32 v42, 0xbfb8aa3b, v41
	v_exp_f32_e32 v42, v42
	s_nop 0
	v_add_f32_e32 v42, 1.0, v42
	v_rcp_f32_e32 v42, v42
	s_nop 0
	v_mul_f32_e32 v41, v41, v42
	v_mul_f32_e32 v42, v40, v41
	v_mov_b32_e32 v40, v36
	v_mov_b32_e32 v41, v32
	v_pk_mul_f32 v[40:41], v[40:41], v[134:135] op_sel_hi:[1,0]
	s_nop 0
	v_mul_f32_e32 v32, 0xbfb8aa3b, v41
	v_exp_f32_e32 v32, v32
	s_nop 0
	v_add_f32_e32 v32, 1.0, v32
	v_rcp_f32_e32 v32, v32
	s_nop 0
	v_mul_f32_e32 v32, v41, v32
	v_mul_f32_e32 v40, v40, v32
	v_mov_b32_e32 v32, v37
	v_pk_mul_f32 v[32:33], v[32:33], v[134:135] op_sel_hi:[1,0]
	s_nop 0
	v_mul_f32_e32 v36, 0xbfb8aa3b, v33
	v_exp_f32_e32 v36, v36
	s_nop 0
	v_add_f32_e32 v36, 1.0, v36
	v_rcp_f32_e32 v36, v36
	s_nop 0
	v_mul_f32_e32 v33, v33, v36
	v_mul_f32_e32 v41, v32, v33
	v_mov_b32_e32 v32, v38
	v_mov_b32_e32 v33, v34
	v_pk_mul_f32 v[32:33], v[32:33], v[134:135] op_sel_hi:[1,0]
	v_lshl_add_u64 v[36:37], v[48:49], 0, v[112:113]
	v_mul_f32_e32 v34, 0xbfb8aa3b, v33
	v_exp_f32_e32 v34, v34
	s_nop 0
	v_add_f32_e32 v34, 1.0, v34
	v_rcp_f32_e32 v34, v34
	s_nop 0
	v_mul_f32_e32 v33, v33, v34
	v_mov_b32_e32 v34, v39
	v_mul_f32_e32 v38, v32, v33
	v_pk_mul_f32 v[32:33], v[34:35], v[134:135] op_sel_hi:[1,0]
	s_nop 0
	v_mul_f32_e32 v34, 0xbfb8aa3b, v33
	v_exp_f32_e32 v34, v34
	s_nop 0
	v_add_f32_e32 v34, 1.0, v34
	v_rcp_f32_e32 v34, v34
	s_nop 0
	v_mul_f32_e32 v33, v33, v34
	v_mul_f32_e32 v35, v32, v33
	v_cvt_pk_bf16_f32 v32, v44, v45
	v_cvt_pk_bf16_f32 v33, v46, v42
	v_cvt_pk_bf16_f32 v34, v40, v41
	v_cvt_pk_bf16_f32 v35, v38, v35
	global_store_dwordx4 v[36:37], v[32:35], off
	s_nop 1
	v_mov_b32_e32 v34, v28
	v_mov_b32_e32 v35, v24
	v_pk_mul_f32 v[34:35], v[34:35], v[132:133] op_sel_hi:[1,0]
	v_add_u32_e32 v32, 0xa0, v129
	v_mul_f32_e32 v24, 0xbfb8aa3b, v35
	v_exp_f32_e32 v24, v24
	v_mad_i64_i32 v[32:33], s[26:27], v32, s83, v[130:131]
	v_lshl_add_u64 v[32:33], v[32:33], 0, s[0:1]
	v_add_f32_e32 v24, 1.0, v24
	v_rcp_f32_e32 v24, v24
	v_lshl_add_u64 v[32:33], v[32:33], 0, s[86:87]
	v_mul_f32_e32 v24, v35, v24
	v_mul_f32_e32 v28, v34, v24
	v_mov_b32_e32 v24, v29
	v_pk_mul_f32 v[24:25], v[24:25], v[132:133] op_sel_hi:[1,0]
	s_nop 0
	v_mul_f32_e32 v29, 0xbfb8aa3b, v25
	v_exp_f32_e32 v29, v29
	s_nop 0
	v_add_f32_e32 v29, 1.0, v29
	v_rcp_f32_e32 v29, v29
	s_nop 0
	v_mul_f32_e32 v25, v25, v29
	v_mul_f32_e32 v29, v24, v25
	v_mov_b32_e32 v24, v30
	v_mov_b32_e32 v25, v26
	v_pk_mul_f32 v[24:25], v[24:25], v[132:133] op_sel_hi:[1,0]
	s_nop 0
	v_mul_f32_e32 v26, 0xbfb8aa3b, v25
	v_exp_f32_e32 v26, v26
	s_nop 0
; __device__ __forceinline__ unsigned cvt_pk_bf16(float lo, float hi) { unsigned r; asm volatile("v_cvt_pk_bf16_f32 %0, %1, %2" : "=v"(r) : "v"(lo), "v"(hi)); return r; }
; #define PG8_BAR __builtin_amdgcn_s_barrier()
; __device__ __forceinline__ float fast_sigmoid(float x) { return __builtin_amdgcn_rcpf(1.0f + __expf(-x)); }
; template <class Epi, class Sched, bool ALIGN_EPI = false, bool SP2 = false>
; __device__ __forceinline__ void gemm_phase(PG8_LAS unsigned char* lds, const Gemm g, const Sched& S, const Epi& E) {
;     ...
;         if constexpr (ALIGN_EPI) { if (wr == 0) PG8_BAR; }
;         if constexpr (Epi::SPLIT) {
;             if (has_next) { E.first(acc, cur, rv1, wr, wc, fr, fq); prev = cur; }
;             else E(acc, cur, wr, wc, fr, fq, lds + STAGE_BYTES);
;         } else if constexpr (!Epi::AFTER_DRAIN) { E(acc, cur, wr, wc, fr, fq, lds + STAGE_BYTES); S.done(cur); }
;         if (!has_next) break;
; #pragma unroll
;         for (int a = 0; a < (Epi::SPLIT ? 1 : 2); ++a)
; #pragma unroll
;             for (int b = 0; b < 2; ++b)
; #pragma unroll
;                 for (int m = 0; m < 4; ++m)
; #pragma unroll
;                     for (int n = 0; n < 2; ++n) acc[a][b][m][n] = (f32x4){0.f, 0.f, 0.f, 0.f};
;         cur = nxt; cA = nA; cB = nB; ++ui;
;         if constexpr (ALIGN_EPI) { if (wr == 1) PG8_BAR; }
;     __device__ __forceinline__ void operator()(const f32x4 (&acc)[2][2][4][2], const pg8::Unit& u, int wr, int wc, int fr_, int fq_, LAS const unsigned char* xl) const {
;     ...
;                     } else {
;                         bf16_t* rowp = O + (size_t)row * ldc + u.pn * 128 + wc * 32 + 8 * fq;
;                         float a[8];
; #pragma unroll
;                         for (int n = 0; n < 2; ++n)
; #pragma unroll
;                             for (int j = 0; j < 4; ++j) { const float g = acc[ai][0][m][n][j] * rinv, up = acc[ai][1][m][n][j] * rinv; a[4 * n + j] = g * fast_sigmoid(g) * up; }
;                         u32x4 w; w.x = pg8::cvt_pk_bf16(a[0], a[1]); w.y = pg8::cvt_pk_bf16(a[2], a[3]); w.z = pg8::cvt_pk_bf16(a[4], a[5]); w.w = pg8::cvt_pk_bf16(a[6], a[7]);
;                         *(u32x4*)rowp = w;
	v_add_f32_e32 v26, 1.0, v26
	v_rcp_f32_e32 v26, v26
	s_nop 0
	v_mul_f32_e32 v25, v25, v26
	v_mov_b32_e32 v26, v31
	v_mul_f32_e32 v30, v24, v25
	v_pk_mul_f32 v[24:25], v[26:27], v[132:133] op_sel_hi:[1,0]
	s_nop 0
	v_mul_f32_e32 v26, 0xbfb8aa3b, v25
	v_exp_f32_e32 v26, v26
	s_nop 0
	v_add_f32_e32 v26, 1.0, v26
	v_rcp_f32_e32 v26, v26
	s_nop 0
	v_mul_f32_e32 v25, v25, v26
	v_mul_f32_e32 v26, v24, v25
	v_mov_b32_e32 v24, v20
	v_mov_b32_e32 v25, v16
	v_pk_mul_f32 v[24:25], v[24:25], v[132:133] op_sel_hi:[1,0]
	s_nop 0
	v_mul_f32_e32 v16, 0xbfb8aa3b, v25
	v_exp_f32_e32 v16, v16
	s_nop 0
	v_add_f32_e32 v16, 1.0, v16
	v_rcp_f32_e32 v16, v16
	s_nop 0
	v_mul_f32_e32 v16, v25, v16
	v_mul_f32_e32 v24, v24, v16
	v_mov_b32_e32 v16, v21
	v_pk_mul_f32 v[16:17], v[16:17], v[132:133] op_sel_hi:[1,0]
	s_nop 0
	v_mul_f32_e32 v20, 0xbfb8aa3b, v17
	v_exp_f32_e32 v20, v20
	s_nop 0
	v_add_f32_e32 v20, 1.0, v20
	v_rcp_f32_e32 v20, v20
	s_nop 0
	v_mul_f32_e32 v17, v17, v20
	v_mul_f32_e32 v25, v16, v17
	v_mov_b32_e32 v16, v22
	v_mov_b32_e32 v17, v18
	v_pk_mul_f32 v[16:17], v[16:17], v[132:133] op_sel_hi:[1,0]
	v_lshl_add_u64 v[20:21], v[32:33], 0, v[112:113]
	v_mul_f32_e32 v18, 0xbfb8aa3b, v17
	v_exp_f32_e32 v18, v18
	s_nop 0
	v_add_f32_e32 v18, 1.0, v18
	v_rcp_f32_e32 v18, v18
	s_nop 0
	v_mul_f32_e32 v17, v17, v18
	v_mov_b32_e32 v18, v23
	v_mul_f32_e32 v22, v16, v17
	v_pk_mul_f32 v[16:17], v[18:19], v[132:133] op_sel_hi:[1,0]
	s_nop 0
	v_mul_f32_e32 v18, 0xbfb8aa3b, v17
	v_exp_f32_e32 v18, v18
	s_nop 0
	v_add_f32_e32 v18, 1.0, v18
	v_rcp_f32_e32 v18, v18
	s_nop 0
	v_mul_f32_e32 v17, v17, v18
	v_mul_f32_e32 v19, v16, v17
	v_cvt_pk_bf16_f32 v16, v28, v29
	v_cvt_pk_bf16_f32 v17, v30, v26
	v_cvt_pk_bf16_f32 v18, v24, v25
	v_cvt_pk_bf16_f32 v19, v22, v19
	global_store_dwordx4 v[20:21], v[16:19], off
	s_nop 1
	v_mov_b32_e32 v18, v12
	v_mov_b32_e32 v19, v8
	v_pk_mul_f32 v[18:19], v[18:19], v[128:129] op_sel_hi:[1,0]
	v_add_u32_e32 v16, 0xb0, v129
	v_mul_f32_e32 v8, 0xbfb8aa3b, v19
	v_exp_f32_e32 v8, v8
	v_mad_i64_i32 v[16:17], s[26:27], v16, s83, v[130:131]
	v_lshl_add_u64 v[16:17], v[16:17], 0, s[0:1]
	v_add_f32_e32 v8, 1.0, v8
	v_rcp_f32_e32 v8, v8
	v_lshl_add_u64 v[16:17], v[16:17], 0, s[86:87]
	s_mov_b64 s[0:1], -1
	v_mul_f32_e32 v8, v19, v8
	v_mul_f32_e32 v12, v18, v8
	v_mov_b32_e32 v8, v13
	v_pk_mul_f32 v[8:9], v[8:9], v[128:129] op_sel_hi:[1,0]
	s_nop 0
	v_mul_f32_e32 v13, 0xbfb8aa3b, v9
	v_exp_f32_e32 v13, v13
	s_nop 0
	v_add_f32_e32 v13, 1.0, v13
	v_rcp_f32_e32 v13, v13
	s_nop 0
	v_mul_f32_e32 v9, v9, v13
	v_mul_f32_e32 v13, v8, v9
	v_mov_b32_e32 v8, v14
	v_mov_b32_e32 v9, v10
	v_pk_mul_f32 v[8:9], v[8:9], v[128:129] op_sel_hi:[1,0]
	s_nop 0
	v_mul_f32_e32 v10, 0xbfb8aa3b, v9
	v_exp_f32_e32 v10, v10
	s_nop 0
	v_add_f32_e32 v10, 1.0, v10
	v_rcp_f32_e32 v10, v10
	s_nop 0
	v_mul_f32_e32 v9, v9, v10
	v_mov_b32_e32 v10, v15
	v_mul_f32_e32 v14, v8, v9
	v_pk_mul_f32 v[8:9], v[10:11], v[128:129] op_sel_hi:[1,0]
	s_nop 0
	v_mul_f32_e32 v10, 0xbfb8aa3b, v9
	v_exp_f32_e32 v10, v10
	s_nop 0
	v_add_f32_e32 v10, 1.0, v10
	v_rcp_f32_e32 v10, v10
	s_nop 0
	v_mul_f32_e32 v9, v9, v10
	v_mul_f32_e32 v10, v8, v9
	v_mov_b32_e32 v8, v0
	v_mov_b32_e32 v9, v4
	v_pk_mul_f32 v[8:9], v[8:9], v[128:129] op_sel_hi:[1,0]
	v_mov_b32_e32 v4, v1
	v_mul_f32_e32 v0, 0xbfb8aa3b, v9
	v_exp_f32_e32 v0, v0
	s_nop 0
	v_add_f32_e32 v0, 1.0, v0
	v_rcp_f32_e32 v0, v0
	s_nop 0
	v_mul_f32_e32 v0, v9, v0
	v_mul_f32_e32 v8, v8, v0
	v_pk_mul_f32 v[0:1], v[4:5], v[128:129] op_sel_hi:[1,0]
	s_nop 0
	v_mul_f32_e32 v4, 0xbfb8aa3b, v1
	v_exp_f32_e32 v4, v4
	s_nop 0
	v_add_f32_e32 v4, 1.0, v4
	v_rcp_f32_e32 v4, v4
	s_nop 0
	v_mul_f32_e32 v1, v1, v4
	v_mul_f32_e32 v9, v0, v1
	v_mov_b32_e32 v0, v2
	v_mov_b32_e32 v1, v6
	v_pk_mul_f32 v[0:1], v[0:1], v[128:129] op_sel_hi:[1,0]
	v_mov_b32_e32 v6, v3
	v_mul_f32_e32 v2, 0xbfb8aa3b, v1
	v_exp_f32_e32 v2, v2
	v_lshl_add_u64 v[4:5], v[16:17], 0, v[112:113]
	v_add_f32_e32 v2, 1.0, v2
	v_rcp_f32_e32 v2, v2
	s_nop 0
	v_mul_f32_e32 v1, v1, v2
	v_mul_f32_e32 v11, v0, v1
	v_pk_mul_f32 v[0:1], v[6:7], v[128:129] op_sel_hi:[1,0]
	s_nop 0
	v_mul_f32_e32 v2, 0xbfb8aa3b, v1
	v_exp_f32_e32 v2, v2
	s_nop 0
	v_add_f32_e32 v2, 1.0, v2
	v_rcp_f32_e32 v2, v2
	s_nop 0
	v_mul_f32_e32 v1, v1, v2
	v_mul_f32_e32 v3, v0, v1
	v_cvt_pk_bf16_f32 v0, v12, v13
	v_cvt_pk_bf16_f32 v1, v14, v10
	v_cvt_pk_bf16_f32 v2, v8, v9
	v_cvt_pk_bf16_f32 v3, v11, v3
	global_store_dwordx4 v[4:5], v[0:3], off
	s_cbranch_vccnz .LBB0_403
	s_andn2_b64 vcc, exec, s[20:21]
	s_cbranch_vccnz .LBB0_402
	s_barrier
	s_branch .LBB0_402

; #define PG8_LAS __attribute__((address_space(3)))
; #define PG8_STAGE(bufoff, gbase, voff) do { _Pragma("unroll") for (int _i = 0; _i < 2; ++_i) \
;         __builtin_amdgcn_global_load_lds((const unsigned*)((const char*)(gbase) + (voff)[_i]), (PG8_LAS unsigned*)(lds + (bufoff) + ldsw + _i * 8192), 16, 0, 0); } while (0)
; #define PG8_LDA(dst, b, h) do { _Pragma("unroll") for (int m = 0; m < 4; ++m) _Pragma("unroll") for (int k = 0; k < 2; ++k) dst[m][k] = *(const PG8_LAS bf16x8*)(lds + PG8_SA(b, h) + aoff + m * 2048 + k * 1024); } while (0)
; #define PG8_WAIT_V(n) asm volatile("s_waitcnt vmcnt(" #n ")" ::: "memory")
; #define PG8_BAR __builtin_amdgcn_s_barrier()
; template <class Epi, class Sched, bool ALIGN_EPI = false, bool SP2 = false>
; __device__ __forceinline__ void gemm_phase(PG8_LAS unsigned char* lds, const Gemm g, const Sched& S, const Epi& E) {
;     ...
;     for (;;) {
;         const bool has_next = S.next(ui + 1, nxt);
;         const char* nA = has_next ? (const char*)g.A + (size_t)nxt.pm * tstepA : cA; const char* nB = has_next ? (const char*)g.Bt + (size_t)nxt.pn * tstep : cB;
;         for (int t = 0; t < nt; t += 2) {
;             const bool last = (t == nt - 2);
;             if constexpr (Epi::RVLDS) { if (last) {
;                 const char* pg = (const char*)E.part_in + (size_t)cur.pm * 16384 + (size_t)tid * 16;
;                 __builtin_amdgcn_global_load_lds((const unsigned*)pg, (PG8_LAS unsigned*)(lds + STAGE_BYTES + ldsw), 16, 0, 0);
;                 __builtin_amdgcn_global_load_lds((const unsigned*)(pg + 8192), (PG8_LAS unsigned*)(lds + STAGE_BYTES + 8192 + ldsw), 16, 0, 0); } }
;             const bool plast = Epi::RVLDS && last;
;             const bool defer = Epi::SPLIT && (t == 0) && (ui > 0);
;             const char* a1 = cA + (size_t)(t + 1) * kstep;
;             const char* a2 = last ? nA : cA + (size_t)(t + 2) * kstep; const char* b2 = last ? nB : cB + (size_t)(t + 2) * kstep;
;             const char* a3 = a2 + kstep; const char* b3 = b2 + kstep;
;             if (last && has_next) S.a_ready(nxt);
;             if constexpr (SP2) {
;             PG8_LDB(B0, 0, 0); PG8_LDB(B1, 0, 1); PG8_SCHED; PG8_LDA(At, 0, 0); PG8_STAGE(PG8_SA(1, 1), a1 + hstepA, voffA);
;             if (plast) PG8_WAIT_V(10); else PG8_WAIT_SEL(defer, 12, 16);
;             PG8_WAIT_L(0); PG8_BAR; PG8_MMA(0, 0, At, B0); PG8_MMA(0, 1, At, B1);
.LBB0_462:
	s_andn2_b64 vcc, exec, s[18:19]
	s_cbranch_vccnz .Lzt_3
	s_add_u32 s24, s24, 0x80
	s_addc_u32 s25, s25, 0
	s_add_u32 s33, s26, 0x100
	v_mov_b32_e32 v0, 0
	s_addc_u32 s48, s27, 0
	s_mov_b32 s26, 0
	v_mov_b32_e32 v1, v0
	v_mov_b32_e32 v2, v0
	v_mov_b32_e32 v3, v0
	v_mov_b32_e32 v4, v0
	v_mov_b32_e32 v5, v0
	v_mov_b32_e32 v6, v0
	v_mov_b32_e32 v7, v0
	v_mov_b32_e32 v16, v0
	v_mov_b32_e32 v17, v0
	v_mov_b32_e32 v18, v0
	v_mov_b32_e32 v19, v0
	v_mov_b32_e32 v20, v0
	v_mov_b32_e32 v21, v0
	v_mov_b32_e32 v22, v0
	v_mov_b32_e32 v23, v0
	v_mov_b32_e32 v32, v0
	v_mov_b32_e32 v33, v0
	v_mov_b32_e32 v34, v0
	v_mov_b32_e32 v35, v0
	v_mov_b32_e32 v36, v0
	v_mov_b32_e32 v37, v0
	v_mov_b32_e32 v38, v0
	v_mov_b32_e32 v39, v0
	v_mov_b32_e32 v48, v0
	v_mov_b32_e32 v49, v0
	v_mov_b32_e32 v50, v0
	v_mov_b32_e32 v51, v0
	v_mov_b32_e32 v52, v0
	v_mov_b32_e32 v53, v0
	v_mov_b32_e32 v54, v0
	v_mov_b32_e32 v55, v0
	v_mov_b32_e32 v8, v0
	v_mov_b32_e32 v9, v0
	v_mov_b32_e32 v10, v0
	v_mov_b32_e32 v11, v0
	v_mov_b32_e32 v12, v0
	v_mov_b32_e32 v13, v0
	v_mov_b32_e32 v14, v0
	v_mov_b32_e32 v15, v0
	v_mov_b32_e32 v24, v0
	v_mov_b32_e32 v25, v0
	v_mov_b32_e32 v26, v0
	v_mov_b32_e32 v27, v0
	v_mov_b32_e32 v28, v0
	v_mov_b32_e32 v29, v0
	v_mov_b32_e32 v30, v0
	v_mov_b32_e32 v31, v0
	v_mov_b32_e32 v40, v0
	v_mov_b32_e32 v41, v0
	v_mov_b32_e32 v42, v0
	v_mov_b32_e32 v43, v0
	v_mov_b32_e32 v44, v0
	v_mov_b32_e32 v45, v0
	v_mov_b32_e32 v46, v0
	v_mov_b32_e32 v47, v0
	v_mov_b32_e32 v56, v0
	v_mov_b32_e32 v57, v0
	v_mov_b32_e32 v58, v0
	v_mov_b32_e32 v59, v0
	v_mov_b32_e32 v60, v0
	v_mov_b32_e32 v61, v0
	v_mov_b32_e32 v62, v0
	v_mov_b32_e32 v63, v0
	v_mov_b32_e32 v64, v0
	v_mov_b32_e32 v65, v0
	v_mov_b32_e32 v66, v0
	v_mov_b32_e32 v67, v0
	v_mov_b32_e32 v68, v0
	v_mov_b32_e32 v69, v0
	v_mov_b32_e32 v70, v0
	v_mov_b32_e32 v71, v0
	v_mov_b32_e32 v80, v0
	v_mov_b32_e32 v81, v0
	v_mov_b32_e32 v82, v0
	v_mov_b32_e32 v83, v0
	v_mov_b32_e32 v84, v0
	v_mov_b32_e32 v85, v0
	v_mov_b32_e32 v86, v0
	v_mov_b32_e32 v87, v0
	v_mov_b32_e32 v96, v0
	v_mov_b32_e32 v97, v0
	v_mov_b32_e32 v98, v0
	v_mov_b32_e32 v99, v0
	v_mov_b32_e32 v100, v0
	v_mov_b32_e32 v101, v0
	v_mov_b32_e32 v102, v0
	v_mov_b32_e32 v103, v0
	v_mov_b32_e32 v112, v0
	v_mov_b32_e32 v113, v0
	v_mov_b32_e32 v114, v0
	v_mov_b32_e32 v115, v0
	v_mov_b32_e32 v116, v0
	v_mov_b32_e32 v117, v0
	v_mov_b32_e32 v118, v0
	v_mov_b32_e32 v119, v0
	v_mov_b32_e32 v72, v0
	v_mov_b32_e32 v73, v0
	v_mov_b32_e32 v74, v0
	v_mov_b32_e32 v75, v0
	v_mov_b32_e32 v76, v0
	v_mov_b32_e32 v77, v0
	v_mov_b32_e32 v78, v0
	v_mov_b32_e32 v79, v0
	v_mov_b32_e32 v88, v0
	v_mov_b32_e32 v89, v0
	v_mov_b32_e32 v90, v0
	v_mov_b32_e32 v91, v0
	v_mov_b32_e32 v92, v0
	v_mov_b32_e32 v93, v0
	v_mov_b32_e32 v94, v0
	v_mov_b32_e32 v95, v0
	v_mov_b32_e32 v104, v0
	v_mov_b32_e32 v105, v0
	v_mov_b32_e32 v106, v0
	v_mov_b32_e32 v107, v0
	v_mov_b32_e32 v108, v0
	v_mov_b32_e32 v109, v0
	v_mov_b32_e32 v110, v0
	v_mov_b32_e32 v111, v0
	v_mov_b32_e32 v124, v0
	v_mov_b32_e32 v125, v0
	v_mov_b32_e32 v126, v0
	v_mov_b32_e32 v127, v0
	v_mov_b32_e32 v120, v0
	v_mov_b32_e32 v121, v0
	v_mov_b32_e32 v122, v0
	v_mov_b32_e32 v123, v0
.LBB0_464:
	s_add_i32 s49, s26, 2
	s_add_u32 s50, s24, 0x80
	s_addc_u32 s27, s25, 0
	s_add_i32 s52, 0, 0x10000
	s_cmp_eq_u32 s42, s26
	s_cselect_b32 s27, s9, s27
	s_cselect_b32 s26, s8, s50
	s_cselect_b32 s51, s23, s48
	s_cselect_b32 s50, s22, s33
	s_add_i32 s53, 0, 0x14000
	v_add_u32_e32 v154, s52, v140
	v_add_u32_e32 v170, s53, v140
	ds_read_b128 v[142:145], v154
	ds_read_b128 v[146:149], v154 offset:1024
	ds_read_b128 v[150:153], v154 offset:2048
	ds_read_b128 v[154:157], v154 offset:3072
	ds_read_b128 v[158:161], v170
	ds_read_b128 v[162:165], v170 offset:1024
	ds_read_b128 v[166:169], v170 offset:2048
	ds_read_b128 v[170:173], v170 offset:3072
	v_lshl_add_u64 v[190:191], s[24:25], 0, v[134:135]
	s_add_i32 m0, s34, 0xc000
	ds_read_b128 v[174:177], v141
	ds_read_b128 v[178:181], v141 offset:1024
	ds_read_b128 v[182:185], v141 offset:2048
	ds_read_b128 v[186:189], v141 offset:3072
	ds_read_b128 v[204:207], v141 offset:4096
	ds_read_b128 v[208:211], v141 offset:5120
	ds_read_b128 v[212:215], v141 offset:6144
	ds_read_b128 v[216:219], v141 offset:7168
	global_load_lds_dwordx4 v[190:191], off
	v_lshl_add_u64 v[190:191], s[24:25], 0, v[136:137]
	s_add_i32 m0, s34, 0xe000
	s_nop 0
	global_load_lds_dwordx4 v[190:191], off
	s_waitcnt vmcnt(8)
	s_waitcnt lgkmcnt(0)
	s_barrier
	s_setprio 1
	s_waitcnt lgkmcnt(0)
	v_mfma_f32_16x16x32_bf16 v[120:123], v[142:145], v[174:177], v[120:123]
	v_mfma_f32_16x16x32_bf16 v[124:127], v[150:153], v[174:177], v[124:127]
	v_mfma_f32_16x16x32_bf16 v[108:111], v[142:145], v[182:185], v[108:111]
	v_mfma_f32_16x16x32_bf16 v[104:107], v[150:153], v[182:185], v[104:107]
	v_mfma_f32_16x16x32_bf16 v[92:95], v[142:145], v[204:207], v[92:95]
	v_mfma_f32_16x16x32_bf16 v[88:91], v[150:153], v[204:207], v[88:91]
	v_mfma_f32_16x16x32_bf16 v[76:79], v[142:145], v[212:215], v[76:79]
	v_mfma_f32_16x16x32_bf16 v[72:75], v[150:153], v[212:215], v[72:75]
	v_mfma_f32_16x16x32_bf16 v[120:123], v[146:149], v[178:181], v[120:123]
	v_mfma_f32_16x16x32_bf16 v[124:127], v[154:157], v[178:181], v[124:127]
	v_mfma_f32_16x16x32_bf16 v[108:111], v[146:149], v[186:189], v[108:111]
	v_mfma_f32_16x16x32_bf16 v[104:107], v[154:157], v[186:189], v[104:107]
	v_mfma_f32_16x16x32_bf16 v[92:95], v[146:149], v[208:211], v[92:95]
	v_mfma_f32_16x16x32_bf16 v[88:91], v[154:157], v[208:211], v[88:91]
	v_mfma_f32_16x16x32_bf16 v[76:79], v[146:149], v[216:219], v[76:79]
	v_mfma_f32_16x16x32_bf16 v[72:75], v[154:157], v[216:219], v[72:75]
	s_setprio 0
	s_setprio 1
	v_mfma_f32_16x16x32_bf16 v[116:119], v[158:161], v[174:177], v[116:119]
	v_mfma_f32_16x16x32_bf16 v[112:115], v[166:169], v[174:177], v[112:115]
	v_mfma_f32_16x16x32_bf16 v[100:103], v[158:161], v[182:185], v[100:103]
	v_mfma_f32_16x16x32_bf16 v[96:99], v[166:169], v[182:185], v[96:99]
	v_mfma_f32_16x16x32_bf16 v[84:87], v[158:161], v[204:207], v[84:87]
	v_mfma_f32_16x16x32_bf16 v[80:83], v[166:169], v[204:207], v[80:83]
	v_mfma_f32_16x16x32_bf16 v[68:71], v[158:161], v[212:215], v[68:71]
	v_mfma_f32_16x16x32_bf16 v[64:67], v[166:169], v[212:215], v[64:67]
	v_mfma_f32_16x16x32_bf16 v[116:119], v[162:165], v[178:181], v[116:119]
	v_mfma_f32_16x16x32_bf16 v[112:115], v[170:173], v[178:181], v[112:115]
	v_mfma_f32_16x16x32_bf16 v[100:103], v[162:165], v[186:189], v[100:103]
	v_mfma_f32_16x16x32_bf16 v[96:99], v[170:173], v[186:189], v[96:99]
	v_mfma_f32_16x16x32_bf16 v[84:87], v[162:165], v[208:211], v[84:87]
	v_mfma_f32_16x16x32_bf16 v[80:83], v[170:173], v[208:211], v[80:83]
	v_mfma_f32_16x16x32_bf16 v[68:71], v[162:165], v[216:219], v[68:71]
	v_mfma_f32_16x16x32_bf16 v[64:67], v[170:173], v[216:219], v[64:67]
	s_setprio 0
	s_barrier
; #define PG8_STAGE(bufoff, gbase, voff) do { _Pragma("unroll") for (int _i = 0; _i < 2; ++_i) \
;         __builtin_amdgcn_global_load_lds((const unsigned*)((const char*)(gbase) + (voff)[_i]), (PG8_LAS unsigned*)(lds + (bufoff) + ldsw + _i * 8192), 16, 0, 0); } while (0)
; #define PG8_LDA(dst, b, h) do { _Pragma("unroll") for (int m = 0; m < 4; ++m) _Pragma("unroll") for (int k = 0; k < 2; ++k) dst[m][k] = *(const PG8_LAS bf16x8*)(lds + PG8_SA(b, h) + aoff + m * 2048 + k * 1024); } while (0)
; #define PG8_LDB(dst, b, h) do { _Pragma("unroll") for (int n = 0; n < 2; ++n) _Pragma("unroll") for (int k = 0; k < 2; ++k) dst[n][k] = *(const PG8_LAS bf16x8*)(lds + PG8_SB(b, h) + boff + n * 2048 + k * 1024); } while (0)
; #define PG8_MMA(ai, bj, At, Bt) do { __builtin_amdgcn_s_setprio(1); _Pragma("unroll") for (int m = 0; m < 4; ++m) _Pragma("unroll") for (int n = 0; n < 2; ++n) _Pragma("unroll") for (int k = 0; k < 2; ++k) \
;         acc[ai][bj][m][n] = __builtin_amdgcn_mfma_f32_16x16x32_bf16(Bt[n][k], At[m][k], acc[ai][bj][m][n], 0, 0, 0); __builtin_amdgcn_s_setprio(0); } while (0)
; #define PG8_WAIT_V(n) asm volatile("s_waitcnt vmcnt(" #n ")" ::: "memory")
; #define PG8_WAIT_L(n) asm volatile("s_waitcnt lgkmcnt(" #n ")" ::: "memory")
; #define PG8_BAR __builtin_amdgcn_s_barrier()
; template <class Epi, class Sched, bool ALIGN_EPI = false, bool SP2 = false>
; __device__ __forceinline__ void gemm_phase(PG8_LAS unsigned char* lds, const Gemm g, const Sched& S, const Epi& E) {
;     ...
;             PG8_WAIT_L(0); PG8_BAR; PG8_MMA(0, 0, At, B0); PG8_MMA(0, 1, At, B1);
;             if constexpr (Epi::SPLIT) { if (defer) {
;                 E.second(acc, prev, rv1, wr, wc, fr, fq);
;                 _Pragma("unroll") for (int b = 0; b < 2; ++b) _Pragma("unroll") for (int m = 0; m < 4; ++m) _Pragma("unroll") for (int n = 0; n < 2; ++n) acc[1][b][m][n] = (f32x4){0.f, 0.f, 0.f, 0.f}; } }
;             PG8_BAR; PG8_SCHED;
;             PG8_LDA(At, 0, 1); PG8_STAGE(PG8_SB(0, 0), b2, voffB); PG8_STAGE(PG8_SB(0, 1), b2 + hstep, voffB); PG8_STAGE(PG8_SA(0, 0), a2, voffA);
;             if (plast) PG8_WAIT_V(10); else PG8_WAIT_SEL(defer, 16, 24);
;             PG8_WAIT_L(0); PG8_BAR; PG8_MMA(1, 0, At, B0); PG8_MMA(1, 1, At, B1); PG8_BAR; PG8_SCHED;
;             PG8_LDB(B0, 1, 0); PG8_LDB(B1, 1, 1); PG8_SCHED; PG8_LDA(At, 1, 0); PG8_STAGE(PG8_SA(0, 1), a2 + hstepA, voffA);
	s_add_i32 s52, s52, s31
	v_lshl_add_u64 v[190:191], s[50:51], 0, v[192:193]
	s_mov_b32 m0, s52
	ds_read_b128 v[174:177], v141 offset:16384
	ds_read_b128 v[178:181], v141 offset:17408
	ds_read_b128 v[182:185], v141 offset:18432
	ds_read_b128 v[186:189], v141 offset:19456
	ds_read_b128 v[204:207], v141 offset:20480
	ds_read_b128 v[208:211], v141 offset:21504
	ds_read_b128 v[212:215], v141 offset:22528
	ds_read_b128 v[216:219], v141 offset:23552
	global_load_lds_dwordx4 v[190:191], off
	s_add_i32 m0, s52, 0x2000
	v_lshl_add_u64 v[194:195], s[50:51], 0, v[128:129]
	s_add_u32 s50, s50, s12
	s_addc_u32 s51, s51, s13
	s_add_i32 s52, s53, s31
	global_load_lds_dwordx4 v[194:195], off
	v_lshl_add_u64 v[200:201], s[50:51], 0, v[192:193]
	s_mov_b32 m0, s52
	v_lshl_add_u64 v[202:203], s[50:51], 0, v[128:129]
	global_load_lds_dwordx4 v[200:201], off
	s_add_i32 m0, s52, 0x2000
	v_lshl_add_u64 v[220:221], s[26:27], 0, v[132:133]
	global_load_lds_dwordx4 v[202:203], off
	s_mov_b32 m0, s34
	v_lshl_add_u64 v[222:223], s[26:27], 0, v[130:131]
	global_load_lds_dwordx4 v[220:221], off
	s_mov_b32 m0, s35
	s_nop 0
	global_load_lds_dwordx4 v[222:223], off
	s_waitcnt vmcnt(8)
	s_waitcnt lgkmcnt(0)
	s_barrier
	s_setprio 1
	s_waitcnt lgkmcnt(0)
	v_mfma_f32_16x16x32_bf16 v[60:63], v[142:145], v[174:177], v[60:63]
	v_mfma_f32_16x16x32_bf16 v[56:59], v[150:153], v[174:177], v[56:59]
	v_mfma_f32_16x16x32_bf16 v[44:47], v[142:145], v[182:185], v[44:47]
	v_mfma_f32_16x16x32_bf16 v[40:43], v[150:153], v[182:185], v[40:43]
	v_mfma_f32_16x16x32_bf16 v[28:31], v[142:145], v[204:207], v[28:31]
	v_mfma_f32_16x16x32_bf16 v[24:27], v[150:153], v[204:207], v[24:27]
	v_mfma_f32_16x16x32_bf16 v[12:15], v[142:145], v[212:215], v[12:15]
	v_mfma_f32_16x16x32_bf16 v[8:11], v[150:153], v[212:215], v[8:11]
	v_mfma_f32_16x16x32_bf16 v[60:63], v[146:149], v[178:181], v[60:63]
	v_mfma_f32_16x16x32_bf16 v[56:59], v[154:157], v[178:181], v[56:59]
	v_mfma_f32_16x16x32_bf16 v[44:47], v[146:149], v[186:189], v[44:47]
	v_mfma_f32_16x16x32_bf16 v[40:43], v[154:157], v[186:189], v[40:43]
	v_mfma_f32_16x16x32_bf16 v[28:31], v[146:149], v[208:211], v[28:31]
	v_mfma_f32_16x16x32_bf16 v[24:27], v[154:157], v[208:211], v[24:27]
	v_mfma_f32_16x16x32_bf16 v[12:15], v[146:149], v[216:219], v[12:15]
	v_mfma_f32_16x16x32_bf16 v[8:11], v[154:157], v[216:219], v[8:11]
	s_setprio 0
	s_setprio 1
	v_mfma_f32_16x16x32_bf16 v[52:55], v[158:161], v[174:177], v[52:55]
	v_mfma_f32_16x16x32_bf16 v[48:51], v[166:169], v[174:177], v[48:51]
	v_mfma_f32_16x16x32_bf16 v[36:39], v[158:161], v[182:185], v[36:39]
	v_mfma_f32_16x16x32_bf16 v[32:35], v[166:169], v[182:185], v[32:35]
	v_mfma_f32_16x16x32_bf16 v[20:23], v[158:161], v[204:207], v[20:23]
	v_mfma_f32_16x16x32_bf16 v[16:19], v[166:169], v[204:207], v[16:19]
	v_mfma_f32_16x16x32_bf16 v[4:7], v[158:161], v[212:215], v[4:7]
	v_mfma_f32_16x16x32_bf16 v[0:3], v[166:169], v[212:215], v[0:3]
	v_mfma_f32_16x16x32_bf16 v[52:55], v[162:165], v[178:181], v[52:55]
	v_mfma_f32_16x16x32_bf16 v[48:51], v[170:173], v[178:181], v[48:51]
	v_mfma_f32_16x16x32_bf16 v[36:39], v[162:165], v[186:189], v[36:39]
	v_mfma_f32_16x16x32_bf16 v[32:35], v[170:173], v[186:189], v[32:35]
	v_mfma_f32_16x16x32_bf16 v[20:23], v[162:165], v[208:211], v[20:23]
	v_mfma_f32_16x16x32_bf16 v[16:19], v[170:173], v[208:211], v[16:19]
	v_mfma_f32_16x16x32_bf16 v[4:7], v[162:165], v[216:219], v[4:7]
	v_mfma_f32_16x16x32_bf16 v[0:3], v[170:173], v[216:219], v[0:3]
	s_setprio 0
	s_barrier
	s_add_i32 s50, 0, 0x18000
	s_add_i32 s51, 0, 0x1c000
	v_add_u32_e32 v154, s50, v140
	v_add_u32_e32 v170, s51, v140
	ds_read_b128 v[142:145], v154
	ds_read_b128 v[146:149], v154 offset:1024
	ds_read_b128 v[150:153], v154 offset:2048
	ds_read_b128 v[154:157], v154 offset:3072
	ds_read_b128 v[158:161], v170
	ds_read_b128 v[162:165], v170 offset:1024
	ds_read_b128 v[166:169], v170 offset:2048
	ds_read_b128 v[170:173], v170 offset:3072
	s_add_u32 s26, s26, s0
	s_addc_u32 s27, s27, s1
	s_mov_b32 m0, s36
	v_lshl_add_u64 v[224:225], s[26:27], 0, v[132:133]
	ds_read_b128 v[174:177], v141 offset:32768
	ds_read_b128 v[178:181], v141 offset:33792
	ds_read_b128 v[182:185], v141 offset:34816
	ds_read_b128 v[186:189], v141 offset:35840
	ds_read_b128 v[204:207], v141 offset:36864
	ds_read_b128 v[208:211], v141 offset:37888
	ds_read_b128 v[212:215], v141 offset:38912
	ds_read_b128 v[216:219], v141 offset:39936
	global_load_lds_dwordx4 v[224:225], off
	v_lshl_add_u64 v[224:225], s[26:27], 0, v[130:131]
	s_mov_b32 m0, s37
	s_nop 0
	global_load_lds_dwordx4 v[224:225], off
	s_waitcnt vmcnt(8)
	s_waitcnt lgkmcnt(0)
	s_barrier
; #define PG8_STAGE(bufoff, gbase, voff) do { _Pragma("unroll") for (int _i = 0; _i < 2; ++_i) \
;         __builtin_amdgcn_global_load_lds((const unsigned*)((const char*)(gbase) + (voff)[_i]), (PG8_LAS unsigned*)(lds + (bufoff) + ldsw + _i * 8192), 16, 0, 0); } while (0)
; #define PG8_LDA(dst, b, h) do { _Pragma("unroll") for (int m = 0; m < 4; ++m) _Pragma("unroll") for (int k = 0; k < 2; ++k) dst[m][k] = *(const PG8_LAS bf16x8*)(lds + PG8_SA(b, h) + aoff + m * 2048 + k * 1024); } while (0)
; #define PG8_LDB(dst, b, h) do { _Pragma("unroll") for (int n = 0; n < 2; ++n) _Pragma("unroll") for (int k = 0; k < 2; ++k) dst[n][k] = *(const PG8_LAS bf16x8*)(lds + PG8_SB(b, h) + boff + n * 2048 + k * 1024); } while (0)
; #define PG8_MMA(ai, bj, At, Bt) do { __builtin_amdgcn_s_setprio(1); _Pragma("unroll") for (int m = 0; m < 4; ++m) _Pragma("unroll") for (int n = 0; n < 2; ++n) _Pragma("unroll") for (int k = 0; k < 2; ++k) \
;         acc[ai][bj][m][n] = __builtin_amdgcn_mfma_f32_16x16x32_bf16(Bt[n][k], At[m][k], acc[ai][bj][m][n], 0, 0, 0); __builtin_amdgcn_s_setprio(0); } while (0)
; #define PG8_WAIT_V(n) asm volatile("s_waitcnt vmcnt(" #n ")" ::: "memory")
; #define PG8_WAIT_SEL(d, w4, w8) do { if constexpr (Epi::SPLIT) { if (d) { if constexpr (Epi::NSH == 4) PG8_WAIT_V(w4); else PG8_WAIT_V(w8); } else PG8_WAIT_V(8); } else PG8_WAIT_V(8); } while (0)
; #define PG8_WAIT_L(n) asm volatile("s_waitcnt lgkmcnt(" #n ")" ::: "memory")
; #define PG8_BAR __builtin_amdgcn_s_barrier()
; #define PG8_SCHED __builtin_amdgcn_sched_barrier(0)
; template <class Epi, class Sched, bool ALIGN_EPI = false, bool SP2 = false>
; __device__ __forceinline__ void gemm_phase(PG8_LAS unsigned char* lds, const Gemm g, const Sched& S, const Epi& E) {
;     ...
;             PG8_LDB(B0, 1, 0); PG8_LDB(B1, 1, 1); PG8_SCHED; PG8_LDA(At, 1, 0); PG8_STAGE(PG8_SA(0, 1), a2 + hstepA, voffA);
;             PG8_WAIT_SEL(defer, 12, 16); PG8_WAIT_L(0); PG8_BAR; PG8_MMA(0, 0, At, B0); PG8_MMA(0, 1, At, B1); PG8_BAR; PG8_SCHED;
;             PG8_LDA(At, 1, 1); PG8_STAGE(PG8_SB(1, 0), b3, voffB); PG8_STAGE(PG8_SB(1, 1), b3 + hstep, voffB); PG8_STAGE(PG8_SA(1, 0), a3, voffA);
;             PG8_WAIT_V(8); PG8_WAIT_L(0); PG8_BAR; PG8_MMA(1, 0, At, B0); PG8_MMA(1, 1, At, B1); PG8_BAR; PG8_SCHED;
	s_setprio 1
	s_waitcnt lgkmcnt(0)
	v_mfma_f32_16x16x32_bf16 v[120:123], v[142:145], v[174:177], v[120:123]
	v_mfma_f32_16x16x32_bf16 v[124:127], v[150:153], v[174:177], v[124:127]
	v_mfma_f32_16x16x32_bf16 v[108:111], v[142:145], v[182:185], v[108:111]
	v_mfma_f32_16x16x32_bf16 v[104:107], v[150:153], v[182:185], v[104:107]
	v_mfma_f32_16x16x32_bf16 v[92:95], v[142:145], v[204:207], v[92:95]
	v_mfma_f32_16x16x32_bf16 v[88:91], v[150:153], v[204:207], v[88:91]
	v_mfma_f32_16x16x32_bf16 v[76:79], v[142:145], v[212:215], v[76:79]
	v_mfma_f32_16x16x32_bf16 v[72:75], v[150:153], v[212:215], v[72:75]
	v_mfma_f32_16x16x32_bf16 v[120:123], v[146:149], v[178:181], v[120:123]
	v_mfma_f32_16x16x32_bf16 v[124:127], v[154:157], v[178:181], v[124:127]
	v_mfma_f32_16x16x32_bf16 v[108:111], v[146:149], v[186:189], v[108:111]
	v_mfma_f32_16x16x32_bf16 v[104:107], v[154:157], v[186:189], v[104:107]
	v_mfma_f32_16x16x32_bf16 v[92:95], v[146:149], v[208:211], v[92:95]
	v_mfma_f32_16x16x32_bf16 v[88:91], v[154:157], v[208:211], v[88:91]
	v_mfma_f32_16x16x32_bf16 v[76:79], v[146:149], v[216:219], v[76:79]
	v_mfma_f32_16x16x32_bf16 v[72:75], v[154:157], v[216:219], v[72:75]
	s_setprio 0
	s_setprio 1
	v_mfma_f32_16x16x32_bf16 v[116:119], v[158:161], v[174:177], v[116:119]
	v_mfma_f32_16x16x32_bf16 v[112:115], v[166:169], v[174:177], v[112:115]
	v_mfma_f32_16x16x32_bf16 v[100:103], v[158:161], v[182:185], v[100:103]
	v_mfma_f32_16x16x32_bf16 v[96:99], v[166:169], v[182:185], v[96:99]
	v_mfma_f32_16x16x32_bf16 v[84:87], v[158:161], v[204:207], v[84:87]
	v_mfma_f32_16x16x32_bf16 v[80:83], v[166:169], v[204:207], v[80:83]
	v_mfma_f32_16x16x32_bf16 v[68:71], v[158:161], v[212:215], v[68:71]
	v_mfma_f32_16x16x32_bf16 v[64:67], v[166:169], v[212:215], v[64:67]
	v_mfma_f32_16x16x32_bf16 v[116:119], v[162:165], v[178:181], v[116:119]
	v_mfma_f32_16x16x32_bf16 v[112:115], v[170:173], v[178:181], v[112:115]
	v_mfma_f32_16x16x32_bf16 v[100:103], v[162:165], v[186:189], v[100:103]
	v_mfma_f32_16x16x32_bf16 v[96:99], v[170:173], v[186:189], v[96:99]
	v_mfma_f32_16x16x32_bf16 v[84:87], v[162:165], v[208:211], v[84:87]
	v_mfma_f32_16x16x32_bf16 v[80:83], v[170:173], v[208:211], v[80:83]
	v_mfma_f32_16x16x32_bf16 v[68:71], v[162:165], v[216:219], v[68:71]
	v_mfma_f32_16x16x32_bf16 v[64:67], v[170:173], v[216:219], v[64:67]
	s_setprio 0
	s_barrier
	s_add_i32 s26, s50, s31
	v_lshl_add_u64 v[190:191], v[190:191], 0, s[90:91]
	s_mov_b32 m0, s26
	ds_read_b128 v[174:177], v141 offset:49152
	ds_read_b128 v[178:181], v141 offset:50176
	ds_read_b128 v[182:185], v141 offset:51200
	ds_read_b128 v[186:189], v141 offset:52224
	ds_read_b128 v[204:207], v141 offset:53248
	ds_read_b128 v[208:211], v141 offset:54272
	ds_read_b128 v[212:215], v141 offset:55296
	ds_read_b128 v[216:219], v141 offset:56320
	global_load_lds_dwordx4 v[190:191], off
	v_lshl_add_u64 v[190:191], v[194:195], 0, s[90:91]
	s_add_i32 m0, s26, 0x2000
	s_add_i32 s26, s51, s31
	global_load_lds_dwordx4 v[190:191], off
	v_lshl_add_u64 v[190:191], v[200:201], 0, s[90:91]
	s_mov_b32 m0, s26
	s_nop 0
	global_load_lds_dwordx4 v[190:191], off
	v_lshl_add_u64 v[190:191], v[202:203], 0, s[90:91]
	s_add_i32 m0, s26, 0x2000
	s_nop 0
	global_load_lds_dwordx4 v[190:191], off
	v_lshl_add_u64 v[190:191], v[220:221], 0, s[90:91]
	s_mov_b32 m0, s40
	s_nop 0
	global_load_lds_dwordx4 v[190:191], off
	v_lshl_add_u64 v[190:191], v[222:223], 0, s[90:91]
	s_mov_b32 m0, s41
	s_nop 0
	global_load_lds_dwordx4 v[190:191], off
	s_waitcnt vmcnt(8)
	s_waitcnt lgkmcnt(0)
	s_barrier
	s_setprio 1
	s_waitcnt lgkmcnt(0)
	v_mfma_f32_16x16x32_bf16 v[60:63], v[142:145], v[174:177], v[60:63]
	v_mfma_f32_16x16x32_bf16 v[56:59], v[150:153], v[174:177], v[56:59]
	v_mfma_f32_16x16x32_bf16 v[44:47], v[142:145], v[182:185], v[44:47]
	v_mfma_f32_16x16x32_bf16 v[40:43], v[150:153], v[182:185], v[40:43]
	v_mfma_f32_16x16x32_bf16 v[28:31], v[142:145], v[204:207], v[28:31]
	v_mfma_f32_16x16x32_bf16 v[24:27], v[150:153], v[204:207], v[24:27]
	v_mfma_f32_16x16x32_bf16 v[12:15], v[142:145], v[212:215], v[12:15]
	v_mfma_f32_16x16x32_bf16 v[8:11], v[150:153], v[212:215], v[8:11]
	v_mfma_f32_16x16x32_bf16 v[60:63], v[146:149], v[178:181], v[60:63]
	v_mfma_f32_16x16x32_bf16 v[56:59], v[154:157], v[178:181], v[56:59]
	v_mfma_f32_16x16x32_bf16 v[44:47], v[146:149], v[186:189], v[44:47]
	v_mfma_f32_16x16x32_bf16 v[40:43], v[154:157], v[186:189], v[40:43]
	v_mfma_f32_16x16x32_bf16 v[28:31], v[146:149], v[208:211], v[28:31]
	v_mfma_f32_16x16x32_bf16 v[24:27], v[154:157], v[208:211], v[24:27]
	v_mfma_f32_16x16x32_bf16 v[12:15], v[146:149], v[216:219], v[12:15]
	v_mfma_f32_16x16x32_bf16 v[8:11], v[154:157], v[216:219], v[8:11]
	s_setprio 0
	s_setprio 1
	v_mfma_f32_16x16x32_bf16 v[52:55], v[158:161], v[174:177], v[52:55]
	v_mfma_f32_16x16x32_bf16 v[48:51], v[166:169], v[174:177], v[48:51]
	v_mfma_f32_16x16x32_bf16 v[36:39], v[158:161], v[182:185], v[36:39]
	v_mfma_f32_16x16x32_bf16 v[32:35], v[166:169], v[182:185], v[32:35]
	v_mfma_f32_16x16x32_bf16 v[20:23], v[158:161], v[204:207], v[20:23]
	v_mfma_f32_16x16x32_bf16 v[16:19], v[166:169], v[204:207], v[16:19]
	v_mfma_f32_16x16x32_bf16 v[4:7], v[158:161], v[212:215], v[4:7]
	v_mfma_f32_16x16x32_bf16 v[0:3], v[166:169], v[212:215], v[0:3]
	v_mfma_f32_16x16x32_bf16 v[52:55], v[162:165], v[178:181], v[52:55]
	v_mfma_f32_16x16x32_bf16 v[48:51], v[170:173], v[178:181], v[48:51]
	v_mfma_f32_16x16x32_bf16 v[36:39], v[162:165], v[186:189], v[36:39]
	v_mfma_f32_16x16x32_bf16 v[32:35], v[170:173], v[186:189], v[32:35]
	v_mfma_f32_16x16x32_bf16 v[20:23], v[162:165], v[208:211], v[20:23]
	v_mfma_f32_16x16x32_bf16 v[16:19], v[170:173], v[208:211], v[16:19]
	v_mfma_f32_16x16x32_bf16 v[4:7], v[162:165], v[216:219], v[4:7]
	v_mfma_f32_16x16x32_bf16 v[0:3], v[170:173], v[216:219], v[0:3]
	s_setprio 0
	s_barrier
	s_add_u32 s24, s24, 0x100
	s_addc_u32 s25, s25, 0
	s_add_u32 s33, s33, 0x100
	s_addc_u32 s48, s48, 0
	s_cmp_ge_i32 s49, s38
	s_mov_b32 s26, s49
	s_cbranch_scc0 .LBB0_464

; __device__ __forceinline__ unsigned cvt_pk_bf16(float lo, float hi) { unsigned r; asm volatile("v_cvt_pk_bf16_f32 %0, %1, %2" : "=v"(r) : "v"(lo), "v"(hi)); return r; }
;     __device__ __forceinline__ void operator()(const f32x4 (&acc)[2][2][4][2], const pg8::Unit& u, int wr, int wc, int fr_, int fq_, LAS const unsigned char* xl) const {
;     ...
;                     const int row = row0 + ai * 128 + m * 16;
;                     const float rinv = (MODE == 2) ? 1.f : rv[ai][m];
;                     if (MODE == 0 || MODE == 2) {
;                         bf16_t* rowp = O + (size_t)row * ldc + u.pn * 256 + wc * 32 + 8 * fq;
; #pragma unroll
;                         for (int bj = 0; bj < 2; ++bj) { const f32x4 v0 = acc[ai][bj][m][0] * rinv, v1 = acc[ai][bj][m][1] * rinv;
;                             u32x4 w; w.x = pg8::cvt_pk_bf16(v0[0], v0[1]); w.y = pg8::cvt_pk_bf16(v0[2], v0[3]); w.z = pg8::cvt_pk_bf16(v1[0], v1[1]); w.w = pg8::cvt_pk_bf16(v1[2], v1[3]);
;                             *(u32x4*)(rowp + bj * 128) = w; }
; __device__ __forceinline__ void group_wait(unsigned* ctr, unsigned gen) {
;     int tid_l = threadIdx.x; asm volatile("" : "+v"(tid_l));
;     if (tid_l == 0) {
;         while (__hip_atomic_load(ctr, __ATOMIC_RELAXED, __HIP_MEMORY_SCOPE_AGENT) < gen) __builtin_amdgcn_s_sleep(2);
;         __builtin_amdgcn_fence(__ATOMIC_ACQUIRE, "agent");
;         asm volatile("s_waitcnt vmcnt(0)" ::: "memory");
.LBB0_467:
	v_mov_b32_e32 v142, v138
	v_mov_b32_e32 v143, v139
	s_lshl_b32 s24, s47, 8
	s_add_i32 s24, s24, s39
	v_add_u32_e32 v142, s24, v142
	v_lshlrev_b32_e32 v144, 3, v143
	v_ashrrev_i32_e32 v143, 31, v142
	s_lshl_b32 s24, s46, 8
	v_lshlrev_b64 v[142:143], 11, v[142:143]
	s_ashr_i32 s25, s24, 31
	v_lshl_add_u64 v[142:143], s[74:75], 0, v[142:143]
	v_lshl_add_u64 v[142:143], s[24:25], 1, v[142:143]
	v_ashrrev_i32_e32 v145, 31, v144
	v_lshl_add_u64 v[142:143], v[142:143], 0, s[86:87]
	v_lshl_add_u64 v[142:143], v[144:145], 1, v[142:143]
	s_mov_b64 s[24:25], 0x8000
	v_cvt_pk_bf16_f32 v120, v120, v121
	v_cvt_pk_bf16_f32 v121, v122, v123
	v_cvt_pk_bf16_f32 v122, v124, v125
	v_cvt_pk_bf16_f32 v123, v126, v127
	global_store_dwordx4 v[142:143], v[120:123], off
	v_cvt_pk_bf16_f32 v116, v116, v117
	v_cvt_pk_bf16_f32 v117, v118, v119
	v_cvt_pk_bf16_f32 v118, v112, v113
	v_lshl_add_u64 v[112:113], v[142:143], 0, s[24:25]
	s_mov_b32 s24, 0x8000
	v_cvt_pk_bf16_f32 v119, v114, v115
	global_store_dwordx4 v[142:143], v[116:119], off offset:256
	v_cvt_pk_bf16_f32 v108, v108, v109
	v_cvt_pk_bf16_f32 v109, v110, v111
	v_cvt_pk_bf16_f32 v110, v104, v105
	v_add_co_u32_e32 v104, vcc, s24, v142
	s_mov_b64 s[24:25], 0x10000
	s_nop 0
	v_addc_co_u32_e32 v105, vcc, 0, v143, vcc
	v_cvt_pk_bf16_f32 v111, v106, v107
	global_store_dwordx4 v[104:105], v[108:111], off
	v_cvt_pk_bf16_f32 v100, v100, v101
	v_cvt_pk_bf16_f32 v101, v102, v103
	v_cvt_pk_bf16_f32 v102, v96, v97
	v_lshl_add_u64 v[96:97], v[142:143], 0, s[24:25]
	s_mov_b32 s24, 0x10000
	v_cvt_pk_bf16_f32 v103, v98, v99
	global_store_dwordx4 v[112:113], v[100:103], off offset:256
	v_cvt_pk_bf16_f32 v92, v92, v93
	v_cvt_pk_bf16_f32 v93, v94, v95
	v_cvt_pk_bf16_f32 v94, v88, v89
	v_add_co_u32_e32 v88, vcc, s24, v142
	v_cvt_pk_bf16_f32 v95, v90, v91
	s_mov_b64 s[24:25], 0x18000
	s_nop 0
	v_addc_co_u32_e32 v89, vcc, 0, v143, vcc
	global_store_dwordx4 v[88:89], v[92:95], off
	v_cvt_pk_bf16_f32 v84, v84, v85
	v_cvt_pk_bf16_f32 v85, v86, v87
	v_cvt_pk_bf16_f32 v86, v80, v81
	v_cvt_pk_bf16_f32 v87, v82, v83
	global_store_dwordx4 v[96:97], v[84:87], off offset:256
	v_cvt_pk_bf16_f32 v76, v76, v77
	v_cvt_pk_bf16_f32 v77, v78, v79
	v_cvt_pk_bf16_f32 v78, v72, v73
	v_add_co_u32_e32 v72, vcc, s3, v142
	v_lshl_add_u64 v[80:81], v[142:143], 0, s[24:25]
	s_nop 0
	v_addc_co_u32_e32 v73, vcc, 0, v143, vcc
	s_mov_b64 s[24:25], 0x40000
	v_cvt_pk_bf16_f32 v79, v74, v75
	global_store_dwordx4 v[72:73], v[76:79], off
	v_cvt_pk_bf16_f32 v68, v68, v69
	v_cvt_pk_bf16_f32 v69, v70, v71
	v_cvt_pk_bf16_f32 v70, v64, v65
	v_lshl_add_u64 v[64:65], v[142:143], 0, s[24:25]
	s_mov_b32 s24, 0x40000
	v_cvt_pk_bf16_f32 v71, v66, v67
	global_store_dwordx4 v[80:81], v[68:71], off offset:256
	v_cvt_pk_bf16_f32 v60, v60, v61
	v_cvt_pk_bf16_f32 v61, v62, v63
	v_cvt_pk_bf16_f32 v62, v56, v57
	v_add_co_u32_e32 v56, vcc, s24, v142
	v_cvt_pk_bf16_f32 v63, v58, v59
	s_mov_b64 s[24:25], 0x48000
	s_nop 0
	v_addc_co_u32_e32 v57, vcc, 0, v143, vcc
	global_store_dwordx4 v[56:57], v[60:63], off
	v_cvt_pk_bf16_f32 v52, v52, v53
	v_cvt_pk_bf16_f32 v53, v54, v55
	v_cvt_pk_bf16_f32 v54, v48, v49
	v_cvt_pk_bf16_f32 v55, v50, v51
	global_store_dwordx4 v[64:65], v[52:55], off offset:256
	v_cvt_pk_bf16_f32 v44, v44, v45
	v_cvt_pk_bf16_f32 v45, v46, v47
	v_cvt_pk_bf16_f32 v46, v40, v41
	v_add_co_u32_e32 v40, vcc, s79, v142
	v_lshl_add_u64 v[48:49], v[142:143], 0, s[24:25]
	s_nop 0
	v_addc_co_u32_e32 v41, vcc, 0, v143, vcc
	s_mov_b64 s[24:25], 0x50000
	v_cvt_pk_bf16_f32 v47, v42, v43
	global_store_dwordx4 v[40:41], v[44:47], off
	v_cvt_pk_bf16_f32 v36, v36, v37
	v_cvt_pk_bf16_f32 v37, v38, v39
	v_cvt_pk_bf16_f32 v38, v32, v33
	v_lshl_add_u64 v[32:33], v[142:143], 0, s[24:25]
	s_mov_b32 s24, 0x50000
	v_cvt_pk_bf16_f32 v39, v34, v35
	global_store_dwordx4 v[48:49], v[36:39], off offset:256
	v_cvt_pk_bf16_f32 v28, v28, v29
	v_cvt_pk_bf16_f32 v29, v30, v31
	v_cvt_pk_bf16_f32 v30, v24, v25
	v_add_co_u32_e32 v24, vcc, s24, v142
	v_cvt_pk_bf16_f32 v31, v26, v27
	s_mov_b64 s[24:25], 0x58000
	s_nop 0
	v_addc_co_u32_e32 v25, vcc, 0, v143, vcc
	global_store_dwordx4 v[24:25], v[28:31], off
	v_cvt_pk_bf16_f32 v20, v20, v21
	v_cvt_pk_bf16_f32 v21, v22, v23
	v_cvt_pk_bf16_f32 v22, v16, v17
	v_cvt_pk_bf16_f32 v23, v18, v19
	global_store_dwordx4 v[32:33], v[20:23], off offset:256
	v_cvt_pk_bf16_f32 v12, v12, v13
	v_cvt_pk_bf16_f32 v13, v14, v15
	v_cvt_pk_bf16_f32 v14, v8, v9
	v_add_co_u32_e32 v8, vcc, 0x58000, v142
	v_lshl_add_u64 v[16:17], v[142:143], 0, s[24:25]
	s_nop 0
	v_addc_co_u32_e32 v9, vcc, 0, v143, vcc
	s_and_b64 vcc, exec, s[6:7]
	s_mov_b64 s[6:7], -1
	v_cvt_pk_bf16_f32 v15, v10, v11
	global_store_dwordx4 v[8:9], v[12:15], off
	v_cvt_pk_bf16_f32 v4, v4, v5
	v_cvt_pk_bf16_f32 v5, v6, v7
	v_cvt_pk_bf16_f32 v6, v0, v1
	v_cvt_pk_bf16_f32 v7, v2, v3
	global_store_dwordx4 v[16:17], v[4:7], off offset:256
	s_cbranch_vccnz .LBB0_451
	s_andn2_b64 vcc, exec, s[16:17]
	s_cbranch_vccnz .LBB0_450
	s_barrier
	s_branch .LBB0_450
.LBB0_470:
	s_waitcnt vmcnt(0)
	s_barrier
.LBB0_471:
	s_andn2_b64 vcc, exec, s[62:63]
	s_cbranch_vccnz .LBB0_477
	v_mov_b32_e32 v0, v232
	s_nop 0
	v_cmp_eq_u32_e32 vcc, 0, v0
	s_and_saveexec_b64 s[0:1], vcc
	s_cbranch_execz .LBB0_476
	v_readlane_b32 s6, v254, 26
	v_readlane_b32 s7, v254, 27
	v_readlane_b32 s2, v254, 49
	s_nop 3
	global_load_dword v0, v193, s[6:7] sc1
	s_waitcnt vmcnt(0)
	v_cmp_le_u32_e32 vcc, s2, v0
	s_cbranch_vccnz .LBB0_475

; #define PG8_LAS __attribute__((address_space(3)))
; #define PG8_STAGE(bufoff, gbase, voff) do { _Pragma("unroll") for (int _i = 0; _i < 2; ++_i) \
;         __builtin_amdgcn_global_load_lds((const unsigned*)((const char*)(gbase) + (voff)[_i]), (PG8_LAS unsigned*)(lds + (bufoff) + ldsw + _i * 8192), 16, 0, 0); } while (0)
; #define PG8_LDA(dst, b, h) do { _Pragma("unroll") for (int m = 0; m < 4; ++m) _Pragma("unroll") for (int k = 0; k < 2; ++k) dst[m][k] = *(const PG8_LAS bf16x8*)(lds + PG8_SA(b, h) + aoff + m * 2048 + k * 1024); } while (0)
; #define PG8_WAIT_V(n) asm volatile("s_waitcnt vmcnt(" #n ")" ::: "memory")
; #define PG8_BAR __builtin_amdgcn_s_barrier()
; template <class Epi, class Sched, bool ALIGN_EPI = false, bool SP2 = false>
; __device__ __forceinline__ void gemm_phase(PG8_LAS unsigned char* lds, const Gemm g, const Sched& S, const Epi& E) {
;     ...
;     for (;;) {
;         const bool has_next = S.next(ui + 1, nxt);
;         const char* nA = has_next ? (const char*)g.A + (size_t)nxt.pm * tstepA : cA; const char* nB = has_next ? (const char*)g.Bt + (size_t)nxt.pn * tstep : cB;
;         for (int t = 0; t < nt; t += 2) {
;             const bool last = (t == nt - 2);
;             if constexpr (Epi::RVLDS) { if (last) {
;                 const char* pg = (const char*)E.part_in + (size_t)cur.pm * 16384 + (size_t)tid * 16;
;                 __builtin_amdgcn_global_load_lds((const unsigned*)pg, (PG8_LAS unsigned*)(lds + STAGE_BYTES + ldsw), 16, 0, 0);
;                 __builtin_amdgcn_global_load_lds((const unsigned*)(pg + 8192), (PG8_LAS unsigned*)(lds + STAGE_BYTES + 8192 + ldsw), 16, 0, 0); } }
;             const bool plast = Epi::RVLDS && last;
;             const bool defer = Epi::SPLIT && (t == 0) && (ui > 0);
;             const char* a1 = cA + (size_t)(t + 1) * kstep;
;             const char* a2 = last ? nA : cA + (size_t)(t + 2) * kstep; const char* b2 = last ? nB : cB + (size_t)(t + 2) * kstep;
;             const char* a3 = a2 + kstep; const char* b3 = b2 + kstep;
;             if (last && has_next) S.a_ready(nxt);
;             if constexpr (SP2) {
;             PG8_LDB(B0, 0, 0); PG8_LDB(B1, 0, 1); PG8_SCHED; PG8_LDA(At, 0, 0); PG8_STAGE(PG8_SA(1, 1), a1 + hstepA, voffA);
;             if (plast) PG8_WAIT_V(10); else PG8_WAIT_SEL(defer, 12, 16);
;             PG8_WAIT_L(0); PG8_BAR; PG8_MMA(0, 0, At, B0); PG8_MMA(0, 1, At, B1);
.LBB0_495:
	s_andn2_b64 vcc, exec, s[20:21]
	s_cbranch_vccnz .Lzt_4
	s_add_u32 s0, s0, 0x80
	s_addc_u32 s1, s1, 0
	s_add_u32 s33, s26, 0x100
	v_mov_b32_e32 v0, 0
	s_addc_u32 s48, s27, 0
	s_mov_b32 s26, 0
	v_mov_b32_e32 v1, v0
	v_mov_b32_e32 v2, v0
	v_mov_b32_e32 v3, v0
	v_mov_b32_e32 v4, v0
	v_mov_b32_e32 v5, v0
	v_mov_b32_e32 v6, v0
	v_mov_b32_e32 v7, v0
	v_mov_b32_e32 v16, v0
	v_mov_b32_e32 v17, v0
	v_mov_b32_e32 v18, v0
	v_mov_b32_e32 v19, v0
	v_mov_b32_e32 v20, v0
	v_mov_b32_e32 v21, v0
	v_mov_b32_e32 v22, v0
	v_mov_b32_e32 v23, v0
	v_mov_b32_e32 v32, v0
	v_mov_b32_e32 v33, v0
	v_mov_b32_e32 v34, v0
	v_mov_b32_e32 v35, v0
	v_mov_b32_e32 v36, v0
	v_mov_b32_e32 v37, v0
	v_mov_b32_e32 v38, v0
	v_mov_b32_e32 v39, v0
	v_mov_b32_e32 v48, v0
	v_mov_b32_e32 v49, v0
	v_mov_b32_e32 v50, v0
	v_mov_b32_e32 v51, v0
	v_mov_b32_e32 v52, v0
	v_mov_b32_e32 v53, v0
	v_mov_b32_e32 v54, v0
	v_mov_b32_e32 v55, v0
	v_mov_b32_e32 v8, v0
	v_mov_b32_e32 v9, v0
	v_mov_b32_e32 v10, v0
	v_mov_b32_e32 v11, v0
	v_mov_b32_e32 v12, v0
	v_mov_b32_e32 v13, v0
	v_mov_b32_e32 v14, v0
	v_mov_b32_e32 v15, v0
	v_mov_b32_e32 v24, v0
	v_mov_b32_e32 v25, v0
	v_mov_b32_e32 v26, v0
	v_mov_b32_e32 v27, v0
	v_mov_b32_e32 v28, v0
	v_mov_b32_e32 v29, v0
	v_mov_b32_e32 v30, v0
	v_mov_b32_e32 v31, v0
	v_mov_b32_e32 v40, v0
	v_mov_b32_e32 v41, v0
	v_mov_b32_e32 v42, v0
	v_mov_b32_e32 v43, v0
	v_mov_b32_e32 v44, v0
	v_mov_b32_e32 v45, v0
	v_mov_b32_e32 v46, v0
	v_mov_b32_e32 v47, v0
	v_mov_b32_e32 v56, v0
	v_mov_b32_e32 v57, v0
	v_mov_b32_e32 v58, v0
	v_mov_b32_e32 v59, v0
	v_mov_b32_e32 v60, v0
	v_mov_b32_e32 v61, v0
	v_mov_b32_e32 v62, v0
	v_mov_b32_e32 v63, v0
	v_mov_b32_e32 v64, v0
	v_mov_b32_e32 v65, v0
	v_mov_b32_e32 v66, v0
	v_mov_b32_e32 v67, v0
	v_mov_b32_e32 v68, v0
	v_mov_b32_e32 v69, v0
	v_mov_b32_e32 v70, v0
	v_mov_b32_e32 v71, v0
	v_mov_b32_e32 v80, v0
	v_mov_b32_e32 v81, v0
	v_mov_b32_e32 v82, v0
	v_mov_b32_e32 v83, v0
	v_mov_b32_e32 v84, v0
	v_mov_b32_e32 v85, v0
	v_mov_b32_e32 v86, v0
	v_mov_b32_e32 v87, v0
	v_mov_b32_e32 v96, v0
	v_mov_b32_e32 v97, v0
	v_mov_b32_e32 v98, v0
	v_mov_b32_e32 v99, v0
	v_mov_b32_e32 v100, v0
	v_mov_b32_e32 v101, v0
	v_mov_b32_e32 v102, v0
	v_mov_b32_e32 v103, v0
	v_mov_b32_e32 v112, v0
	v_mov_b32_e32 v113, v0
	v_mov_b32_e32 v114, v0
	v_mov_b32_e32 v115, v0
	v_mov_b32_e32 v116, v0
	v_mov_b32_e32 v117, v0
	v_mov_b32_e32 v118, v0
	v_mov_b32_e32 v119, v0
	v_mov_b32_e32 v72, v0
	v_mov_b32_e32 v73, v0
	v_mov_b32_e32 v74, v0
	v_mov_b32_e32 v75, v0
	v_mov_b32_e32 v76, v0
	v_mov_b32_e32 v77, v0
	v_mov_b32_e32 v78, v0
	v_mov_b32_e32 v79, v0
	v_mov_b32_e32 v88, v0
	v_mov_b32_e32 v89, v0
	v_mov_b32_e32 v90, v0
	v_mov_b32_e32 v91, v0
	v_mov_b32_e32 v92, v0
	v_mov_b32_e32 v93, v0
	v_mov_b32_e32 v94, v0
	v_mov_b32_e32 v95, v0
	v_mov_b32_e32 v104, v0
	v_mov_b32_e32 v105, v0
	v_mov_b32_e32 v106, v0
	v_mov_b32_e32 v107, v0
	v_mov_b32_e32 v108, v0
	v_mov_b32_e32 v109, v0
	v_mov_b32_e32 v110, v0
	v_mov_b32_e32 v111, v0
	v_mov_b32_e32 v124, v0
	v_mov_b32_e32 v125, v0
	v_mov_b32_e32 v126, v0
	v_mov_b32_e32 v127, v0
	v_mov_b32_e32 v120, v0
	v_mov_b32_e32 v121, v0
	v_mov_b32_e32 v122, v0
	v_mov_b32_e32 v123, v0
.LBB0_497:
	s_add_i32 s49, s26, 2
	s_add_u32 s50, s0, 0x80
	s_addc_u32 s27, s1, 0
	s_add_i32 s52, 0, 0x10000
	s_cmp_eq_u32 s43, s26
	s_cselect_b32 s27, s9, s27
	s_cselect_b32 s26, s8, s50
	s_cselect_b32 s51, s25, s48
	s_cselect_b32 s50, s24, s33
	s_add_i32 s53, 0, 0x14000
	v_add_u32_e32 v140, s52, v186
	v_add_u32_e32 v166, s53, v186
	ds_read_b128 v[128:131], v140
	ds_read_b128 v[132:135], v140 offset:1024
	ds_read_b128 v[136:139], v140 offset:2048
	ds_read_b128 v[140:143], v140 offset:3072
	ds_read_b128 v[144:147], v166
	ds_read_b128 v[148:151], v166 offset:1024
	ds_read_b128 v[152:155], v166 offset:2048
	ds_read_b128 v[166:169], v166 offset:3072
	v_lshl_add_u64 v[182:183], s[0:1], 0, v[162:163]
	s_add_i32 m0, s31, 0xc000
	ds_read_b128 v[170:173], v187
	ds_read_b128 v[174:177], v187 offset:1024
	ds_read_b128 v[178:181], v187 offset:2048
	ds_read_b128 v[188:191], v187 offset:3072
	ds_read_b128 v[204:207], v187 offset:4096
	ds_read_b128 v[208:211], v187 offset:5120
	ds_read_b128 v[212:215], v187 offset:6144
	ds_read_b128 v[216:219], v187 offset:7168
	global_load_lds_dwordx4 v[182:183], off
	v_lshl_add_u64 v[182:183], s[0:1], 0, v[164:165]
	s_add_i32 m0, s31, 0xe000
	s_nop 0
	global_load_lds_dwordx4 v[182:183], off
	s_waitcnt vmcnt(8)
	s_waitcnt lgkmcnt(0)
	s_barrier
	s_setprio 1
	s_waitcnt lgkmcnt(0)
	v_mfma_f32_16x16x32_bf16 v[120:123], v[128:131], v[170:173], v[120:123]
	v_mfma_f32_16x16x32_bf16 v[124:127], v[136:139], v[170:173], v[124:127]
	v_mfma_f32_16x16x32_bf16 v[108:111], v[128:131], v[178:181], v[108:111]
	v_mfma_f32_16x16x32_bf16 v[104:107], v[136:139], v[178:181], v[104:107]
	v_mfma_f32_16x16x32_bf16 v[92:95], v[128:131], v[204:207], v[92:95]
	v_mfma_f32_16x16x32_bf16 v[88:91], v[136:139], v[204:207], v[88:91]
	v_mfma_f32_16x16x32_bf16 v[76:79], v[128:131], v[212:215], v[76:79]
	v_mfma_f32_16x16x32_bf16 v[72:75], v[136:139], v[212:215], v[72:75]
	v_mfma_f32_16x16x32_bf16 v[120:123], v[132:135], v[174:177], v[120:123]
	v_mfma_f32_16x16x32_bf16 v[124:127], v[140:143], v[174:177], v[124:127]
	v_mfma_f32_16x16x32_bf16 v[108:111], v[132:135], v[188:191], v[108:111]
	v_mfma_f32_16x16x32_bf16 v[104:107], v[140:143], v[188:191], v[104:107]
	v_mfma_f32_16x16x32_bf16 v[92:95], v[132:135], v[208:211], v[92:95]
	v_mfma_f32_16x16x32_bf16 v[88:91], v[140:143], v[208:211], v[88:91]
	v_mfma_f32_16x16x32_bf16 v[76:79], v[132:135], v[216:219], v[76:79]
	v_mfma_f32_16x16x32_bf16 v[72:75], v[140:143], v[216:219], v[72:75]
	s_setprio 0
	s_setprio 1
	v_mfma_f32_16x16x32_bf16 v[116:119], v[144:147], v[170:173], v[116:119]
	v_mfma_f32_16x16x32_bf16 v[112:115], v[152:155], v[170:173], v[112:115]
	v_mfma_f32_16x16x32_bf16 v[100:103], v[144:147], v[178:181], v[100:103]
	v_mfma_f32_16x16x32_bf16 v[96:99], v[152:155], v[178:181], v[96:99]
	v_mfma_f32_16x16x32_bf16 v[84:87], v[144:147], v[204:207], v[84:87]
	v_mfma_f32_16x16x32_bf16 v[80:83], v[152:155], v[204:207], v[80:83]
	v_mfma_f32_16x16x32_bf16 v[68:71], v[144:147], v[212:215], v[68:71]
	v_mfma_f32_16x16x32_bf16 v[64:67], v[152:155], v[212:215], v[64:67]
	v_mfma_f32_16x16x32_bf16 v[116:119], v[148:151], v[174:177], v[116:119]
	v_mfma_f32_16x16x32_bf16 v[112:115], v[166:169], v[174:177], v[112:115]
	v_mfma_f32_16x16x32_bf16 v[100:103], v[148:151], v[188:191], v[100:103]
	v_mfma_f32_16x16x32_bf16 v[96:99], v[166:169], v[188:191], v[96:99]
	v_mfma_f32_16x16x32_bf16 v[84:87], v[148:151], v[208:211], v[84:87]
	v_mfma_f32_16x16x32_bf16 v[80:83], v[166:169], v[208:211], v[80:83]
	v_mfma_f32_16x16x32_bf16 v[68:71], v[148:151], v[216:219], v[68:71]
	v_mfma_f32_16x16x32_bf16 v[64:67], v[166:169], v[216:219], v[64:67]
	s_setprio 0
	s_barrier
; #define PG8_STAGE(bufoff, gbase, voff) do { _Pragma("unroll") for (int _i = 0; _i < 2; ++_i) \
;         __builtin_amdgcn_global_load_lds((const unsigned*)((const char*)(gbase) + (voff)[_i]), (PG8_LAS unsigned*)(lds + (bufoff) + ldsw + _i * 8192), 16, 0, 0); } while (0)
; #define PG8_LDA(dst, b, h) do { _Pragma("unroll") for (int m = 0; m < 4; ++m) _Pragma("unroll") for (int k = 0; k < 2; ++k) dst[m][k] = *(const PG8_LAS bf16x8*)(lds + PG8_SA(b, h) + aoff + m * 2048 + k * 1024); } while (0)
; #define PG8_LDB(dst, b, h) do { _Pragma("unroll") for (int n = 0; n < 2; ++n) _Pragma("unroll") for (int k = 0; k < 2; ++k) dst[n][k] = *(const PG8_LAS bf16x8*)(lds + PG8_SB(b, h) + boff + n * 2048 + k * 1024); } while (0)
; #define PG8_MMA(ai, bj, At, Bt) do { __builtin_amdgcn_s_setprio(1); _Pragma("unroll") for (int m = 0; m < 4; ++m) _Pragma("unroll") for (int n = 0; n < 2; ++n) _Pragma("unroll") for (int k = 0; k < 2; ++k) \
;         acc[ai][bj][m][n] = __builtin_amdgcn_mfma_f32_16x16x32_bf16(Bt[n][k], At[m][k], acc[ai][bj][m][n], 0, 0, 0); __builtin_amdgcn_s_setprio(0); } while (0)
; #define PG8_WAIT_V(n) asm volatile("s_waitcnt vmcnt(" #n ")" ::: "memory")
; #define PG8_WAIT_L(n) asm volatile("s_waitcnt lgkmcnt(" #n ")" ::: "memory")
; #define PG8_BAR __builtin_amdgcn_s_barrier()
; template <class Epi, class Sched, bool ALIGN_EPI = false, bool SP2 = false>
; __device__ __forceinline__ void gemm_phase(PG8_LAS unsigned char* lds, const Gemm g, const Sched& S, const Epi& E) {
;     ...
;             PG8_WAIT_L(0); PG8_BAR; PG8_MMA(0, 0, At, B0); PG8_MMA(0, 1, At, B1);
;             if constexpr (Epi::SPLIT) { if (defer) {
;                 E.second(acc, prev, rv1, wr, wc, fr, fq);
;                 _Pragma("unroll") for (int b = 0; b < 2; ++b) _Pragma("unroll") for (int m = 0; m < 4; ++m) _Pragma("unroll") for (int n = 0; n < 2; ++n) acc[1][b][m][n] = (f32x4){0.f, 0.f, 0.f, 0.f}; } }
;             PG8_BAR; PG8_SCHED;
;             PG8_LDA(At, 0, 1); PG8_STAGE(PG8_SB(0, 0), b2, voffB); PG8_STAGE(PG8_SB(0, 1), b2 + hstep, voffB); PG8_STAGE(PG8_SA(0, 0), a2, voffA);
;             if (plast) PG8_WAIT_V(10); else PG8_WAIT_SEL(defer, 16, 24);
;             PG8_WAIT_L(0); PG8_BAR; PG8_MMA(1, 0, At, B0); PG8_MMA(1, 1, At, B1); PG8_BAR; PG8_SCHED;
;             PG8_LDB(B0, 1, 0); PG8_LDB(B1, 1, 1); PG8_SCHED; PG8_LDA(At, 1, 0); PG8_STAGE(PG8_SA(0, 1), a2 + hstepA, voffA);
	s_add_i32 s52, s52, s30
	v_lshl_add_u64 v[182:183], s[50:51], 0, v[192:193]
	s_mov_b32 m0, s52
	ds_read_b128 v[170:173], v187 offset:16384
	ds_read_b128 v[174:177], v187 offset:17408
	ds_read_b128 v[178:181], v187 offset:18432
	ds_read_b128 v[188:191], v187 offset:19456
	ds_read_b128 v[204:207], v187 offset:20480
	ds_read_b128 v[208:211], v187 offset:21504
	ds_read_b128 v[212:215], v187 offset:22528
	ds_read_b128 v[216:219], v187 offset:23552
	global_load_lds_dwordx4 v[182:183], off
	s_add_i32 m0, s52, 0x2000
	v_lshl_add_u64 v[194:195], s[50:51], 0, v[156:157]
	s_add_u32 s50, s50, s14
	s_addc_u32 s51, s51, s15
	s_add_i32 s52, s53, s30
	global_load_lds_dwordx4 v[194:195], off
	v_lshl_add_u64 v[200:201], s[50:51], 0, v[192:193]
	s_mov_b32 m0, s52
	v_lshl_add_u64 v[202:203], s[50:51], 0, v[156:157]
	global_load_lds_dwordx4 v[200:201], off
	s_add_i32 m0, s52, 0x2000
	v_lshl_add_u64 v[220:221], s[26:27], 0, v[160:161]
	global_load_lds_dwordx4 v[202:203], off
	s_mov_b32 m0, s31
	v_lshl_add_u64 v[222:223], s[26:27], 0, v[158:159]
	global_load_lds_dwordx4 v[220:221], off
	s_mov_b32 m0, s34
	s_nop 0
	global_load_lds_dwordx4 v[222:223], off
	s_waitcnt vmcnt(8)
	s_waitcnt lgkmcnt(0)
	s_barrier
	s_setprio 1
	s_waitcnt lgkmcnt(0)
	v_mfma_f32_16x16x32_bf16 v[60:63], v[128:131], v[170:173], v[60:63]
	v_mfma_f32_16x16x32_bf16 v[56:59], v[136:139], v[170:173], v[56:59]
	v_mfma_f32_16x16x32_bf16 v[44:47], v[128:131], v[178:181], v[44:47]
	v_mfma_f32_16x16x32_bf16 v[40:43], v[136:139], v[178:181], v[40:43]
	v_mfma_f32_16x16x32_bf16 v[28:31], v[128:131], v[204:207], v[28:31]
	v_mfma_f32_16x16x32_bf16 v[24:27], v[136:139], v[204:207], v[24:27]
	v_mfma_f32_16x16x32_bf16 v[12:15], v[128:131], v[212:215], v[12:15]
	v_mfma_f32_16x16x32_bf16 v[8:11], v[136:139], v[212:215], v[8:11]
	v_mfma_f32_16x16x32_bf16 v[60:63], v[132:135], v[174:177], v[60:63]
	v_mfma_f32_16x16x32_bf16 v[56:59], v[140:143], v[174:177], v[56:59]
	v_mfma_f32_16x16x32_bf16 v[44:47], v[132:135], v[188:191], v[44:47]
	v_mfma_f32_16x16x32_bf16 v[40:43], v[140:143], v[188:191], v[40:43]
	v_mfma_f32_16x16x32_bf16 v[28:31], v[132:135], v[208:211], v[28:31]
	v_mfma_f32_16x16x32_bf16 v[24:27], v[140:143], v[208:211], v[24:27]
	v_mfma_f32_16x16x32_bf16 v[12:15], v[132:135], v[216:219], v[12:15]
	v_mfma_f32_16x16x32_bf16 v[8:11], v[140:143], v[216:219], v[8:11]
	s_setprio 0
	s_setprio 1
	v_mfma_f32_16x16x32_bf16 v[52:55], v[144:147], v[170:173], v[52:55]
	v_mfma_f32_16x16x32_bf16 v[48:51], v[152:155], v[170:173], v[48:51]
	v_mfma_f32_16x16x32_bf16 v[36:39], v[144:147], v[178:181], v[36:39]
	v_mfma_f32_16x16x32_bf16 v[32:35], v[152:155], v[178:181], v[32:35]
	v_mfma_f32_16x16x32_bf16 v[20:23], v[144:147], v[204:207], v[20:23]
	v_mfma_f32_16x16x32_bf16 v[16:19], v[152:155], v[204:207], v[16:19]
	v_mfma_f32_16x16x32_bf16 v[4:7], v[144:147], v[212:215], v[4:7]
	v_mfma_f32_16x16x32_bf16 v[0:3], v[152:155], v[212:215], v[0:3]
	v_mfma_f32_16x16x32_bf16 v[52:55], v[148:151], v[174:177], v[52:55]
	v_mfma_f32_16x16x32_bf16 v[48:51], v[166:169], v[174:177], v[48:51]
	v_mfma_f32_16x16x32_bf16 v[36:39], v[148:151], v[188:191], v[36:39]
	v_mfma_f32_16x16x32_bf16 v[32:35], v[166:169], v[188:191], v[32:35]
	v_mfma_f32_16x16x32_bf16 v[20:23], v[148:151], v[208:211], v[20:23]
	v_mfma_f32_16x16x32_bf16 v[16:19], v[166:169], v[208:211], v[16:19]
	v_mfma_f32_16x16x32_bf16 v[4:7], v[148:151], v[216:219], v[4:7]
	v_mfma_f32_16x16x32_bf16 v[0:3], v[166:169], v[216:219], v[0:3]
	s_setprio 0
	s_barrier
	s_add_i32 s50, 0, 0x18000
	s_add_i32 s51, 0, 0x1c000
	v_add_u32_e32 v140, s50, v186
	v_add_u32_e32 v166, s51, v186
	ds_read_b128 v[128:131], v140
	ds_read_b128 v[132:135], v140 offset:1024
	ds_read_b128 v[136:139], v140 offset:2048
	ds_read_b128 v[140:143], v140 offset:3072
	ds_read_b128 v[144:147], v166
	ds_read_b128 v[148:151], v166 offset:1024
	ds_read_b128 v[152:155], v166 offset:2048
	ds_read_b128 v[166:169], v166 offset:3072
	s_add_u32 s26, s26, s10
	s_addc_u32 s27, s27, s11
	s_mov_b32 m0, s35
	v_lshl_add_u64 v[224:225], s[26:27], 0, v[160:161]
	ds_read_b128 v[170:173], v187 offset:32768
	ds_read_b128 v[174:177], v187 offset:33792
	ds_read_b128 v[178:181], v187 offset:34816
	ds_read_b128 v[188:191], v187 offset:35840
	ds_read_b128 v[204:207], v187 offset:36864
	ds_read_b128 v[208:211], v187 offset:37888
	ds_read_b128 v[212:215], v187 offset:38912
	ds_read_b128 v[216:219], v187 offset:39936
	global_load_lds_dwordx4 v[224:225], off
	v_lshl_add_u64 v[224:225], s[26:27], 0, v[158:159]
	s_mov_b32 m0, s36
	s_nop 0
	global_load_lds_dwordx4 v[224:225], off
	s_waitcnt vmcnt(8)
	s_waitcnt lgkmcnt(0)
	s_barrier
; #define PG8_STAGE(bufoff, gbase, voff) do { _Pragma("unroll") for (int _i = 0; _i < 2; ++_i) \
;         __builtin_amdgcn_global_load_lds((const unsigned*)((const char*)(gbase) + (voff)[_i]), (PG8_LAS unsigned*)(lds + (bufoff) + ldsw + _i * 8192), 16, 0, 0); } while (0)
; #define PG8_LDA(dst, b, h) do { _Pragma("unroll") for (int m = 0; m < 4; ++m) _Pragma("unroll") for (int k = 0; k < 2; ++k) dst[m][k] = *(const PG8_LAS bf16x8*)(lds + PG8_SA(b, h) + aoff + m * 2048 + k * 1024); } while (0)
; #define PG8_LDB(dst, b, h) do { _Pragma("unroll") for (int n = 0; n < 2; ++n) _Pragma("unroll") for (int k = 0; k < 2; ++k) dst[n][k] = *(const PG8_LAS bf16x8*)(lds + PG8_SB(b, h) + boff + n * 2048 + k * 1024); } while (0)
; #define PG8_MMA(ai, bj, At, Bt) do { __builtin_amdgcn_s_setprio(1); _Pragma("unroll") for (int m = 0; m < 4; ++m) _Pragma("unroll") for (int n = 0; n < 2; ++n) _Pragma("unroll") for (int k = 0; k < 2; ++k) \
;         acc[ai][bj][m][n] = __builtin_amdgcn_mfma_f32_16x16x32_bf16(Bt[n][k], At[m][k], acc[ai][bj][m][n], 0, 0, 0); __builtin_amdgcn_s_setprio(0); } while (0)
; #define PG8_WAIT_V(n) asm volatile("s_waitcnt vmcnt(" #n ")" ::: "memory")
; #define PG8_WAIT_SEL(d, w4, w8) do { if constexpr (Epi::SPLIT) { if (d) { if constexpr (Epi::NSH == 4) PG8_WAIT_V(w4); else PG8_WAIT_V(w8); } else PG8_WAIT_V(8); } else PG8_WAIT_V(8); } while (0)
; #define PG8_WAIT_L(n) asm volatile("s_waitcnt lgkmcnt(" #n ")" ::: "memory")
; #define PG8_BAR __builtin_amdgcn_s_barrier()
; #define PG8_SCHED __builtin_amdgcn_sched_barrier(0)
; template <class Epi, class Sched, bool ALIGN_EPI = false, bool SP2 = false>
; __device__ __forceinline__ void gemm_phase(PG8_LAS unsigned char* lds, const Gemm g, const Sched& S, const Epi& E) {
;     ...
;             PG8_LDB(B0, 1, 0); PG8_LDB(B1, 1, 1); PG8_SCHED; PG8_LDA(At, 1, 0); PG8_STAGE(PG8_SA(0, 1), a2 + hstepA, voffA);
;             PG8_WAIT_SEL(defer, 12, 16); PG8_WAIT_L(0); PG8_BAR; PG8_MMA(0, 0, At, B0); PG8_MMA(0, 1, At, B1); PG8_BAR; PG8_SCHED;
;             PG8_LDA(At, 1, 1); PG8_STAGE(PG8_SB(1, 0), b3, voffB); PG8_STAGE(PG8_SB(1, 1), b3 + hstep, voffB); PG8_STAGE(PG8_SA(1, 0), a3, voffA);
;             PG8_WAIT_V(8); PG8_WAIT_L(0); PG8_BAR; PG8_MMA(1, 0, At, B0); PG8_MMA(1, 1, At, B1); PG8_BAR; PG8_SCHED;
	s_setprio 1
	s_waitcnt lgkmcnt(0)
	v_mfma_f32_16x16x32_bf16 v[120:123], v[128:131], v[170:173], v[120:123]
	v_mfma_f32_16x16x32_bf16 v[124:127], v[136:139], v[170:173], v[124:127]
	v_mfma_f32_16x16x32_bf16 v[108:111], v[128:131], v[178:181], v[108:111]
	v_mfma_f32_16x16x32_bf16 v[104:107], v[136:139], v[178:181], v[104:107]
	v_mfma_f32_16x16x32_bf16 v[92:95], v[128:131], v[204:207], v[92:95]
	v_mfma_f32_16x16x32_bf16 v[88:91], v[136:139], v[204:207], v[88:91]
	v_mfma_f32_16x16x32_bf16 v[76:79], v[128:131], v[212:215], v[76:79]
	v_mfma_f32_16x16x32_bf16 v[72:75], v[136:139], v[212:215], v[72:75]
	v_mfma_f32_16x16x32_bf16 v[120:123], v[132:135], v[174:177], v[120:123]
	v_mfma_f32_16x16x32_bf16 v[124:127], v[140:143], v[174:177], v[124:127]
	v_mfma_f32_16x16x32_bf16 v[108:111], v[132:135], v[188:191], v[108:111]
	v_mfma_f32_16x16x32_bf16 v[104:107], v[140:143], v[188:191], v[104:107]
	v_mfma_f32_16x16x32_bf16 v[92:95], v[132:135], v[208:211], v[92:95]
	v_mfma_f32_16x16x32_bf16 v[88:91], v[140:143], v[208:211], v[88:91]
	v_mfma_f32_16x16x32_bf16 v[76:79], v[132:135], v[216:219], v[76:79]
	v_mfma_f32_16x16x32_bf16 v[72:75], v[140:143], v[216:219], v[72:75]
	s_setprio 0
	s_setprio 1
	v_mfma_f32_16x16x32_bf16 v[116:119], v[144:147], v[170:173], v[116:119]
	v_mfma_f32_16x16x32_bf16 v[112:115], v[152:155], v[170:173], v[112:115]
	v_mfma_f32_16x16x32_bf16 v[100:103], v[144:147], v[178:181], v[100:103]
	v_mfma_f32_16x16x32_bf16 v[96:99], v[152:155], v[178:181], v[96:99]
	v_mfma_f32_16x16x32_bf16 v[84:87], v[144:147], v[204:207], v[84:87]
	v_mfma_f32_16x16x32_bf16 v[80:83], v[152:155], v[204:207], v[80:83]
	v_mfma_f32_16x16x32_bf16 v[68:71], v[144:147], v[212:215], v[68:71]
	v_mfma_f32_16x16x32_bf16 v[64:67], v[152:155], v[212:215], v[64:67]
	v_mfma_f32_16x16x32_bf16 v[116:119], v[148:151], v[174:177], v[116:119]
	v_mfma_f32_16x16x32_bf16 v[112:115], v[166:169], v[174:177], v[112:115]
	v_mfma_f32_16x16x32_bf16 v[100:103], v[148:151], v[188:191], v[100:103]
	v_mfma_f32_16x16x32_bf16 v[96:99], v[166:169], v[188:191], v[96:99]
	v_mfma_f32_16x16x32_bf16 v[84:87], v[148:151], v[208:211], v[84:87]
	v_mfma_f32_16x16x32_bf16 v[80:83], v[166:169], v[208:211], v[80:83]
	v_mfma_f32_16x16x32_bf16 v[68:71], v[148:151], v[216:219], v[68:71]
	v_mfma_f32_16x16x32_bf16 v[64:67], v[166:169], v[216:219], v[64:67]
	s_setprio 0
	s_barrier
	s_add_i32 s26, s50, s30
	v_lshl_add_u64 v[182:183], v[182:183], 0, s[90:91]
	s_mov_b32 m0, s26
	ds_read_b128 v[170:173], v187 offset:49152
	ds_read_b128 v[174:177], v187 offset:50176
	ds_read_b128 v[178:181], v187 offset:51200
	ds_read_b128 v[188:191], v187 offset:52224
	ds_read_b128 v[204:207], v187 offset:53248
	ds_read_b128 v[208:211], v187 offset:54272
	ds_read_b128 v[212:215], v187 offset:55296
	ds_read_b128 v[216:219], v187 offset:56320
	global_load_lds_dwordx4 v[182:183], off
	v_lshl_add_u64 v[182:183], v[194:195], 0, s[90:91]
	s_add_i32 m0, s26, 0x2000
	s_add_i32 s26, s51, s30
	global_load_lds_dwordx4 v[182:183], off
	v_lshl_add_u64 v[182:183], v[200:201], 0, s[90:91]
	s_mov_b32 m0, s26
	s_nop 0
	global_load_lds_dwordx4 v[182:183], off
	v_lshl_add_u64 v[182:183], v[202:203], 0, s[90:91]
	s_add_i32 m0, s26, 0x2000
	s_nop 0
	global_load_lds_dwordx4 v[182:183], off
	v_lshl_add_u64 v[182:183], v[220:221], 0, s[90:91]
	s_mov_b32 m0, s41
	s_nop 0
	global_load_lds_dwordx4 v[182:183], off
	v_lshl_add_u64 v[182:183], v[222:223], 0, s[90:91]
	s_mov_b32 m0, s42
	s_nop 0
	global_load_lds_dwordx4 v[182:183], off
	s_waitcnt vmcnt(8)
	s_waitcnt lgkmcnt(0)
	s_barrier
	s_setprio 1
	s_waitcnt lgkmcnt(0)
	v_mfma_f32_16x16x32_bf16 v[60:63], v[128:131], v[170:173], v[60:63]
	v_mfma_f32_16x16x32_bf16 v[56:59], v[136:139], v[170:173], v[56:59]
	v_mfma_f32_16x16x32_bf16 v[44:47], v[128:131], v[178:181], v[44:47]
	v_mfma_f32_16x16x32_bf16 v[40:43], v[136:139], v[178:181], v[40:43]
	v_mfma_f32_16x16x32_bf16 v[28:31], v[128:131], v[204:207], v[28:31]
	v_mfma_f32_16x16x32_bf16 v[24:27], v[136:139], v[204:207], v[24:27]
	v_mfma_f32_16x16x32_bf16 v[12:15], v[128:131], v[212:215], v[12:15]
	v_mfma_f32_16x16x32_bf16 v[8:11], v[136:139], v[212:215], v[8:11]
	v_mfma_f32_16x16x32_bf16 v[60:63], v[132:135], v[174:177], v[60:63]
	v_mfma_f32_16x16x32_bf16 v[56:59], v[140:143], v[174:177], v[56:59]
	v_mfma_f32_16x16x32_bf16 v[44:47], v[132:135], v[188:191], v[44:47]
	v_mfma_f32_16x16x32_bf16 v[40:43], v[140:143], v[188:191], v[40:43]
	v_mfma_f32_16x16x32_bf16 v[28:31], v[132:135], v[208:211], v[28:31]
	v_mfma_f32_16x16x32_bf16 v[24:27], v[140:143], v[208:211], v[24:27]
	v_mfma_f32_16x16x32_bf16 v[12:15], v[132:135], v[216:219], v[12:15]
	v_mfma_f32_16x16x32_bf16 v[8:11], v[140:143], v[216:219], v[8:11]
	s_setprio 0
	s_setprio 1
	v_mfma_f32_16x16x32_bf16 v[52:55], v[144:147], v[170:173], v[52:55]
	v_mfma_f32_16x16x32_bf16 v[48:51], v[152:155], v[170:173], v[48:51]
	v_mfma_f32_16x16x32_bf16 v[36:39], v[144:147], v[178:181], v[36:39]
	v_mfma_f32_16x16x32_bf16 v[32:35], v[152:155], v[178:181], v[32:35]
	v_mfma_f32_16x16x32_bf16 v[20:23], v[144:147], v[204:207], v[20:23]
	v_mfma_f32_16x16x32_bf16 v[16:19], v[152:155], v[204:207], v[16:19]
	v_mfma_f32_16x16x32_bf16 v[4:7], v[144:147], v[212:215], v[4:7]
	v_mfma_f32_16x16x32_bf16 v[0:3], v[152:155], v[212:215], v[0:3]
	v_mfma_f32_16x16x32_bf16 v[52:55], v[148:151], v[174:177], v[52:55]
	v_mfma_f32_16x16x32_bf16 v[48:51], v[166:169], v[174:177], v[48:51]
	v_mfma_f32_16x16x32_bf16 v[36:39], v[148:151], v[188:191], v[36:39]
	v_mfma_f32_16x16x32_bf16 v[32:35], v[166:169], v[188:191], v[32:35]
	v_mfma_f32_16x16x32_bf16 v[20:23], v[148:151], v[208:211], v[20:23]
	v_mfma_f32_16x16x32_bf16 v[16:19], v[166:169], v[208:211], v[16:19]
	v_mfma_f32_16x16x32_bf16 v[4:7], v[148:151], v[216:219], v[4:7]
	v_mfma_f32_16x16x32_bf16 v[0:3], v[166:169], v[216:219], v[0:3]
	s_setprio 0
	s_barrier
	s_add_u32 s0, s0, 0x100
	s_addc_u32 s1, s1, 0
	s_add_u32 s33, s33, 0x100
	s_addc_u32 s48, s48, 0
	s_cmp_ge_i32 s49, s38
	s_mov_b32 s26, s49
	s_cbranch_scc0 .LBB0_497

; #define PG8_BAR __builtin_amdgcn_s_barrier()
; template <class Epi, class Sched, bool ALIGN_EPI = false, bool SP2 = false>
; __device__ __forceinline__ void gemm_phase(PG8_LAS unsigned char* lds, const Gemm g, const Sched& S, const Epi& E) {
;     ...
;         if constexpr (ALIGN_EPI) { if (wr == 0) PG8_BAR; }
;         if constexpr (Epi::SPLIT) {
;             if (has_next) { E.first(acc, cur, rv1, wr, wc, fr, fq); prev = cur; }
;             else E(acc, cur, wr, wc, fr, fq, lds + STAGE_BYTES);
;         } else if constexpr (!Epi::AFTER_DRAIN) { E(acc, cur, wr, wc, fr, fq, lds + STAGE_BYTES); S.done(cur); }
;         if (!has_next) break;
; #pragma unroll
;         for (int a = 0; a < (Epi::SPLIT ? 1 : 2); ++a)
; #pragma unroll
;             for (int b = 0; b < 2; ++b)
; #pragma unroll
;                 for (int m = 0; m < 4; ++m)
; #pragma unroll
;                     for (int n = 0; n < 2; ++n) acc[a][b][m][n] = (f32x4){0.f, 0.f, 0.f, 0.f};
;         cur = nxt; cA = nA; cB = nB; ++ui;
;         if constexpr (ALIGN_EPI) { if (wr == 1) PG8_BAR; }
;     __device__ __forceinline__ void operator()(const f32x4 (&acc)[2][2][4][2], const pg8::Unit& u, int wr, int wc, int fr_, int fq_, LAS const unsigned char* xl) const {
;     ...
;                     ss = xrow16_sum(ss);
;                     if (fq == 0) part_out[(size_t)row * 16 + u.pn * 4 + wc] = ss;
.LBB0_516:
	s_or_b64 exec, exec, s[26:27]
	s_and_b64 vcc, exec, s[6:7]
	s_mov_b64 s[0:1], -1
	s_cbranch_vccnz .LBB0_484
	s_andn2_b64 vcc, exec, s[18:19]
	s_cbranch_vccnz .LBB0_483
	s_barrier
	s_branch .LBB0_483

; #define PG8_LAS __attribute__((address_space(3)))
; template <class Epi, class Sched, bool ALIGN_EPI = false, bool SP2 = false>
; __device__ __forceinline__ void gemm_phase(PG8_LAS unsigned char* lds, const Gemm g, const Sched& S, const Epi& E) {
;     ...
;                 const char* pg = (const char*)E.part_in + (size_t)cur.pm * 16384 + (size_t)tid * 16;
;                 __builtin_amdgcn_global_load_lds((const unsigned*)pg, (PG8_LAS unsigned*)(lds + STAGE_BYTES + ldsw), 16, 0, 0);
;                 __builtin_amdgcn_global_load_lds((const unsigned*)(pg + 8192), (PG8_LAS unsigned*)(lds + STAGE_BYTES + 8192 + ldsw), 16, 0, 0); } }
;     ...
; #pragma unroll
;         for (int a = 0; a < (Epi::SPLIT ? 1 : 2); ++a)
; #pragma unroll
;             for (int b = 0; b < 2; ++b)
; #pragma unroll
;                 for (int m = 0; m < 4; ++m)
; #pragma unroll
;                     for (int n = 0; n < 2; ++n) acc[a][b][m][n] = (f32x4){0.f, 0.f, 0.f, 0.f};
.LBB0_558:
	s_andn2_b64 vcc, exec, s[22:23]
	s_cbranch_vccnz .Lzt_5
	s_ashr_i32 s1, s0, 31
	s_lshl_b64 s[34:35], s[0:1], 14
	s_add_u32 s28, s28, 0x80
	s_addc_u32 s29, s29, 0
	v_lshl_add_u64 v[216:217], v[210:211], 0, s[34:35]
	s_mov_b64 s[34:35], 0x2000
	s_add_u32 s1, s30, 0x100
	v_mov_b32_e32 v0, 0
	v_lshl_add_u64 v[218:219], v[216:217], 0, s[34:35]
	s_addc_u32 s33, s31, 0
	s_mov_b32 s59, 0
	v_mov_b32_e32 v1, v0
	v_mov_b32_e32 v2, v0
	v_mov_b32_e32 v3, v0
	v_mov_b32_e32 v4, v0
	v_mov_b32_e32 v5, v0
	v_mov_b32_e32 v6, v0
	v_mov_b32_e32 v7, v0
	v_mov_b32_e32 v16, v0
	v_mov_b32_e32 v17, v0
	v_mov_b32_e32 v18, v0
	v_mov_b32_e32 v19, v0
	v_mov_b32_e32 v20, v0
	v_mov_b32_e32 v21, v0
	v_mov_b32_e32 v22, v0
	v_mov_b32_e32 v23, v0
	v_mov_b32_e32 v32, v0
	v_mov_b32_e32 v33, v0
	v_mov_b32_e32 v34, v0
	v_mov_b32_e32 v35, v0
	v_mov_b32_e32 v36, v0
	v_mov_b32_e32 v37, v0
	v_mov_b32_e32 v38, v0
	v_mov_b32_e32 v39, v0
	v_mov_b32_e32 v48, v0
	v_mov_b32_e32 v49, v0
	v_mov_b32_e32 v50, v0
	v_mov_b32_e32 v51, v0
	v_mov_b32_e32 v52, v0
	v_mov_b32_e32 v53, v0
	v_mov_b32_e32 v54, v0
	v_mov_b32_e32 v55, v0
	v_mov_b32_e32 v8, v0
	v_mov_b32_e32 v9, v0
	v_mov_b32_e32 v10, v0
	v_mov_b32_e32 v11, v0
	v_mov_b32_e32 v12, v0
	v_mov_b32_e32 v13, v0
	v_mov_b32_e32 v14, v0
	v_mov_b32_e32 v15, v0
	v_mov_b32_e32 v24, v0
	v_mov_b32_e32 v25, v0
	v_mov_b32_e32 v26, v0
	v_mov_b32_e32 v27, v0
	v_mov_b32_e32 v28, v0
	v_mov_b32_e32 v29, v0
	v_mov_b32_e32 v30, v0
	v_mov_b32_e32 v31, v0
	v_mov_b32_e32 v40, v0
	v_mov_b32_e32 v41, v0
	v_mov_b32_e32 v42, v0
	v_mov_b32_e32 v43, v0
	v_mov_b32_e32 v44, v0
	v_mov_b32_e32 v45, v0
	v_mov_b32_e32 v46, v0
	v_mov_b32_e32 v47, v0
	v_mov_b32_e32 v56, v0
	v_mov_b32_e32 v57, v0
	v_mov_b32_e32 v58, v0
	v_mov_b32_e32 v59, v0
	v_mov_b32_e32 v60, v0
	v_mov_b32_e32 v61, v0
	v_mov_b32_e32 v62, v0
	v_mov_b32_e32 v63, v0
	v_mov_b32_e32 v64, v0
	v_mov_b32_e32 v65, v0
	v_mov_b32_e32 v66, v0
	v_mov_b32_e32 v67, v0
	v_mov_b32_e32 v68, v0
	v_mov_b32_e32 v69, v0
	v_mov_b32_e32 v70, v0
	v_mov_b32_e32 v71, v0
	v_mov_b32_e32 v80, v0
	v_mov_b32_e32 v81, v0
	v_mov_b32_e32 v82, v0
	v_mov_b32_e32 v83, v0
	v_mov_b32_e32 v84, v0
	v_mov_b32_e32 v85, v0
	v_mov_b32_e32 v86, v0
	v_mov_b32_e32 v87, v0
	v_mov_b32_e32 v96, v0
	v_mov_b32_e32 v97, v0
	v_mov_b32_e32 v98, v0
	v_mov_b32_e32 v99, v0
	v_mov_b32_e32 v100, v0
	v_mov_b32_e32 v101, v0
	v_mov_b32_e32 v102, v0
	v_mov_b32_e32 v103, v0
	v_mov_b32_e32 v112, v0
	v_mov_b32_e32 v113, v0
	v_mov_b32_e32 v114, v0
	v_mov_b32_e32 v115, v0
	v_mov_b32_e32 v116, v0
	v_mov_b32_e32 v117, v0
	v_mov_b32_e32 v118, v0
	v_mov_b32_e32 v119, v0
	v_mov_b32_e32 v72, v0
	v_mov_b32_e32 v73, v0
	v_mov_b32_e32 v74, v0
	v_mov_b32_e32 v75, v0
	v_mov_b32_e32 v76, v0
	v_mov_b32_e32 v77, v0
	v_mov_b32_e32 v78, v0
	v_mov_b32_e32 v79, v0
	v_mov_b32_e32 v88, v0
	v_mov_b32_e32 v89, v0
	v_mov_b32_e32 v90, v0
	v_mov_b32_e32 v91, v0
	v_mov_b32_e32 v92, v0
	v_mov_b32_e32 v93, v0
	v_mov_b32_e32 v94, v0
	v_mov_b32_e32 v95, v0
	v_mov_b32_e32 v104, v0
	v_mov_b32_e32 v105, v0
	v_mov_b32_e32 v106, v0
	v_mov_b32_e32 v107, v0
	v_mov_b32_e32 v108, v0
	v_mov_b32_e32 v109, v0
	v_mov_b32_e32 v110, v0
	v_mov_b32_e32 v111, v0
	v_mov_b32_e32 v120, v0
	v_mov_b32_e32 v121, v0
	v_mov_b32_e32 v122, v0
	v_mov_b32_e32 v123, v0
	v_mov_b32_e32 v124, v0
	v_mov_b32_e32 v125, v0
	v_mov_b32_e32 v126, v0
	v_mov_b32_e32 v127, v0
	s_branch .LBB0_561

; #define PG8_STAGE(bufoff, gbase, voff) do { _Pragma("unroll") for (int _i = 0; _i < 2; ++_i) \
;         __builtin_amdgcn_global_load_lds((const unsigned*)((const char*)(gbase) + (voff)[_i]), (PG8_LAS unsigned*)(lds + (bufoff) + ldsw + _i * 8192), 16, 0, 0); } while (0)
; #define PG8_LDA(dst, b, h) do { _Pragma("unroll") for (int m = 0; m < 4; ++m) _Pragma("unroll") for (int k = 0; k < 2; ++k) dst[m][k] = *(const PG8_LAS bf16x8*)(lds + PG8_SA(b, h) + aoff + m * 2048 + k * 1024); } while (0)
; #define PG8_LDB(dst, b, h) do { _Pragma("unroll") for (int n = 0; n < 2; ++n) _Pragma("unroll") for (int k = 0; k < 2; ++k) dst[n][k] = *(const PG8_LAS bf16x8*)(lds + PG8_SB(b, h) + boff + n * 2048 + k * 1024); } while (0)
; #define PG8_WAIT_V(n) asm volatile("s_waitcnt vmcnt(" #n ")" ::: "memory")
; #define PG8_WAIT_SEL(d, w4, w8) do { if constexpr (Epi::SPLIT) { if (d) { if constexpr (Epi::NSH == 4) PG8_WAIT_V(w4); else PG8_WAIT_V(w8); } else PG8_WAIT_V(8); } else PG8_WAIT_V(8); } while (0)
; #define PG8_SCHED __builtin_amdgcn_sched_barrier(0)
; template <class Epi, class Sched, bool ALIGN_EPI = false, bool SP2 = false>
; __device__ __forceinline__ void gemm_phase(PG8_LAS unsigned char* lds, const Gemm g, const Sched& S, const Epi& E) {
;     ...
;             PG8_LDB(B0, 0, 0); PG8_LDB(B1, 0, 1); PG8_SCHED; PG8_LDA(At, 0, 0); PG8_STAGE(PG8_SA(1, 1), a1 + hstepA, voffA);
;             if (plast) PG8_WAIT_V(10); else PG8_WAIT_SEL(defer, 12, 16);
.LBB0_563:
	v_add_u32_e32 v128, 0, v239
	v_add_u32_e32 v129, 0x10000, v128
	v_add_u32_e32 v140, 0x14000, v128
	ds_read_b128 v[144:147], v129
	ds_read_b128 v[148:151], v129 offset:1024
	ds_read_b128 v[152:155], v129 offset:2048
	ds_read_b128 v[156:159], v129 offset:3072
	ds_read_b128 v[128:131], v140
	ds_read_b128 v[132:135], v140 offset:1024
	ds_read_b128 v[136:139], v140 offset:2048
	ds_read_b128 v[140:143], v140 offset:3072
	v_lshl_add_u64 v[194:195], s[28:29], 0, v[212:213]
	s_add_i32 m0, s41, 0xc000
	ds_read_b128 v[184:187], v240
	ds_read_b128 v[188:191], v240 offset:1024
	ds_read_b128 v[176:179], v240 offset:2048
	ds_read_b128 v[180:183], v240 offset:3072
	ds_read_b128 v[168:171], v240 offset:4096
	ds_read_b128 v[172:175], v240 offset:5120
	ds_read_b128 v[160:163], v240 offset:6144
	ds_read_b128 v[164:167], v240 offset:7168
	global_load_lds_dwordx4 v[194:195], off
	v_lshl_add_u64 v[194:195], s[28:29], 0, v[214:215]
	s_add_i32 m0, s41, 0xe000
	s_mov_b64 s[36:37], -1
	global_load_lds_dwordx4 v[194:195], off
	s_and_b64 vcc, exec, s[34:35]
	s_cbranch_vccz .LBB0_565
	s_waitcnt vmcnt(8)
	s_mov_b64 s[36:37], 0

; #define PG8_STAGE(bufoff, gbase, voff) do { _Pragma("unroll") for (int _i = 0; _i < 2; ++_i) \
;         __builtin_amdgcn_global_load_lds((const unsigned*)((const char*)(gbase) + (voff)[_i]), (PG8_LAS unsigned*)(lds + (bufoff) + ldsw + _i * 8192), 16, 0, 0); } while (0)
; #define PG8_LDA(dst, b, h) do { _Pragma("unroll") for (int m = 0; m < 4; ++m) _Pragma("unroll") for (int k = 0; k < 2; ++k) dst[m][k] = *(const PG8_LAS bf16x8*)(lds + PG8_SA(b, h) + aoff + m * 2048 + k * 1024); } while (0)
; #define PG8_LDB(dst, b, h) do { _Pragma("unroll") for (int n = 0; n < 2; ++n) _Pragma("unroll") for (int k = 0; k < 2; ++k) dst[n][k] = *(const PG8_LAS bf16x8*)(lds + PG8_SB(b, h) + boff + n * 2048 + k * 1024); } while (0)
; #define PG8_WAIT_V(n) asm volatile("s_waitcnt vmcnt(" #n ")" ::: "memory")
; #define PG8_WAIT_SEL(d, w4, w8) do { if constexpr (Epi::SPLIT) { if (d) { if constexpr (Epi::NSH == 4) PG8_WAIT_V(w4); else PG8_WAIT_V(w8); } else PG8_WAIT_V(8); } else PG8_WAIT_V(8); } while (0)
; #define PG8_BAR __builtin_amdgcn_s_barrier()
; template <class Epi, class Sched, bool ALIGN_EPI = false, bool SP2 = false>
; __device__ __forceinline__ void gemm_phase(PG8_LAS unsigned char* lds, const Gemm g, const Sched& S, const Epi& E) {
;     ...
;             const char* a2 = last ? nA : cA + (size_t)(t + 2) * kstep; const char* b2 = last ? nB : cB + (size_t)(t + 2) * kstep;
;             const char* a3 = a2 + kstep; const char* b3 = b2 + kstep;
;             if (last && has_next) S.a_ready(nxt);
;             if constexpr (SP2) {
;             PG8_LDB(B0, 0, 0); PG8_LDB(B1, 0, 1); PG8_SCHED; PG8_LDA(At, 0, 0); PG8_STAGE(PG8_SA(1, 1), a1 + hstepA, voffA);
;             if (plast) PG8_WAIT_V(10); else PG8_WAIT_SEL(defer, 12, 16);
;             PG8_WAIT_L(0); PG8_BAR; PG8_MMA(0, 0, At, B0); PG8_MMA(0, 1, At, B1);
;             if constexpr (Epi::SPLIT) { if (defer) {
;                 E.second(acc, prev, rv1, wr, wc, fr, fq);
;                 _Pragma("unroll") for (int b = 0; b < 2; ++b) _Pragma("unroll") for (int m = 0; m < 4; ++m) _Pragma("unroll") for (int n = 0; n < 2; ++n) acc[1][b][m][n] = (f32x4){0.f, 0.f, 0.f, 0.f}; } }
;             PG8_BAR; PG8_SCHED;
;             PG8_LDA(At, 0, 1); PG8_STAGE(PG8_SB(0, 0), b2, voffB); PG8_STAGE(PG8_SB(0, 1), b2 + hstep, voffB); PG8_STAGE(PG8_SA(0, 0), a2, voffA);
;             if (plast) PG8_WAIT_V(10); else PG8_WAIT_SEL(defer, 16, 24);
.LBB0_567:
	s_add_u32 s36, s28, 0x80
	s_addc_u32 s37, s29, 0
	s_waitcnt lgkmcnt(0)
	s_and_b64 s[30:31], s[30:31], exec
	s_cselect_b32 s31, s7, s37
	s_cselect_b32 s30, s6, s36
	s_cselect_b32 s37, s27, s33
	s_cselect_b32 s36, s26, s1
	s_barrier
	s_setprio 1
	s_waitcnt lgkmcnt(0)
	v_mfma_f32_16x16x32_bf16 v[124:127], v[144:147], v[184:187], v[124:127]
	v_mfma_f32_16x16x32_bf16 v[120:123], v[152:155], v[184:187], v[120:123]
	v_mfma_f32_16x16x32_bf16 v[108:111], v[144:147], v[176:179], v[108:111]
	v_mfma_f32_16x16x32_bf16 v[104:107], v[152:155], v[176:179], v[104:107]
	v_mfma_f32_16x16x32_bf16 v[92:95], v[144:147], v[168:171], v[92:95]
	v_mfma_f32_16x16x32_bf16 v[88:91], v[152:155], v[168:171], v[88:91]
	v_mfma_f32_16x16x32_bf16 v[76:79], v[144:147], v[160:163], v[76:79]
	v_mfma_f32_16x16x32_bf16 v[72:75], v[152:155], v[160:163], v[72:75]
	v_mfma_f32_16x16x32_bf16 v[124:127], v[148:151], v[188:191], v[124:127]
	v_mfma_f32_16x16x32_bf16 v[120:123], v[156:159], v[188:191], v[120:123]
	v_mfma_f32_16x16x32_bf16 v[108:111], v[148:151], v[180:183], v[108:111]
	v_mfma_f32_16x16x32_bf16 v[104:107], v[156:159], v[180:183], v[104:107]
	v_mfma_f32_16x16x32_bf16 v[92:95], v[148:151], v[172:175], v[92:95]
	v_mfma_f32_16x16x32_bf16 v[88:91], v[156:159], v[172:175], v[88:91]
	v_mfma_f32_16x16x32_bf16 v[76:79], v[148:151], v[164:167], v[76:79]
	v_mfma_f32_16x16x32_bf16 v[72:75], v[156:159], v[164:167], v[72:75]
	s_setprio 0
	s_setprio 1
	v_mfma_f32_16x16x32_bf16 v[116:119], v[128:131], v[184:187], v[116:119]
	v_mfma_f32_16x16x32_bf16 v[112:115], v[136:139], v[184:187], v[112:115]
	v_mfma_f32_16x16x32_bf16 v[100:103], v[128:131], v[176:179], v[100:103]
	v_mfma_f32_16x16x32_bf16 v[96:99], v[136:139], v[176:179], v[96:99]
	v_mfma_f32_16x16x32_bf16 v[84:87], v[128:131], v[168:171], v[84:87]
	v_mfma_f32_16x16x32_bf16 v[80:83], v[136:139], v[168:171], v[80:83]
	v_mfma_f32_16x16x32_bf16 v[68:71], v[128:131], v[160:163], v[68:71]
	v_mfma_f32_16x16x32_bf16 v[64:67], v[136:139], v[160:163], v[64:67]
	v_mfma_f32_16x16x32_bf16 v[116:119], v[132:135], v[188:191], v[116:119]
	v_mfma_f32_16x16x32_bf16 v[112:115], v[140:143], v[188:191], v[112:115]
	v_mfma_f32_16x16x32_bf16 v[100:103], v[132:135], v[180:183], v[100:103]
	v_mfma_f32_16x16x32_bf16 v[96:99], v[140:143], v[180:183], v[96:99]
	v_mfma_f32_16x16x32_bf16 v[84:87], v[132:135], v[172:175], v[84:87]
	v_mfma_f32_16x16x32_bf16 v[80:83], v[140:143], v[172:175], v[80:83]
	v_mfma_f32_16x16x32_bf16 v[68:71], v[132:135], v[164:167], v[68:71]
	v_mfma_f32_16x16x32_bf16 v[64:67], v[140:143], v[164:167], v[64:67]
	s_setprio 0
	s_barrier
	s_mov_b32 m0, s42
	v_lshl_add_u64 v[222:223], s[36:37], 0, v[192:193]
	v_lshl_add_u64 v[220:221], s[36:37], 0, v[204:205]
	s_add_u32 s36, s36, s12
	ds_read_b128 v[184:187], v240 offset:16384
	ds_read_b128 v[188:191], v240 offset:17408
	ds_read_b128 v[176:179], v240 offset:18432
	ds_read_b128 v[180:183], v240 offset:19456
	ds_read_b128 v[168:171], v240 offset:20480
	ds_read_b128 v[172:175], v240 offset:21504
	ds_read_b128 v[160:163], v240 offset:22528
	ds_read_b128 v[164:167], v240 offset:23552
	global_load_lds_dwordx4 v[222:223], off
	s_mov_b32 m0, s43
	s_addc_u32 s37, s37, s13
	global_load_lds_dwordx4 v[220:221], off
	v_lshl_add_u64 v[230:231], s[36:37], 0, v[192:193]
	s_mov_b32 m0, s44
	v_lshl_add_u64 v[228:229], s[36:37], 0, v[204:205]
	global_load_lds_dwordx4 v[230:231], off
	s_mov_b32 m0, s45
	v_lshl_add_u64 v[224:225], s[30:31], 0, v[208:209]
	global_load_lds_dwordx4 v[228:229], off
	s_mov_b32 m0, s41
	v_lshl_add_u64 v[226:227], s[30:31], 0, v[206:207]
	global_load_lds_dwordx4 v[224:225], off
	s_mov_b32 m0, s46
	s_mov_b64 s[36:37], -1
	global_load_lds_dwordx4 v[226:227], off
	s_and_b64 vcc, exec, s[34:35]
	s_cbranch_vccz .LBB0_569
	s_waitcnt vmcnt(8)
	s_mov_b64 s[36:37], 0

; #define PG8_WAIT_V(n) asm volatile("s_waitcnt vmcnt(" #n ")" ::: "memory")
; #define PG8_BAR __builtin_amdgcn_s_barrier()
; template <class Epi, class Sched, bool ALIGN_EPI = false, bool SP2 = false>
; __device__ __forceinline__ void gemm_phase(PG8_LAS unsigned char* lds, const Gemm g, const Sched& S, const Epi& E) {
;     ...
;         if (!has_next) break;
; #pragma unroll
;         for (int a = 0; a < (Epi::SPLIT ? 1 : 2); ++a)
; #pragma unroll
;             for (int b = 0; b < 2; ++b)
; #pragma unroll
;                 for (int m = 0; m < 4; ++m)
; #pragma unroll
;                     for (int n = 0; n < 2; ++n) acc[a][b][m][n] = (f32x4){0.f, 0.f, 0.f, 0.f};
;         cur = nxt; cA = nA; cB = nB; ++ui;
;         if constexpr (ALIGN_EPI) { if (wr == 1) PG8_BAR; }
;     }
;     PG8_WAIT_V(0);
;     if constexpr (!ALIGN_EPI) { if (wr == 0) PG8_BAR; }
;     PG8_BAR;
.LBB0_589:
	s_or_b64 exec, exec, s[28:29]
	s_and_b64 vcc, exec, s[4:5]
	s_mov_b64 s[0:1], -1
	s_cbranch_vccnz .LBB0_547
	s_andn2_b64 vcc, exec, s[16:17]
	s_cbranch_vccnz .LBB0_546
	s_barrier
	s_branch .LBB0_546
.LBB0_592:
	s_waitcnt vmcnt(0)
	s_movk_i32 s56, 0x2c1
	v_readlane_b32 s57, v254, 50
	v_readlane_b32 s58, v254, 51
	s_barrier
	s_mov_b64 s[0:1], -1
	s_and_b64 vcc, exec, s[66:67]
	s_cbranch_vccz .LBB0_542

; template <class Epi, class Sched, bool ALIGN_EPI = false, bool SP2 = false>
; __device__ __forceinline__ void gemm_phase(PG8_LAS unsigned char* lds, const Gemm g, const Sched& S, const Epi& E) {
;     ...
; #pragma unroll
;         for (int a = 0; a < (Epi::SPLIT ? 1 : 2); ++a)
; #pragma unroll
;             for (int b = 0; b < 2; ++b)
; #pragma unroll
;                 for (int m = 0; m < 4; ++m)
; #pragma unroll
;                     for (int n = 0; n < 2; ++n) acc[a][b][m][n] = (f32x4){0.f, 0.f, 0.f, 0.f};
.Lzt_0:
	v_mov_b32_e32 v127, 0
	v_mov_b32_e32 v126, v127
	v_mov_b32_e32 v125, v127
	v_mov_b32_e32 v124, v127
	v_mov_b32_e32 v123, v127
	v_mov_b32_e32 v122, v127
	v_mov_b32_e32 v121, v127
	v_mov_b32_e32 v120, v127
	v_mov_b32_e32 v111, v127
	v_mov_b32_e32 v110, v127
	v_mov_b32_e32 v109, v127
	v_mov_b32_e32 v108, v127
	v_mov_b32_e32 v107, v127
	v_mov_b32_e32 v106, v127
	v_mov_b32_e32 v105, v127
	v_mov_b32_e32 v104, v127
	v_mov_b32_e32 v95, v127
	v_mov_b32_e32 v94, v127
	v_mov_b32_e32 v93, v127
	v_mov_b32_e32 v92, v127
	v_mov_b32_e32 v91, v127
	v_mov_b32_e32 v90, v127
	v_mov_b32_e32 v89, v127
	v_mov_b32_e32 v88, v127
	v_mov_b32_e32 v79, v127
	v_mov_b32_e32 v78, v127
	v_mov_b32_e32 v77, v127
	v_mov_b32_e32 v76, v127
	v_mov_b32_e32 v75, v127
	v_mov_b32_e32 v74, v127
	v_mov_b32_e32 v73, v127
	v_mov_b32_e32 v72, v127
	v_mov_b32_e32 v119, v127
	v_mov_b32_e32 v118, v127
	v_mov_b32_e32 v117, v127
	v_mov_b32_e32 v116, v127
	v_mov_b32_e32 v115, v127
	v_mov_b32_e32 v114, v127
	v_mov_b32_e32 v113, v127
	v_mov_b32_e32 v112, v127
	v_mov_b32_e32 v103, v127
	v_mov_b32_e32 v102, v127
	v_mov_b32_e32 v101, v127
	v_mov_b32_e32 v100, v127
	v_mov_b32_e32 v99, v127
	v_mov_b32_e32 v98, v127
	v_mov_b32_e32 v97, v127
	v_mov_b32_e32 v96, v127
	v_mov_b32_e32 v87, v127
	v_mov_b32_e32 v86, v127
	v_mov_b32_e32 v85, v127
	v_mov_b32_e32 v84, v127
	v_mov_b32_e32 v83, v127
	v_mov_b32_e32 v82, v127
	v_mov_b32_e32 v81, v127
	v_mov_b32_e32 v80, v127
	v_mov_b32_e32 v71, v127
	v_mov_b32_e32 v70, v127
	v_mov_b32_e32 v69, v127
	v_mov_b32_e32 v68, v127
	v_mov_b32_e32 v67, v127
	v_mov_b32_e32 v66, v127
	v_mov_b32_e32 v65, v127
	v_mov_b32_e32 v64, v127
	v_mov_b32_e32 v63, v127
	v_mov_b32_e32 v62, v127
	v_mov_b32_e32 v61, v127
	v_mov_b32_e32 v60, v127
	v_mov_b32_e32 v59, v127
	v_mov_b32_e32 v58, v127
	v_mov_b32_e32 v57, v127
	v_mov_b32_e32 v56, v127
	v_mov_b32_e32 v47, v127
	v_mov_b32_e32 v46, v127
	v_mov_b32_e32 v45, v127
	v_mov_b32_e32 v44, v127
	v_mov_b32_e32 v43, v127
	v_mov_b32_e32 v42, v127
	v_mov_b32_e32 v41, v127
	v_mov_b32_e32 v40, v127
	v_mov_b32_e32 v31, v127
	v_mov_b32_e32 v30, v127
	v_mov_b32_e32 v29, v127
	v_mov_b32_e32 v28, v127
	v_mov_b32_e32 v27, v127
	v_mov_b32_e32 v26, v127
	v_mov_b32_e32 v25, v127
	v_mov_b32_e32 v24, v127
	v_mov_b32_e32 v15, v127
	v_mov_b32_e32 v14, v127
	v_mov_b32_e32 v13, v127
	v_mov_b32_e32 v12, v127
	v_mov_b32_e32 v11, v127
	v_mov_b32_e32 v10, v127
	v_mov_b32_e32 v9, v127
	v_mov_b32_e32 v8, v127
	v_mov_b32_e32 v55, v127
	v_mov_b32_e32 v54, v127
	v_mov_b32_e32 v53, v127
	v_mov_b32_e32 v52, v127
	v_mov_b32_e32 v51, v127
	v_mov_b32_e32 v50, v127
	v_mov_b32_e32 v49, v127
	v_mov_b32_e32 v48, v127
	v_mov_b32_e32 v39, v127
	v_mov_b32_e32 v38, v127
	v_mov_b32_e32 v37, v127
	v_mov_b32_e32 v36, v127
	v_mov_b32_e32 v35, v127
	v_mov_b32_e32 v34, v127
	v_mov_b32_e32 v33, v127
	v_mov_b32_e32 v32, v127
	v_mov_b32_e32 v23, v127
	v_mov_b32_e32 v22, v127
	v_mov_b32_e32 v21, v127
	v_mov_b32_e32 v20, v127
	v_mov_b32_e32 v19, v127
	v_mov_b32_e32 v18, v127
	v_mov_b32_e32 v17, v127
	v_mov_b32_e32 v16, v127
	v_mov_b32_e32 v7, v127
	v_mov_b32_e32 v6, v127
	v_mov_b32_e32 v5, v127
	v_mov_b32_e32 v4, v127
	v_mov_b32_e32 v3, v127
	v_mov_b32_e32 v2, v127
	v_mov_b32_e32 v1, v127
	v_mov_b32_e32 v0, v127
	s_branch .LBB0_263
; template <class Epi, class Sched, bool ALIGN_EPI = false, bool SP2 = false>
; __device__ __forceinline__ void gemm_phase(PG8_LAS unsigned char* lds, const Gemm g, const Sched& S, const Epi& E) {
;     ...
; #pragma unroll
;         for (int a = 0; a < (Epi::SPLIT ? 1 : 2); ++a)
; #pragma unroll
;             for (int b = 0; b < 2; ++b)
; #pragma unroll
;                 for (int m = 0; m < 4; ++m)
; #pragma unroll
;                     for (int n = 0; n < 2; ++n) acc[a][b][m][n] = (f32x4){0.f, 0.f, 0.f, 0.f};
.Lzt_1:
	v_mov_b32_e32 v123, 0
	v_mov_b32_e32 v122, v123
	v_mov_b32_e32 v121, v123
	v_mov_b32_e32 v120, v123
	v_mov_b32_e32 v127, v123
	v_mov_b32_e32 v126, v123
	v_mov_b32_e32 v125, v123
	v_mov_b32_e32 v124, v123
	v_mov_b32_e32 v111, v123
	v_mov_b32_e32 v110, v123
	v_mov_b32_e32 v109, v123
	v_mov_b32_e32 v108, v123
	v_mov_b32_e32 v107, v123
	v_mov_b32_e32 v106, v123
	v_mov_b32_e32 v105, v123
	v_mov_b32_e32 v104, v123
	v_mov_b32_e32 v95, v123
	v_mov_b32_e32 v94, v123
	v_mov_b32_e32 v93, v123
	v_mov_b32_e32 v92, v123
	v_mov_b32_e32 v91, v123
	v_mov_b32_e32 v90, v123
	v_mov_b32_e32 v89, v123
	v_mov_b32_e32 v88, v123
	v_mov_b32_e32 v79, v123
	v_mov_b32_e32 v78, v123
	v_mov_b32_e32 v77, v123
	v_mov_b32_e32 v76, v123
	v_mov_b32_e32 v75, v123
	v_mov_b32_e32 v74, v123
	v_mov_b32_e32 v73, v123
	v_mov_b32_e32 v72, v123
	v_mov_b32_e32 v119, v123
	v_mov_b32_e32 v118, v123
	v_mov_b32_e32 v117, v123
	v_mov_b32_e32 v116, v123
	v_mov_b32_e32 v115, v123
	v_mov_b32_e32 v114, v123
	v_mov_b32_e32 v113, v123
	v_mov_b32_e32 v112, v123
	v_mov_b32_e32 v103, v123
	v_mov_b32_e32 v102, v123
	v_mov_b32_e32 v101, v123
	v_mov_b32_e32 v100, v123
	v_mov_b32_e32 v99, v123
	v_mov_b32_e32 v98, v123
	v_mov_b32_e32 v97, v123
	v_mov_b32_e32 v96, v123
	v_mov_b32_e32 v87, v123
	v_mov_b32_e32 v86, v123
	v_mov_b32_e32 v85, v123
	v_mov_b32_e32 v84, v123
	v_mov_b32_e32 v83, v123
	v_mov_b32_e32 v82, v123
	v_mov_b32_e32 v81, v123
	v_mov_b32_e32 v80, v123
	v_mov_b32_e32 v71, v123
	v_mov_b32_e32 v70, v123
	v_mov_b32_e32 v69, v123
	v_mov_b32_e32 v68, v123
	v_mov_b32_e32 v67, v123
	v_mov_b32_e32 v66, v123
	v_mov_b32_e32 v65, v123
	v_mov_b32_e32 v64, v123
	v_mov_b32_e32 v63, v123
	v_mov_b32_e32 v62, v123
	v_mov_b32_e32 v61, v123
	v_mov_b32_e32 v60, v123
	v_mov_b32_e32 v59, v123
	v_mov_b32_e32 v58, v123
	v_mov_b32_e32 v57, v123
	v_mov_b32_e32 v56, v123
	v_mov_b32_e32 v47, v123
	v_mov_b32_e32 v46, v123
	v_mov_b32_e32 v45, v123
	v_mov_b32_e32 v44, v123
	v_mov_b32_e32 v43, v123
	v_mov_b32_e32 v42, v123
	v_mov_b32_e32 v41, v123
	v_mov_b32_e32 v40, v123
	v_mov_b32_e32 v31, v123
	v_mov_b32_e32 v30, v123
	v_mov_b32_e32 v29, v123
	v_mov_b32_e32 v28, v123
	v_mov_b32_e32 v27, v123
	v_mov_b32_e32 v26, v123
	v_mov_b32_e32 v25, v123
	v_mov_b32_e32 v24, v123
	v_mov_b32_e32 v15, v123
	v_mov_b32_e32 v14, v123
	v_mov_b32_e32 v13, v123
	v_mov_b32_e32 v12, v123
	v_mov_b32_e32 v11, v123
	v_mov_b32_e32 v10, v123
	v_mov_b32_e32 v9, v123
	v_mov_b32_e32 v8, v123
	v_mov_b32_e32 v55, v123
	v_mov_b32_e32 v54, v123
	v_mov_b32_e32 v53, v123
	v_mov_b32_e32 v52, v123
	v_mov_b32_e32 v51, v123
	v_mov_b32_e32 v50, v123
	v_mov_b32_e32 v49, v123
	v_mov_b32_e32 v48, v123
	v_mov_b32_e32 v39, v123
	v_mov_b32_e32 v38, v123
	v_mov_b32_e32 v37, v123
	v_mov_b32_e32 v36, v123
	v_mov_b32_e32 v35, v123
	v_mov_b32_e32 v34, v123
	v_mov_b32_e32 v33, v123
	v_mov_b32_e32 v32, v123
	v_mov_b32_e32 v23, v123
	v_mov_b32_e32 v22, v123
	v_mov_b32_e32 v21, v123
	v_mov_b32_e32 v20, v123
	v_mov_b32_e32 v19, v123
	v_mov_b32_e32 v18, v123
	v_mov_b32_e32 v17, v123
	v_mov_b32_e32 v16, v123
	v_mov_b32_e32 v7, v123
	v_mov_b32_e32 v6, v123
	v_mov_b32_e32 v5, v123
	v_mov_b32_e32 v4, v123
	v_mov_b32_e32 v3, v123
	v_mov_b32_e32 v2, v123
	v_mov_b32_e32 v1, v123
	v_mov_b32_e32 v0, v123
	s_branch .LBB0_354
.Lzt_2:
	v_mov_b32_e32 v123, 0
	v_mov_b32_e32 v122, v123
	v_mov_b32_e32 v121, v123
	v_mov_b32_e32 v120, v123
	v_mov_b32_e32 v115, v123
	v_mov_b32_e32 v114, v123
	v_mov_b32_e32 v113, v123
	v_mov_b32_e32 v112, v123
	v_mov_b32_e32 v107, v123
	v_mov_b32_e32 v106, v123
	v_mov_b32_e32 v105, v123
	v_mov_b32_e32 v104, v123
	v_mov_b32_e32 v99, v123
	v_mov_b32_e32 v98, v123
	v_mov_b32_e32 v97, v123
	v_mov_b32_e32 v96, v123
	v_mov_b32_e32 v91, v123
	v_mov_b32_e32 v90, v123
	v_mov_b32_e32 v89, v123
	v_mov_b32_e32 v88, v123
	v_mov_b32_e32 v83, v123
	v_mov_b32_e32 v82, v123
	v_mov_b32_e32 v81, v123
	v_mov_b32_e32 v80, v123
	v_mov_b32_e32 v75, v123
	v_mov_b32_e32 v74, v123
	v_mov_b32_e32 v73, v123
	v_mov_b32_e32 v72, v123
	v_mov_b32_e32 v67, v123
	v_mov_b32_e32 v66, v123
	v_mov_b32_e32 v65, v123
	v_mov_b32_e32 v64, v123
	v_mov_b32_e32 v127, v123
	v_mov_b32_e32 v126, v123
	v_mov_b32_e32 v125, v123
	v_mov_b32_e32 v124, v123
	v_mov_b32_e32 v119, v123
	v_mov_b32_e32 v118, v123
	v_mov_b32_e32 v117, v123
	v_mov_b32_e32 v116, v123
	v_mov_b32_e32 v111, v123
	v_mov_b32_e32 v110, v123
	v_mov_b32_e32 v109, v123
	v_mov_b32_e32 v108, v123
	v_mov_b32_e32 v103, v123
	v_mov_b32_e32 v102, v123
	v_mov_b32_e32 v101, v123
	v_mov_b32_e32 v100, v123
	v_mov_b32_e32 v95, v123
	v_mov_b32_e32 v94, v123
	v_mov_b32_e32 v93, v123
	v_mov_b32_e32 v92, v123
	v_mov_b32_e32 v87, v123
	v_mov_b32_e32 v86, v123
	v_mov_b32_e32 v85, v123
	v_mov_b32_e32 v84, v123
	v_mov_b32_e32 v79, v123
	v_mov_b32_e32 v78, v123
	v_mov_b32_e32 v77, v123
	v_mov_b32_e32 v76, v123
	v_mov_b32_e32 v71, v123
	v_mov_b32_e32 v70, v123
	v_mov_b32_e32 v69, v123
	v_mov_b32_e32 v68, v123
	v_mov_b32_e32 v59, v123
	v_mov_b32_e32 v58, v123
	v_mov_b32_e32 v57, v123
	v_mov_b32_e32 v56, v123
	v_mov_b32_e32 v51, v123
	v_mov_b32_e32 v50, v123
	v_mov_b32_e32 v49, v123
	v_mov_b32_e32 v48, v123
	v_mov_b32_e32 v43, v123
	v_mov_b32_e32 v42, v123
	v_mov_b32_e32 v41, v123
	v_mov_b32_e32 v40, v123
	v_mov_b32_e32 v35, v123
	v_mov_b32_e32 v34, v123
	v_mov_b32_e32 v33, v123
	v_mov_b32_e32 v32, v123
	v_mov_b32_e32 v27, v123
	v_mov_b32_e32 v26, v123
	v_mov_b32_e32 v25, v123
	v_mov_b32_e32 v24, v123
	v_mov_b32_e32 v19, v123
	v_mov_b32_e32 v18, v123
	v_mov_b32_e32 v17, v123
	v_mov_b32_e32 v16, v123
	v_mov_b32_e32 v11, v123
	v_mov_b32_e32 v10, v123
	v_mov_b32_e32 v9, v123
	v_mov_b32_e32 v8, v123
	v_mov_b32_e32 v7, v123
	v_mov_b32_e32 v6, v123
	v_mov_b32_e32 v5, v123
	v_mov_b32_e32 v4, v123
	v_mov_b32_e32 v63, v123
	v_mov_b32_e32 v62, v123
	v_mov_b32_e32 v61, v123
	v_mov_b32_e32 v60, v123
	v_mov_b32_e32 v55, v123
	v_mov_b32_e32 v54, v123
	v_mov_b32_e32 v53, v123
	v_mov_b32_e32 v52, v123
	v_mov_b32_e32 v47, v123
	v_mov_b32_e32 v46, v123
	v_mov_b32_e32 v45, v123
	v_mov_b32_e32 v44, v123
	v_mov_b32_e32 v39, v123
	v_mov_b32_e32 v38, v123
	v_mov_b32_e32 v37, v123
	v_mov_b32_e32 v36, v123
	v_mov_b32_e32 v31, v123
	v_mov_b32_e32 v30, v123
	v_mov_b32_e32 v29, v123
	v_mov_b32_e32 v28, v123
	v_mov_b32_e32 v23, v123
	v_mov_b32_e32 v22, v123
	v_mov_b32_e32 v21, v123
	v_mov_b32_e32 v20, v123
	v_mov_b32_e32 v15, v123
	v_mov_b32_e32 v14, v123
	v_mov_b32_e32 v13, v123
	v_mov_b32_e32 v12, v123
	v_mov_b32_e32 v3, v123
	v_mov_b32_e32 v2, v123
	v_mov_b32_e32 v1, v123
	v_mov_b32_e32 v0, v123
	s_branch .LBB0_423

; __global__ void __launch_bounds__(512, 2) mega(Args A) {
	.amdhsa_kernel _Z4mega4Args
		.amdhsa_group_segment_fixed_size 0
		.amdhsa_private_segment_fixed_size 0
		.amdhsa_kernarg_size 408
		.amdhsa_user_sgpr_count 2
		.amdhsa_user_sgpr_dispatch_ptr 0
		.amdhsa_user_sgpr_queue_ptr 0
		.amdhsa_user_sgpr_kernarg_segment_ptr 1
		.amdhsa_user_sgpr_dispatch_id 0
		.amdhsa_user_sgpr_kernarg_preload_length 0
		.amdhsa_user_sgpr_kernarg_preload_offset 0
		.amdhsa_user_sgpr_private_segment_size 0
		.amdhsa_uses_dynamic_stack 0
		.amdhsa_enable_private_segment 0
		.amdhsa_system_sgpr_workgroup_id_x 1
		.amdhsa_system_sgpr_workgroup_id_y 0
		.amdhsa_system_sgpr_workgroup_id_z 0
		.amdhsa_system_sgpr_workgroup_info 0
		.amdhsa_system_vgpr_workitem_id 2
		.amdhsa_next_free_vgpr 256
		.amdhsa_next_free_sgpr 100
		.amdhsa_accum_offset 256
		.amdhsa_reserve_vcc 1
		.amdhsa_float_round_mode_32 0
		.amdhsa_float_round_mode_16_64 0
		.amdhsa_float_denorm_mode_32 3
		.amdhsa_float_denorm_mode_16_64 3
		.amdhsa_dx10_clamp 1
		.amdhsa_ieee_mode 1
		.amdhsa_fp16_overflow 0
		.amdhsa_tg_split 0
		.amdhsa_exception_fp_ieee_invalid_op 0
		.amdhsa_exception_fp_denorm_src 0
		.amdhsa_exception_fp_ieee_div_zero 0
		.amdhsa_exception_fp_ieee_overflow 0
		.amdhsa_exception_fp_ieee_underflow 0
		.amdhsa_exception_fp_ieee_inexact 0
		.amdhsa_exception_int_div_zero 0
	.end_amdhsa_kernel

; __global__ void __launch_bounds__(512, 2) mega(Args A) {
amdhsa.kernels:
  - .agpr_count:     0
    .args:
      - .offset:         0
        .size:           152
        .value_kind:     by_value
      - .offset:         152
        .size:           4
        .value_kind:     hidden_block_count_x
      - .offset:         156
        .size:           4
        .value_kind:     hidden_block_count_y
      - .offset:         160
        .size:           4
        .value_kind:     hidden_block_count_z
      - .offset:         164
        .size:           2
        .value_kind:     hidden_group_size_x
      - .offset:         166
        .size:           2
        .value_kind:     hidden_group_size_y
      - .offset:         168
        .size:           2
        .value_kind:     hidden_group_size_z
      - .offset:         170
        .size:           2
        .value_kind:     hidden_remainder_x
      - .offset:         172
        .size:           2
        .value_kind:     hidden_remainder_y
      - .offset:         174
        .size:           2
        .value_kind:     hidden_remainder_z
      - .offset:         192
        .size:           8
        .value_kind:     hidden_global_offset_x
      - .offset:         200
        .size:           8
        .value_kind:     hidden_global_offset_y
      - .offset:         208
        .size:           8
        .value_kind:     hidden_global_offset_z
      - .offset:         216
        .size:           2
        .value_kind:     hidden_grid_dims
      - .offset:         240
        .size:           8
        .value_kind:     hidden_multigrid_sync_arg
      - .offset:         272
        .size:           4
        .value_kind:     hidden_dynamic_lds_size
    .group_segment_fixed_size: 0
    .kernarg_segment_align: 8
    .kernarg_segment_size: 408
    .language:       OpenCL C
    .language_version:
      - 2
      - 0
    .max_flat_workgroup_size: 512
    .name:           _Z4mega4Args
    .private_segment_fixed_size: 0
    .sgpr_count:     106
    .sgpr_spill_count: 107
    .symbol:         _Z4mega4Args.kd
    .uniform_work_group_size: 1
    .uses_dynamic_stack: false
    .vgpr_count:     256
    .vgpr_spill_count: 0
    .wavefront_size: 64
